# speedup vs baseline: 1.0173x; 1.0173x over previous
; DEVI float sigmoidf_(float x) { return fminf(__builtin_amdgcn_rcpf(1.f + __builtin_amdgcn_exp2f(-LOG2E * x)), 1.f); }
; #define EPI_HALF(AI, ...) _Pragma("unroll") for(int bj=0;bj<2;++bj) _Pragma("unroll") for(int m=0;m<4;++m) _Pragma("unroll") for(int n=0;n<2;++n) { \
;     const int ai=(AI); const int row=brow+ai*128+wr*64+m*16+fq*4; const int col=bcol+bj*128+wc*32+n*16+fr; \
;     f32x4& v=acc[ai][bj][m][n]; __VA_ARGS__ }
; #define EPI_SC4(ARR) float sc4[2][2]; _Pragma("unroll") for(int bj=0;bj<2;++bj) _Pragma("unroll") for(int n=0;n<2;++n) sc4[bj][n]=(ARR)[RSI(bcol+bj*128+wc*32+n*16+fr)];
; DEVI void run_phase(const int ph, const Params& P, char* shmc, const int wave_u) {
;     ...
;       EPI_SC4(rs2)
; #pragma unroll
;       for (int ah = 0; ah < 2; ++ah) {
;         u32x2 uu[2][4][2];
;         EPI_HALF(ah, { (void)v; uu[bj][m][n] = *reinterpret_cast<const u32x2*>(ub + (long)col * 2048 + row); })
;         EPI_HALF(ah, { const float sc = sc4[bj][n]; const u32x2 u = uu[bj][m][n];
;           st_bf4(T + (long)col * 2048 + row, __uint_as_float(u[0] << 16) * sigmoidf_(v[0] * sc), __uint_as_float(u[0] & 0xffff0000u) * sigmoidf_(v[1] * sc),
;                  __uint_as_float(u[1] << 16) * sigmoidf_(v[2] * sc), __uint_as_float(u[1] & 0xffff0000u) * sigmoidf_(v[3] * sc)); })
;       }
.LBB0_55:
	s_or_b64 exec, exec, s[8:9]
	v_mbcnt_lo_u32_b32 v222, -1, 0
	v_mbcnt_hi_u32_b32 v222, -1, v222
	v_bfe_u32 v222, v222, 4, 1
	v_mul_u32_u24_e32 v222, 24, v222
	v_mov_b32_e32 v223, 0
	v_mbcnt_lo_u32_b32 v131, -1, 0
	v_mbcnt_hi_u32_b32 v131, -1, v131
	s_movk_i32 s1, 0xfda0
	v_or_b32_e32 v134, s5, v131
	v_lshrrev_b32_e32 v130, 1, v134
	v_and_b32_e32 v32, 15, v131
	v_and_b32_e32 v130, 0x60, v130
	v_or3_b32 v130, v32, v130, s6
	v_and_b32_e32 v32, 7, v131
	v_lshlrev_b32_e32 v132, 2, v130
	v_and_or_b32 v132, v132, s1, v32
	v_ashrrev_i32_e32 v133, 31, v132
	v_lshl_add_u64 v[132:133], v[132:133], 2, s[24:25]
	flat_load_dword v194, v[132:133]
	flat_load_dword v193, v[132:133] offset:256
	flat_load_dword v192, v[132:133] offset:2048
	flat_load_dword v32, v[132:133] offset:2304
	v_ashrrev_i32_e32 v132, 2, v134
	v_and_b32_e32 v132, 0xffffffc0, v132
	v_add_u32_e32 v132, s0, v132
	v_lshrrev_b32_e32 v131, 2, v131
	v_and_or_b32 v138, v131, 12, v132
	v_ashrrev_i32_e32 v139, 31, v138
	v_ashrrev_i32_e32 v131, 31, v130
	v_lshlrev_b64 v[166:167], 1, v[138:139]
	v_lshlrev_b64 v[136:137], 12, v[130:131]
	v_lshl_add_u64 v[142:143], s[82:83], 0, v[166:167]
	v_lshl_add_u64 v[134:135], v[142:143], 0, v[136:137]
	flat_load_dwordx2 v[180:181], v[134:135]
	v_or_b32_e32 v134, 16, v130
	v_ashrrev_i32_e32 v135, 31, v134
	v_lshlrev_b64 v[134:135], 12, v[134:135]
	v_lshl_add_u64 v[140:141], v[142:143], 0, v[134:135]
	flat_load_dwordx2 v[178:179], v[140:141]
	v_or_b32_e32 v140, 16, v138
	v_ashrrev_i32_e32 v141, 31, v140
	v_lshl_add_u64 v[148:149], s[82:83], 0, v[136:137]
	v_lshlrev_b64 v[152:153], 1, v[140:141]
	v_lshl_add_u64 v[140:141], v[148:149], 0, v[152:153]
	flat_load_dwordx2 v[176:177], v[140:141]
	v_lshl_add_u64 v[150:151], s[82:83], 0, v[134:135]
	v_lshl_add_u64 v[140:141], v[150:151], 0, v[152:153]
	flat_load_dwordx2 v[174:175], v[140:141]
	v_or_b32_e32 v140, 32, v138
	v_ashrrev_i32_e32 v141, 31, v140
	v_lshlrev_b64 v[144:145], 1, v[140:141]
	v_lshl_add_u64 v[140:141], v[148:149], 0, v[144:145]
	flat_load_dwordx2 v[172:173], v[140:141]
	v_lshl_add_u64 v[140:141], v[150:151], 0, v[144:145]
	v_or_b32_e32 v132, 48, v138
	flat_load_dwordx2 v[170:171], v[140:141]
	v_ashrrev_i32_e32 v133, 31, v132
	v_lshlrev_b64 v[140:141], 1, v[132:133]
	v_lshl_add_u64 v[132:133], v[148:149], 0, v[140:141]
	flat_load_dwordx2 v[168:169], v[132:133]
	v_lshl_add_u64 v[132:133], v[150:151], 0, v[140:141]
	flat_load_dwordx2 v[164:165], v[132:133]
	v_or_b32_e32 v132, 0x80, v130
	v_ashrrev_i32_e32 v133, 31, v132
	v_lshlrev_b64 v[132:133], 12, v[132:133]
	v_lshl_add_u64 v[148:149], v[142:143], 0, v[132:133]
	flat_load_dwordx2 v[162:163], v[148:149]
	v_or_b32_e32 v130, 0x90, v130
	v_ashrrev_i32_e32 v131, 31, v130
	v_lshlrev_b64 v[130:131], 12, v[130:131]
	v_lshl_add_u64 v[142:143], v[142:143], 0, v[130:131]
	flat_load_dwordx2 v[160:161], v[142:143]
	v_lshl_add_u64 v[142:143], s[82:83], 0, v[132:133]
	v_lshl_add_u64 v[148:149], v[142:143], 0, v[152:153]
	flat_load_dwordx2 v[158:159], v[148:149]
	v_lshl_add_u64 v[182:183], s[82:83], 0, v[130:131]
	v_lshl_add_u64 v[148:149], v[182:183], 0, v[152:153]
	flat_load_dwordx2 v[156:157], v[148:149]
	v_lshl_add_u64 v[148:149], v[142:143], 0, v[144:145]
	flat_load_dwordx2 v[154:155], v[148:149]
	v_lshl_add_u64 v[148:149], v[182:183], 0, v[144:145]
	flat_load_dwordx2 v[150:151], v[148:149]
	v_lshl_add_u64 v[142:143], v[142:143], 0, v[140:141]
	flat_load_dwordx2 v[148:149], v[142:143]
	v_lshl_add_u64 v[142:143], v[182:183], 0, v[140:141]
	flat_load_dwordx2 v[142:143], v[142:143]
	v_lshl_add_u64 v[166:167], s[12:13], 0, v[166:167]
	v_lshl_add_u64 v[182:183], v[166:167], 0, v[136:137]
	v_readlane_b32 s0, v254, 26
	s_add_i32 s84, s84, s0
	s_cmpk_gt_i32 s84, 0x1ff
	v_readlane_b32 s1, v254, 27
	s_waitcnt vmcnt(0) lgkmcnt(0)
	v_mul_f32_e32 v126, v126, v194
	v_mul_f32_e32 v126, 0xbfb8aa3b, v126
	v_mul_f32_e32 v127, v127, v194
	v_exp_f32_e32 v126, v126
	v_mul_f32_e32 v127, 0xbfb8aa3b, v127
	v_mul_f32_e32 v128, v128, v194
	v_exp_f32_e32 v127, v127
	v_mul_f32_e32 v128, 0xbfb8aa3b, v128
	v_mul_f32_e32 v129, v129, v194
	v_exp_f32_e32 v128, v128
	v_mul_f32_e32 v129, 0xbfb8aa3b, v129
	v_mul_f32_e32 v122, v122, v193
	v_exp_f32_e32 v129, v129
	v_mul_f32_e32 v122, 0xbfb8aa3b, v122
	v_mul_f32_e32 v123, v123, v193
	v_add_f32_e32 v126, 1.0, v126
	v_exp_f32_e32 v122, v122
	v_mul_f32_e32 v123, 0xbfb8aa3b, v123
	v_mul_f32_e32 v124, v124, v193
	v_rcp_f32_e32 v126, v126
	v_add_f32_e32 v127, 1.0, v127
	v_exp_f32_e32 v123, v123
	v_mul_f32_e32 v124, 0xbfb8aa3b, v124
	v_mul_f32_e32 v125, v125, v193
	v_rcp_f32_e32 v127, v127
	v_add_f32_e32 v128, 1.0, v128
	v_exp_f32_e32 v124, v124
	v_mul_f32_e32 v125, 0xbfb8aa3b, v125
	v_mul_f32_e32 v118, v118, v194
	v_rcp_f32_e32 v128, v128
	v_add_f32_e32 v129, 1.0, v129
	v_exp_f32_e32 v125, v125
	v_mul_f32_e32 v118, 0xbfb8aa3b, v118
	v_mul_f32_e32 v119, v119, v194
	v_rcp_f32_e32 v129, v129
	v_add_f32_e32 v122, 1.0, v122
	v_exp_f32_e32 v118, v118
	v_mul_f32_e32 v119, 0xbfb8aa3b, v119
	v_mul_f32_e32 v120, v120, v194
	v_lshlrev_b32_e32 v139, 16, v180
	v_min_f32_e32 v126, 1.0, v126
	v_rcp_f32_e32 v122, v122
	v_add_f32_e32 v123, 1.0, v123
	v_exp_f32_e32 v119, v119
	v_mul_f32_e32 v120, 0xbfb8aa3b, v120
	v_mul_f32_e32 v121, v121, v194
	v_mul_f32_e32 v126, v126, v139
	v_and_b32_e32 v139, 0xffff0000, v180
	v_min_f32_e32 v127, 1.0, v127
	v_rcp_f32_e32 v123, v123
	v_add_f32_e32 v124, 1.0, v124
	v_exp_f32_e32 v120, v120
	v_mul_f32_e32 v121, 0xbfb8aa3b, v121
	v_mul_f32_e32 v114, v114, v193
	v_mul_f32_e32 v127, v127, v139
	v_lshlrev_b32_e32 v139, 16, v181
	v_min_f32_e32 v128, 1.0, v128
	v_rcp_f32_e32 v124, v124
	v_add_f32_e32 v125, 1.0, v125
; DEVI float sigmoidf_(float x) { return fminf(__builtin_amdgcn_rcpf(1.f + __builtin_amdgcn_exp2f(-LOG2E * x)), 1.f); }
; #define EPI_HALF(AI, ...) _Pragma("unroll") for(int bj=0;bj<2;++bj) _Pragma("unroll") for(int m=0;m<4;++m) _Pragma("unroll") for(int n=0;n<2;++n) { \
;     const int ai=(AI); const int row=brow+ai*128+wr*64+m*16+fq*4; const int col=bcol+bj*128+wc*32+n*16+fr; \
;     f32x4& v=acc[ai][bj][m][n]; __VA_ARGS__ }
; #define EPI_SC4(ARR) float sc4[2][2]; _Pragma("unroll") for(int bj=0;bj<2;++bj) _Pragma("unroll") for(int n=0;n<2;++n) sc4[bj][n]=(ARR)[RSI(bcol+bj*128+wc*32+n*16+fr)];
; DEVI void run_phase(const int ph, const Params& P, char* shmc, const int wave_u) {
;     ...
;       EPI_SC4(rs2)
; #pragma unroll
;       for (int ah = 0; ah < 2; ++ah) {
;         u32x2 uu[2][4][2];
;         EPI_HALF(ah, { (void)v; uu[bj][m][n] = *reinterpret_cast<const u32x2*>(ub + (long)col * 2048 + row); })
;         EPI_HALF(ah, { const float sc = sc4[bj][n]; const u32x2 u = uu[bj][m][n];
;           st_bf4(T + (long)col * 2048 + row, __uint_as_float(u[0] << 16) * sigmoidf_(v[0] * sc), __uint_as_float(u[0] & 0xffff0000u) * sigmoidf_(v[1] * sc),
;                  __uint_as_float(u[1] << 16) * sigmoidf_(v[2] * sc), __uint_as_float(u[1] & 0xffff0000u) * sigmoidf_(v[3] * sc)); })
;       }
	v_exp_f32_e32 v121, v121
	v_mul_f32_e32 v114, 0xbfb8aa3b, v114
	v_mul_f32_e32 v115, v115, v193
	v_mul_f32_e32 v128, v128, v139
	v_and_b32_e32 v139, 0xffff0000, v181
	v_min_f32_e32 v129, 1.0, v129
	v_rcp_f32_e32 v125, v125
	v_add_f32_e32 v118, 1.0, v118
	v_exp_f32_e32 v114, v114
	v_mul_f32_e32 v115, 0xbfb8aa3b, v115
	v_mul_f32_e32 v116, v116, v193
	v_mul_f32_e32 v129, v129, v139
	v_cvt_pk_bf16_f32 v126, v126, v127
	v_cvt_pk_bf16_f32 v127, v128, v129
	v_lshlrev_b32_e32 v128, 16, v178
	v_min_f32_e32 v122, 1.0, v122
	v_rcp_f32_e32 v118, v118
	v_add_f32_e32 v119, 1.0, v119
	v_exp_f32_e32 v115, v115
	v_mul_f32_e32 v116, 0xbfb8aa3b, v116
	v_mul_f32_e32 v117, v117, v193
	v_mul_f32_e32 v122, v122, v128
	v_and_b32_e32 v128, 0xffff0000, v178
	v_min_f32_e32 v123, 1.0, v123
	v_rcp_f32_e32 v119, v119
	v_add_f32_e32 v120, 1.0, v120
	v_exp_f32_e32 v116, v116
	v_mul_f32_e32 v117, 0xbfb8aa3b, v117
	v_mul_f32_e32 v110, v110, v194
	v_mul_f32_e32 v123, v123, v128
	v_lshlrev_b32_e32 v128, 16, v179
	v_min_f32_e32 v124, 1.0, v124
	v_rcp_f32_e32 v120, v120
	v_add_f32_e32 v121, 1.0, v121
	v_exp_f32_e32 v117, v117
	v_mul_f32_e32 v110, 0xbfb8aa3b, v110
	v_mul_f32_e32 v111, v111, v194
	v_mov_b32_e32 v196, v126
	v_mov_b32_e32 v197, v127
	v_lshl_add_u64 v[212:213], v[182:183], 0, v[222:223]
	v_lshl_add_u64 v[126:127], v[166:167], 0, v[134:135]
	v_mul_f32_e32 v124, v124, v128
	v_and_b32_e32 v128, 0xffff0000, v179
	v_min_f32_e32 v125, 1.0, v125
	v_rcp_f32_e32 v121, v121
	v_add_f32_e32 v114, 1.0, v114
	v_exp_f32_e32 v110, v110
	v_mul_f32_e32 v111, 0xbfb8aa3b, v111
	v_mul_f32_e32 v112, v112, v194
	v_mul_f32_e32 v125, v125, v128
	v_cvt_pk_bf16_f32 v122, v122, v123
	v_cvt_pk_bf16_f32 v123, v124, v125
	v_mov_b32_e32 v200, v122
	v_mov_b32_e32 v201, v123
	v_lshl_add_u64 v[216:217], v[126:127], 0, v[222:223]
	v_lshlrev_b32_e32 v126, 16, v176
	v_min_f32_e32 v118, 1.0, v118
	v_rcp_f32_e32 v114, v114
	v_add_f32_e32 v115, 1.0, v115
	v_exp_f32_e32 v111, v111
	v_mul_f32_e32 v112, 0xbfb8aa3b, v112
	v_mul_f32_e32 v113, v113, v194
	v_mul_f32_e32 v118, v118, v126
	v_and_b32_e32 v126, 0xffff0000, v176
	v_min_f32_e32 v119, 1.0, v119
	v_rcp_f32_e32 v115, v115
	v_add_f32_e32 v116, 1.0, v116
	v_exp_f32_e32 v112, v112
	v_mul_f32_e32 v113, 0xbfb8aa3b, v113
	v_mul_f32_e32 v106, v106, v193
	v_lshl_add_u64 v[122:123], s[12:13], 0, v[136:137]
	v_mul_f32_e32 v119, v119, v126
	v_lshlrev_b32_e32 v126, 16, v177
	v_min_f32_e32 v120, 1.0, v120
	v_rcp_f32_e32 v116, v116
	v_add_f32_e32 v117, 1.0, v117
	v_exp_f32_e32 v113, v113
	v_mul_f32_e32 v106, 0xbfb8aa3b, v106
	v_mul_f32_e32 v107, v107, v193
	v_lshl_add_u64 v[124:125], v[122:123], 0, v[152:153]
	v_mul_f32_e32 v120, v120, v126
	v_and_b32_e32 v126, 0xffff0000, v177
	v_min_f32_e32 v121, 1.0, v121
	v_rcp_f32_e32 v117, v117
	v_add_f32_e32 v110, 1.0, v110
	v_exp_f32_e32 v106, v106
	v_mul_f32_e32 v107, 0xbfb8aa3b, v107
	v_mul_f32_e32 v108, v108, v193
	v_mul_f32_e32 v121, v121, v126
	v_cvt_pk_bf16_f32 v118, v118, v119
	v_cvt_pk_bf16_f32 v119, v120, v121
	v_mov_b32_e32 v198, v118
	v_mov_b32_e32 v199, v119
	s_nop 1
	v_permlane16_swap_b32_e32 v196, v198
	v_permlane16_swap_b32_e32 v197, v199
	flat_store_dwordx4 v[212:213], v[196:199]
	v_lshlrev_b32_e32 v124, 16, v174
	v_min_f32_e32 v114, 1.0, v114
	v_rcp_f32_e32 v110, v110
	v_add_f32_e32 v111, 1.0, v111
	v_exp_f32_e32 v107, v107
	v_mul_f32_e32 v108, 0xbfb8aa3b, v108
	v_mul_f32_e32 v109, v109, v193
	v_mul_f32_e32 v114, v114, v124
	v_and_b32_e32 v124, 0xffff0000, v174
	v_min_f32_e32 v115, 1.0, v115
	v_rcp_f32_e32 v111, v111
	v_add_f32_e32 v112, 1.0, v112
	v_exp_f32_e32 v108, v108
	v_mul_f32_e32 v109, 0xbfb8aa3b, v109
	v_mul_f32_e32 v102, v102, v194
	v_mul_f32_e32 v115, v115, v124
	v_lshlrev_b32_e32 v124, 16, v175
	v_min_f32_e32 v116, 1.0, v116
	v_rcp_f32_e32 v112, v112
	v_add_f32_e32 v113, 1.0, v113
	v_exp_f32_e32 v109, v109
	v_mul_f32_e32 v102, 0xbfb8aa3b, v102
	v_mul_f32_e32 v103, v103, v194
	v_mul_f32_e32 v116, v116, v124
	v_and_b32_e32 v124, 0xffff0000, v175
	v_min_f32_e32 v117, 1.0, v117
	v_rcp_f32_e32 v113, v113
	v_add_f32_e32 v106, 1.0, v106
	v_exp_f32_e32 v102, v102
	v_mul_f32_e32 v103, 0xbfb8aa3b, v103
	v_mul_f32_e32 v104, v104, v194
	v_mul_f32_e32 v117, v117, v124
	v_cvt_pk_bf16_f32 v114, v114, v115
	v_cvt_pk_bf16_f32 v115, v116, v117
	v_lshlrev_b32_e32 v116, 16, v172
	v_min_f32_e32 v110, 1.0, v110
	v_rcp_f32_e32 v106, v106
	v_add_f32_e32 v107, 1.0, v107
	v_exp_f32_e32 v103, v103
	v_mul_f32_e32 v104, 0xbfb8aa3b, v104
	v_mul_f32_e32 v105, v105, v194
	v_mul_f32_e32 v110, v110, v116
	v_and_b32_e32 v116, 0xffff0000, v172
	v_min_f32_e32 v111, 1.0, v111
	v_rcp_f32_e32 v107, v107
	v_add_f32_e32 v108, 1.0, v108
	v_exp_f32_e32 v104, v104
	v_mul_f32_e32 v105, 0xbfb8aa3b, v105
	v_mul_f32_e32 v98, v98, v193
	v_lshl_add_u64 v[118:119], s[12:13], 0, v[134:135]
	v_mul_f32_e32 v111, v111, v116
	v_lshlrev_b32_e32 v116, 16, v173
	v_min_f32_e32 v112, 1.0, v112
	v_rcp_f32_e32 v108, v108
	v_add_f32_e32 v109, 1.0, v109
	v_exp_f32_e32 v105, v105
	v_mul_f32_e32 v98, 0xbfb8aa3b, v98
	v_mul_f32_e32 v99, v99, v193
	v_lshl_add_u64 v[120:121], v[118:119], 0, v[152:153]
	v_mul_f32_e32 v112, v112, v116
	v_and_b32_e32 v116, 0xffff0000, v173
	v_min_f32_e32 v113, 1.0, v113
	v_rcp_f32_e32 v109, v109
	v_add_f32_e32 v102, 1.0, v102
	v_exp_f32_e32 v98, v98
	v_mul_f32_e32 v99, 0xbfb8aa3b, v99
	v_mul_f32_e32 v100, v100, v193
	v_mov_b32_e32 v202, v114
	v_mov_b32_e32 v203, v115
	s_nop 1
	v_permlane16_swap_b32_e32 v200, v202
	v_permlane16_swap_b32_e32 v201, v203
	flat_store_dwordx4 v[216:217], v[200:203]
	v_mul_f32_e32 v113, v113, v116
	v_cvt_pk_bf16_f32 v110, v110, v111
	v_cvt_pk_bf16_f32 v111, v112, v113
	v_lshlrev_b32_e32 v112, 16, v170
; DEVI float sigmoidf_(float x) { return fminf(__builtin_amdgcn_rcpf(1.f + __builtin_amdgcn_exp2f(-LOG2E * x)), 1.f); }
; #define EPI_HALF(AI, ...) _Pragma("unroll") for(int bj=0;bj<2;++bj) _Pragma("unroll") for(int m=0;m<4;++m) _Pragma("unroll") for(int n=0;n<2;++n) { \
;     const int ai=(AI); const int row=brow+ai*128+wr*64+m*16+fq*4; const int col=bcol+bj*128+wc*32+n*16+fr; \
;     f32x4& v=acc[ai][bj][m][n]; __VA_ARGS__ }
; #define EPI_SC4(ARR) float sc4[2][2]; _Pragma("unroll") for(int bj=0;bj<2;++bj) _Pragma("unroll") for(int n=0;n<2;++n) sc4[bj][n]=(ARR)[RSI(bcol+bj*128+wc*32+n*16+fr)];
; DEVI void run_phase(const int ph, const Params& P, char* shmc, const int wave_u) {
;     ...
;       EPI_SC4(rs2)
; #pragma unroll
;       for (int ah = 0; ah < 2; ++ah) {
;         u32x2 uu[2][4][2];
;         EPI_HALF(ah, { (void)v; uu[bj][m][n] = *reinterpret_cast<const u32x2*>(ub + (long)col * 2048 + row); })
;         EPI_HALF(ah, { const float sc = sc4[bj][n]; const u32x2 u = uu[bj][m][n];
;           st_bf4(T + (long)col * 2048 + row, __uint_as_float(u[0] << 16) * sigmoidf_(v[0] * sc), __uint_as_float(u[0] & 0xffff0000u) * sigmoidf_(v[1] * sc),
;                  __uint_as_float(u[1] << 16) * sigmoidf_(v[2] * sc), __uint_as_float(u[1] & 0xffff0000u) * sigmoidf_(v[3] * sc)); })
;       }
	v_min_f32_e32 v106, 1.0, v106
	v_rcp_f32_e32 v102, v102
	v_add_f32_e32 v103, 1.0, v103
	v_exp_f32_e32 v99, v99
	v_mul_f32_e32 v100, 0xbfb8aa3b, v100
	v_mul_f32_e32 v101, v101, v193
	v_mul_f32_e32 v106, v106, v112
	v_and_b32_e32 v112, 0xffff0000, v170
	v_min_f32_e32 v107, 1.0, v107
	v_rcp_f32_e32 v103, v103
	v_add_f32_e32 v104, 1.0, v104
	v_exp_f32_e32 v100, v100
	v_mul_f32_e32 v101, 0xbfb8aa3b, v101
	v_mul_f32_e32 v94, v94, v192
	v_mul_f32_e32 v107, v107, v112
	v_lshlrev_b32_e32 v112, 16, v171
	v_min_f32_e32 v108, 1.0, v108
	v_rcp_f32_e32 v104, v104
	v_add_f32_e32 v105, 1.0, v105
	v_exp_f32_e32 v101, v101
	v_mul_f32_e32 v94, 0xbfb8aa3b, v94
	v_mul_f32_e32 v95, v95, v192
	v_lshl_add_u64 v[114:115], v[122:123], 0, v[144:145]
	v_mul_f32_e32 v108, v108, v112
	v_and_b32_e32 v112, 0xffff0000, v171
	v_min_f32_e32 v109, 1.0, v109
	v_rcp_f32_e32 v105, v105
	v_add_f32_e32 v98, 1.0, v98
	v_exp_f32_e32 v94, v94
	v_mul_f32_e32 v95, 0xbfb8aa3b, v95
	v_mul_f32_e32 v96, v96, v192
	v_mov_b32_e32 v204, v110
	v_mov_b32_e32 v205, v111
	v_lshl_add_u64 v[218:219], v[114:115], 0, v[222:223]
	v_mul_f32_e32 v109, v109, v112
	v_cvt_pk_bf16_f32 v106, v106, v107
	v_cvt_pk_bf16_f32 v107, v108, v109
	v_lshlrev_b32_e32 v108, 16, v168
	v_min_f32_e32 v102, 1.0, v102
	v_rcp_f32_e32 v98, v98
	v_add_f32_e32 v99, 1.0, v99
	v_exp_f32_e32 v95, v95
	v_mul_f32_e32 v96, 0xbfb8aa3b, v96
	v_mul_f32_e32 v97, v97, v192
	v_mul_f32_e32 v102, v102, v108
	v_and_b32_e32 v108, 0xffff0000, v168
	v_min_f32_e32 v103, 1.0, v103
	v_rcp_f32_e32 v99, v99
	v_add_f32_e32 v100, 1.0, v100
	v_exp_f32_e32 v96, v96
	v_mul_f32_e32 v97, 0xbfb8aa3b, v97
	v_mul_f32_e32 v90, v90, v32
	v_mul_f32_e32 v103, v103, v108
	v_lshlrev_b32_e32 v108, 16, v169
	v_min_f32_e32 v104, 1.0, v104
	v_rcp_f32_e32 v100, v100
	v_add_f32_e32 v101, 1.0, v101
	v_exp_f32_e32 v97, v97
	v_mul_f32_e32 v90, 0xbfb8aa3b, v90
	v_mul_f32_e32 v91, v91, v32
	v_lshl_add_u64 v[110:111], v[118:119], 0, v[144:145]
	v_mul_f32_e32 v104, v104, v108
	v_and_b32_e32 v108, 0xffff0000, v169
	v_min_f32_e32 v105, 1.0, v105
	v_rcp_f32_e32 v101, v101
	v_add_f32_e32 v94, 1.0, v94
	v_exp_f32_e32 v90, v90
	v_mul_f32_e32 v91, 0xbfb8aa3b, v91
	v_mul_f32_e32 v92, v92, v32
	v_mov_b32_e32 v208, v106
	v_mov_b32_e32 v209, v107
	v_lshl_add_u64 v[220:221], v[110:111], 0, v[222:223]
	v_mul_f32_e32 v105, v105, v108
	v_cvt_pk_bf16_f32 v102, v102, v103
	v_cvt_pk_bf16_f32 v103, v104, v105
	v_lshlrev_b32_e32 v104, 16, v164
	v_min_f32_e32 v98, 1.0, v98
	v_rcp_f32_e32 v94, v94
	v_add_f32_e32 v95, 1.0, v95
	v_exp_f32_e32 v91, v91
	v_mul_f32_e32 v92, 0xbfb8aa3b, v92
	v_mul_f32_e32 v93, v93, v32
	v_mul_f32_e32 v98, v98, v104
	v_and_b32_e32 v104, 0xffff0000, v164
	v_min_f32_e32 v99, 1.0, v99
	v_rcp_f32_e32 v95, v95
	v_add_f32_e32 v96, 1.0, v96
	v_exp_f32_e32 v92, v92
	v_mul_f32_e32 v93, 0xbfb8aa3b, v93
	v_mul_f32_e32 v86, v86, v192
	v_mul_f32_e32 v99, v99, v104
	v_lshlrev_b32_e32 v104, 16, v165
	v_min_f32_e32 v100, 1.0, v100
	v_rcp_f32_e32 v96, v96
	v_add_f32_e32 v97, 1.0, v97
	v_exp_f32_e32 v93, v93
	v_mul_f32_e32 v86, 0xbfb8aa3b, v86
	v_mul_f32_e32 v87, v87, v192
	v_lshl_add_u64 v[106:107], v[122:123], 0, v[140:141]
	v_mul_f32_e32 v100, v100, v104
	v_and_b32_e32 v104, 0xffff0000, v165
	v_min_f32_e32 v101, 1.0, v101
	v_rcp_f32_e32 v97, v97
	v_add_f32_e32 v90, 1.0, v90
	v_exp_f32_e32 v86, v86
	v_mul_f32_e32 v87, 0xbfb8aa3b, v87
	v_mul_f32_e32 v88, v88, v192
	v_mov_b32_e32 v206, v102
	v_mov_b32_e32 v207, v103
	s_nop 1
	v_permlane16_swap_b32_e32 v204, v206
	v_permlane16_swap_b32_e32 v205, v207
	flat_store_dwordx4 v[218:219], v[204:207]
	v_mul_f32_e32 v101, v101, v104
	v_cvt_pk_bf16_f32 v98, v98, v99
	v_cvt_pk_bf16_f32 v99, v100, v101
	v_lshlrev_b32_e32 v100, 16, v162
	v_min_f32_e32 v94, 1.0, v94
	v_rcp_f32_e32 v90, v90
	v_add_f32_e32 v91, 1.0, v91
	v_exp_f32_e32 v87, v87
	v_mul_f32_e32 v88, 0xbfb8aa3b, v88
	v_mul_f32_e32 v89, v89, v192
	v_mul_f32_e32 v94, v94, v100
	v_and_b32_e32 v100, 0xffff0000, v162
	v_min_f32_e32 v95, 1.0, v95
	v_rcp_f32_e32 v91, v91
	v_add_f32_e32 v92, 1.0, v92
	v_exp_f32_e32 v88, v88
	v_mul_f32_e32 v89, 0xbfb8aa3b, v89
	v_mul_f32_e32 v82, v82, v32
	v_mul_f32_e32 v95, v95, v100
	v_lshlrev_b32_e32 v100, 16, v163
	v_min_f32_e32 v96, 1.0, v96
	v_rcp_f32_e32 v92, v92
	v_add_f32_e32 v93, 1.0, v93
	v_exp_f32_e32 v89, v89
	v_mul_f32_e32 v82, 0xbfb8aa3b, v82
	v_mul_f32_e32 v83, v83, v32
	v_lshl_add_u64 v[102:103], v[118:119], 0, v[140:141]
	v_mul_f32_e32 v96, v96, v100
	v_and_b32_e32 v100, 0xffff0000, v163
	v_min_f32_e32 v97, 1.0, v97
	v_rcp_f32_e32 v93, v93
	v_add_f32_e32 v86, 1.0, v86
	v_exp_f32_e32 v82, v82
	v_mul_f32_e32 v83, 0xbfb8aa3b, v83
	v_mul_f32_e32 v84, v84, v32
	v_mov_b32_e32 v210, v98
	v_mov_b32_e32 v211, v99
	s_nop 1
	v_permlane16_swap_b32_e32 v208, v210
	v_permlane16_swap_b32_e32 v209, v211
	flat_store_dwordx4 v[220:221], v[208:211]
	v_mul_f32_e32 v97, v97, v100
	v_cvt_pk_bf16_f32 v94, v94, v95
	v_cvt_pk_bf16_f32 v95, v96, v97
	v_lshlrev_b32_e32 v96, 16, v160
	v_min_f32_e32 v90, 1.0, v90
	v_rcp_f32_e32 v86, v86
	v_add_f32_e32 v87, 1.0, v87
	v_exp_f32_e32 v83, v83
	v_mul_f32_e32 v84, 0xbfb8aa3b, v84
	v_mul_f32_e32 v85, v85, v32
	v_mul_f32_e32 v90, v90, v96
	v_and_b32_e32 v96, 0xffff0000, v160
	v_min_f32_e32 v91, 1.0, v91
	v_rcp_f32_e32 v87, v87
	v_add_f32_e32 v88, 1.0, v88
	v_exp_f32_e32 v84, v84
	v_mul_f32_e32 v85, 0xbfb8aa3b, v85
	v_mul_f32_e32 v78, v78, v192
	v_lshl_add_u64 v[98:99], v[166:167], 0, v[132:133]
	v_mul_f32_e32 v91, v91, v96
	v_lshlrev_b32_e32 v96, 16, v161
	v_min_f32_e32 v92, 1.0, v92
	v_rcp_f32_e32 v88, v88
	v_add_f32_e32 v89, 1.0, v89
	v_exp_f32_e32 v85, v85
	v_mul_f32_e32 v78, 0xbfb8aa3b, v78
	v_mul_f32_e32 v79, v79, v192
; DEVI float sigmoidf_(float x) { return fminf(__builtin_amdgcn_rcpf(1.f + __builtin_amdgcn_exp2f(-LOG2E * x)), 1.f); }
; #define EPI_HALF(AI, ...) _Pragma("unroll") for(int bj=0;bj<2;++bj) _Pragma("unroll") for(int m=0;m<4;++m) _Pragma("unroll") for(int n=0;n<2;++n) { \
;     const int ai=(AI); const int row=brow+ai*128+wr*64+m*16+fq*4; const int col=bcol+bj*128+wc*32+n*16+fr; \
;     f32x4& v=acc[ai][bj][m][n]; __VA_ARGS__ }
; #define EPI_SC4(ARR) float sc4[2][2]; _Pragma("unroll") for(int bj=0;bj<2;++bj) _Pragma("unroll") for(int n=0;n<2;++n) sc4[bj][n]=(ARR)[RSI(bcol+bj*128+wc*32+n*16+fr)];
; DEVI void run_phase(const int ph, const Params& P, char* shmc, const int wave_u) {
;     ...
;       EPI_SC4(rs2)
; #pragma unroll
;       for (int ah = 0; ah < 2; ++ah) {
;         u32x2 uu[2][4][2];
;         EPI_HALF(ah, { (void)v; uu[bj][m][n] = *reinterpret_cast<const u32x2*>(ub + (long)col * 2048 + row); })
;         EPI_HALF(ah, { const float sc = sc4[bj][n]; const u32x2 u = uu[bj][m][n];
;           st_bf4(T + (long)col * 2048 + row, __uint_as_float(u[0] << 16) * sigmoidf_(v[0] * sc), __uint_as_float(u[0] & 0xffff0000u) * sigmoidf_(v[1] * sc),
;                  __uint_as_float(u[1] << 16) * sigmoidf_(v[2] * sc), __uint_as_float(u[1] & 0xffff0000u) * sigmoidf_(v[3] * sc)); })
;       }
	v_mov_b32_e32 v196, v94
	v_mov_b32_e32 v197, v95
	v_lshl_add_u64 v[212:213], v[98:99], 0, v[222:223]
	v_lshl_add_u64 v[94:95], v[166:167], 0, v[130:131]
	v_mul_f32_e32 v92, v92, v96
	v_and_b32_e32 v96, 0xffff0000, v161
	v_min_f32_e32 v93, 1.0, v93
	v_rcp_f32_e32 v89, v89
	v_add_f32_e32 v82, 1.0, v82
	v_exp_f32_e32 v78, v78
	v_mul_f32_e32 v79, 0xbfb8aa3b, v79
	v_mul_f32_e32 v80, v80, v192
	v_mul_f32_e32 v93, v93, v96
	v_cvt_pk_bf16_f32 v90, v90, v91
	v_cvt_pk_bf16_f32 v91, v92, v93
	v_mov_b32_e32 v200, v90
	v_mov_b32_e32 v201, v91
	v_lshl_add_u64 v[216:217], v[94:95], 0, v[222:223]
	v_lshlrev_b32_e32 v94, 16, v158
	v_min_f32_e32 v86, 1.0, v86
	v_rcp_f32_e32 v82, v82
	v_add_f32_e32 v83, 1.0, v83
	v_exp_f32_e32 v79, v79
	v_mul_f32_e32 v80, 0xbfb8aa3b, v80
	v_mul_f32_e32 v81, v81, v192
	v_mul_f32_e32 v86, v86, v94
	v_and_b32_e32 v94, 0xffff0000, v158
	v_min_f32_e32 v87, 1.0, v87
	v_rcp_f32_e32 v83, v83
	v_add_f32_e32 v84, 1.0, v84
	v_exp_f32_e32 v80, v80
	v_mul_f32_e32 v81, 0xbfb8aa3b, v81
	v_mul_f32_e32 v74, v74, v32
	v_lshl_add_u64 v[90:91], s[12:13], 0, v[132:133]
	v_mul_f32_e32 v87, v87, v94
	v_lshlrev_b32_e32 v94, 16, v159
	v_min_f32_e32 v88, 1.0, v88
	v_rcp_f32_e32 v84, v84
	v_add_f32_e32 v85, 1.0, v85
	v_exp_f32_e32 v81, v81
	v_mul_f32_e32 v74, 0xbfb8aa3b, v74
	v_mul_f32_e32 v75, v75, v32
	v_lshl_add_u64 v[92:93], v[90:91], 0, v[152:153]
	v_mul_f32_e32 v88, v88, v94
	v_and_b32_e32 v94, 0xffff0000, v159
	v_min_f32_e32 v89, 1.0, v89
	v_rcp_f32_e32 v85, v85
	v_add_f32_e32 v78, 1.0, v78
	v_exp_f32_e32 v74, v74
	v_mul_f32_e32 v75, 0xbfb8aa3b, v75
	v_mul_f32_e32 v76, v76, v32
	v_mul_f32_e32 v89, v89, v94
	v_cvt_pk_bf16_f32 v86, v86, v87
	v_cvt_pk_bf16_f32 v87, v88, v89
	v_mov_b32_e32 v198, v86
	v_mov_b32_e32 v199, v87
	s_nop 1
	v_permlane16_swap_b32_e32 v196, v198
	v_permlane16_swap_b32_e32 v197, v199
	flat_store_dwordx4 v[212:213], v[196:199]
	v_lshlrev_b32_e32 v92, 16, v156
	v_min_f32_e32 v82, 1.0, v82
	v_rcp_f32_e32 v78, v78
	v_add_f32_e32 v79, 1.0, v79
	v_exp_f32_e32 v75, v75
	v_mul_f32_e32 v76, 0xbfb8aa3b, v76
	v_mul_f32_e32 v77, v77, v32
	v_mul_f32_e32 v82, v82, v92
	v_and_b32_e32 v92, 0xffff0000, v156
	v_min_f32_e32 v83, 1.0, v83
	v_rcp_f32_e32 v79, v79
	v_add_f32_e32 v80, 1.0, v80
	v_exp_f32_e32 v76, v76
	v_mul_f32_e32 v77, 0xbfb8aa3b, v77
	v_mul_f32_e32 v70, v70, v192
	v_mul_f32_e32 v83, v83, v92
	v_lshlrev_b32_e32 v92, 16, v157
	v_min_f32_e32 v84, 1.0, v84
	v_rcp_f32_e32 v80, v80
	v_add_f32_e32 v81, 1.0, v81
	v_exp_f32_e32 v77, v77
	v_mul_f32_e32 v70, 0xbfb8aa3b, v70
	v_mul_f32_e32 v71, v71, v192
	v_mul_f32_e32 v84, v84, v92
	v_and_b32_e32 v92, 0xffff0000, v157
	v_min_f32_e32 v85, 1.0, v85
	v_rcp_f32_e32 v81, v81
	v_add_f32_e32 v74, 1.0, v74
	v_exp_f32_e32 v70, v70
	v_mul_f32_e32 v71, 0xbfb8aa3b, v71
	v_mul_f32_e32 v72, v72, v192
	v_mul_f32_e32 v85, v85, v92
	v_cvt_pk_bf16_f32 v82, v82, v83
	v_cvt_pk_bf16_f32 v83, v84, v85
	v_lshlrev_b32_e32 v84, 16, v154
	v_min_f32_e32 v78, 1.0, v78
	v_rcp_f32_e32 v74, v74
	v_add_f32_e32 v75, 1.0, v75
	v_exp_f32_e32 v71, v71
	v_mul_f32_e32 v72, 0xbfb8aa3b, v72
	v_mul_f32_e32 v73, v73, v192
	v_mul_f32_e32 v78, v78, v84
	v_and_b32_e32 v84, 0xffff0000, v154
	v_min_f32_e32 v79, 1.0, v79
	v_rcp_f32_e32 v75, v75
	v_add_f32_e32 v76, 1.0, v76
	v_exp_f32_e32 v72, v72
	v_mul_f32_e32 v73, 0xbfb8aa3b, v73
	v_mul_f32_e32 v66, v66, v32
	v_lshl_add_u64 v[86:87], s[12:13], 0, v[130:131]
	v_mul_f32_e32 v79, v79, v84
	v_lshlrev_b32_e32 v84, 16, v155
	v_min_f32_e32 v80, 1.0, v80
	v_rcp_f32_e32 v76, v76
	v_add_f32_e32 v77, 1.0, v77
	v_exp_f32_e32 v73, v73
	v_mul_f32_e32 v66, 0xbfb8aa3b, v66
	v_mul_f32_e32 v67, v67, v32
	v_lshl_add_u64 v[88:89], v[86:87], 0, v[152:153]
	v_mul_f32_e32 v80, v80, v84
	v_and_b32_e32 v84, 0xffff0000, v155
	v_min_f32_e32 v81, 1.0, v81
	v_rcp_f32_e32 v77, v77
	v_add_f32_e32 v70, 1.0, v70
	v_exp_f32_e32 v66, v66
	v_mul_f32_e32 v67, 0xbfb8aa3b, v67
	v_mul_f32_e32 v68, v68, v32
	v_mov_b32_e32 v202, v82
	v_mov_b32_e32 v203, v83
	s_nop 1
	v_permlane16_swap_b32_e32 v200, v202
	v_permlane16_swap_b32_e32 v201, v203
	flat_store_dwordx4 v[216:217], v[200:203]
	v_mul_f32_e32 v81, v81, v84
	v_cvt_pk_bf16_f32 v78, v78, v79
	v_cvt_pk_bf16_f32 v79, v80, v81
	v_lshlrev_b32_e32 v80, 16, v150
	v_min_f32_e32 v74, 1.0, v74
	v_rcp_f32_e32 v70, v70
	v_add_f32_e32 v71, 1.0, v71
	v_exp_f32_e32 v67, v67
	v_mul_f32_e32 v68, 0xbfb8aa3b, v68
	v_mul_f32_e32 v69, v69, v32
	v_mul_f32_e32 v74, v74, v80
	v_and_b32_e32 v80, 0xffff0000, v150
	v_min_f32_e32 v75, 1.0, v75
	v_rcp_f32_e32 v71, v71
	v_add_f32_e32 v72, 1.0, v72
	v_exp_f32_e32 v68, v68
	v_mul_f32_e32 v69, 0xbfb8aa3b, v69
	v_mul_f32_e32 v75, v75, v80
	v_lshlrev_b32_e32 v80, 16, v151
	v_min_f32_e32 v76, 1.0, v76
	v_rcp_f32_e32 v72, v72
	v_add_f32_e32 v73, 1.0, v73
	v_exp_f32_e32 v69, v69
	v_lshl_add_u64 v[82:83], v[90:91], 0, v[144:145]
	v_mul_f32_e32 v76, v76, v80
	v_and_b32_e32 v80, 0xffff0000, v151
	v_min_f32_e32 v77, 1.0, v77
	v_rcp_f32_e32 v73, v73
	v_add_f32_e32 v66, 1.0, v66
	v_mov_b32_e32 v204, v78
	v_mov_b32_e32 v205, v79
	v_lshl_add_u64 v[218:219], v[82:83], 0, v[222:223]
	v_mul_f32_e32 v77, v77, v80
	v_cvt_pk_bf16_f32 v74, v74, v75
	v_cvt_pk_bf16_f32 v75, v76, v77
	v_lshlrev_b32_e32 v76, 16, v148
	v_min_f32_e32 v70, 1.0, v70
	v_rcp_f32_e32 v66, v66
	v_add_f32_e32 v67, 1.0, v67
	v_mul_f32_e32 v70, v70, v76
	v_and_b32_e32 v76, 0xffff0000, v148
	v_min_f32_e32 v71, 1.0, v71
	v_rcp_f32_e32 v67, v67
	v_add_f32_e32 v68, 1.0, v68
	v_mul_f32_e32 v71, v71, v76
	v_lshlrev_b32_e32 v76, 16, v149
	v_min_f32_e32 v72, 1.0, v72
	v_rcp_f32_e32 v68, v68
	v_add_f32_e32 v69, 1.0, v69
	v_lshl_add_u64 v[78:79], v[86:87], 0, v[144:145]
	v_mul_f32_e32 v72, v72, v76
; DEVI float sigmoidf_(float x) { return fminf(__builtin_amdgcn_rcpf(1.f + __builtin_amdgcn_exp2f(-LOG2E * x)), 1.f); }
; #define EPI_HALF(AI, ...) _Pragma("unroll") for(int bj=0;bj<2;++bj) _Pragma("unroll") for(int m=0;m<4;++m) _Pragma("unroll") for(int n=0;n<2;++n) { \
;     const int ai=(AI); const int row=brow+ai*128+wr*64+m*16+fq*4; const int col=bcol+bj*128+wc*32+n*16+fr; \
;     f32x4& v=acc[ai][bj][m][n]; __VA_ARGS__ }
; #define EPI_SC4(ARR) float sc4[2][2]; _Pragma("unroll") for(int bj=0;bj<2;++bj) _Pragma("unroll") for(int n=0;n<2;++n) sc4[bj][n]=(ARR)[RSI(bcol+bj*128+wc*32+n*16+fr)];
; DEVI void run_phase(const int ph, const Params& P, char* shmc, const int wave_u) {
;     ...
;       EPI_SC4(rs2)
; #pragma unroll
;       for (int ah = 0; ah < 2; ++ah) {
;         u32x2 uu[2][4][2];
;         EPI_HALF(ah, { (void)v; uu[bj][m][n] = *reinterpret_cast<const u32x2*>(ub + (long)col * 2048 + row); })
;         EPI_HALF(ah, { const float sc = sc4[bj][n]; const u32x2 u = uu[bj][m][n];
;           st_bf4(T + (long)col * 2048 + row, __uint_as_float(u[0] << 16) * sigmoidf_(v[0] * sc), __uint_as_float(u[0] & 0xffff0000u) * sigmoidf_(v[1] * sc),
;                  __uint_as_float(u[1] << 16) * sigmoidf_(v[2] * sc), __uint_as_float(u[1] & 0xffff0000u) * sigmoidf_(v[3] * sc)); })
;       }
	v_and_b32_e32 v76, 0xffff0000, v149
	v_min_f32_e32 v73, 1.0, v73
	v_rcp_f32_e32 v69, v69
	v_mov_b32_e32 v208, v74
	v_mov_b32_e32 v209, v75
	v_lshl_add_u64 v[220:221], v[78:79], 0, v[222:223]
	v_mul_f32_e32 v73, v73, v76
	v_cvt_pk_bf16_f32 v70, v70, v71
	v_cvt_pk_bf16_f32 v71, v72, v73
	v_lshlrev_b32_e32 v72, 16, v142
	v_min_f32_e32 v66, 1.0, v66
	v_mul_f32_e32 v66, v66, v72
	v_and_b32_e32 v72, 0xffff0000, v142
	v_min_f32_e32 v67, 1.0, v67
	v_lshl_add_u64 v[74:75], v[90:91], 0, v[140:141]
	v_mul_f32_e32 v67, v67, v72
	v_lshlrev_b32_e32 v72, 16, v143
	v_min_f32_e32 v68, 1.0, v68
	v_mov_b32_e32 v206, v70
	v_mov_b32_e32 v207, v71
	s_nop 1
	v_permlane16_swap_b32_e32 v204, v206
	v_permlane16_swap_b32_e32 v205, v207
	flat_store_dwordx4 v[218:219], v[204:207]
	v_lshl_add_u64 v[70:71], v[86:87], 0, v[140:141]
	v_mul_f32_e32 v68, v68, v72
	v_and_b32_e32 v72, 0xffff0000, v143
	v_min_f32_e32 v69, 1.0, v69
	v_cvt_pk_bf16_f32 v66, v66, v67
	v_mul_f32_e32 v69, v69, v72
	v_cvt_pk_bf16_f32 v67, v68, v69
	v_mov_b32_e32 v210, v66
	v_mov_b32_e32 v211, v67
	s_nop 1
	v_permlane16_swap_b32_e32 v208, v210
	v_permlane16_swap_b32_e32 v209, v211
	flat_store_dwordx4 v[220:221], v[208:211]
	v_add_u32_e32 v66, 0x80, v138
	v_ashrrev_i32_e32 v67, 31, v66
	v_add_u32_e32 v68, 0xb0, v138
	v_lshlrev_b64 v[104:105], 1, v[66:67]
	v_ashrrev_i32_e32 v69, 31, v68
	v_lshl_add_u64 v[66:67], s[82:83], 0, v[104:105]
	v_lshlrev_b64 v[86:87], 1, v[68:69]
	v_lshl_add_u64 v[68:69], v[66:67], 0, v[136:137]
	flat_load_dwordx2 v[106:107], v[68:69]
	v_lshl_add_u64 v[68:69], v[66:67], 0, v[134:135]
	flat_load_dwordx2 v[102:103], v[68:69]
	v_add_u32_e32 v68, 0x90, v138
	v_ashrrev_i32_e32 v69, 31, v68
	v_lshlrev_b64 v[100:101], 1, v[68:69]
	v_lshl_add_u64 v[68:69], s[82:83], 0, v[100:101]
	v_lshl_add_u64 v[70:71], v[68:69], 0, v[136:137]
	flat_load_dwordx2 v[98:99], v[70:71]
	v_lshl_add_u64 v[70:71], v[68:69], 0, v[134:135]
	flat_load_dwordx2 v[96:97], v[70:71]
	v_add_u32_e32 v70, 0xa0, v138
	v_ashrrev_i32_e32 v71, 31, v70
	v_lshlrev_b64 v[94:95], 1, v[70:71]
	v_lshl_add_u64 v[70:71], s[82:83], 0, v[94:95]
	v_lshl_add_u64 v[72:73], v[70:71], 0, v[136:137]
	flat_load_dwordx2 v[92:93], v[72:73]
	v_lshl_add_u64 v[72:73], v[70:71], 0, v[134:135]
	flat_load_dwordx2 v[90:91], v[72:73]
	v_lshl_add_u64 v[80:81], s[82:83], 0, v[86:87]
	v_lshl_add_u64 v[72:73], v[80:81], 0, v[136:137]
	flat_load_dwordx2 v[88:89], v[72:73]
	v_lshl_add_u64 v[72:73], v[80:81], 0, v[134:135]
	flat_load_dwordx2 v[84:85], v[72:73]
	v_lshl_add_u64 v[72:73], v[66:67], 0, v[132:133]
	flat_load_dwordx2 v[82:83], v[72:73]
	v_lshl_add_u64 v[66:67], v[66:67], 0, v[130:131]
	flat_load_dwordx2 v[78:79], v[66:67]
	v_lshl_add_u64 v[66:67], v[68:69], 0, v[132:133]
	flat_load_dwordx2 v[76:77], v[66:67]
	v_lshl_add_u64 v[66:67], v[68:69], 0, v[130:131]
	flat_load_dwordx2 v[74:75], v[66:67]
	v_lshl_add_u64 v[66:67], v[70:71], 0, v[132:133]
	flat_load_dwordx2 v[72:73], v[66:67]
	v_lshl_add_u64 v[66:67], v[70:71], 0, v[130:131]
	flat_load_dwordx2 v[70:71], v[66:67]
	v_lshl_add_u64 v[66:67], v[80:81], 0, v[132:133]
	flat_load_dwordx2 v[68:69], v[66:67]
	v_lshl_add_u64 v[66:67], v[80:81], 0, v[130:131]
	flat_load_dwordx2 v[66:67], v[66:67]
	v_mul_f32_e32 v63, v63, v194
	v_mul_f32_e32 v62, v62, v194
	v_mul_f32_e32 v63, 0xbfb8aa3b, v63
	v_mul_f32_e32 v64, v64, v194
	v_mul_f32_e32 v62, 0xbfb8aa3b, v62
	v_exp_f32_e32 v63, v63
	v_mul_f32_e32 v64, 0xbfb8aa3b, v64
	v_mul_f32_e32 v65, v65, v194
	v_exp_f32_e32 v62, v62
	v_exp_f32_e32 v64, v64
	v_mul_f32_e32 v65, 0xbfb8aa3b, v65
	v_mul_f32_e32 v58, v58, v193
	v_exp_f32_e32 v65, v65
	v_mul_f32_e32 v58, 0xbfb8aa3b, v58
	v_mul_f32_e32 v59, v59, v193
	v_exp_f32_e32 v58, v58
	v_mul_f32_e32 v59, 0xbfb8aa3b, v59
	v_mul_f32_e32 v60, v60, v193
	v_add_f32_e32 v63, 1.0, v63
	v_exp_f32_e32 v59, v59
	v_mul_f32_e32 v60, 0xbfb8aa3b, v60
	v_mul_f32_e32 v61, v61, v193
	v_add_f32_e32 v62, 1.0, v62
	v_rcp_f32_e32 v63, v63
	v_add_f32_e32 v64, 1.0, v64
	v_exp_f32_e32 v60, v60
	v_mul_f32_e32 v61, 0xbfb8aa3b, v61
	v_mul_f32_e32 v54, v54, v194
	v_rcp_f32_e32 v62, v62
	v_rcp_f32_e32 v64, v64
	v_add_f32_e32 v65, 1.0, v65
	v_exp_f32_e32 v61, v61
	v_mul_f32_e32 v54, 0xbfb8aa3b, v54
	v_mul_f32_e32 v55, v55, v194
	v_rcp_f32_e32 v65, v65
	v_add_f32_e32 v58, 1.0, v58
	v_exp_f32_e32 v54, v54
	v_mul_f32_e32 v55, 0xbfb8aa3b, v55
	v_mul_f32_e32 v56, v56, v194
	v_rcp_f32_e32 v58, v58
	v_add_f32_e32 v59, 1.0, v59
	v_exp_f32_e32 v55, v55
	v_mul_f32_e32 v56, 0xbfb8aa3b, v56
	v_mul_f32_e32 v57, v57, v194
	s_waitcnt vmcnt(0) lgkmcnt(0)
; DEVI float sigmoidf_(float x) { return fminf(__builtin_amdgcn_rcpf(1.f + __builtin_amdgcn_exp2f(-LOG2E * x)), 1.f); }
; #define EPI_HALF(AI, ...) _Pragma("unroll") for(int bj=0;bj<2;++bj) _Pragma("unroll") for(int m=0;m<4;++m) _Pragma("unroll") for(int n=0;n<2;++n) { \
;     const int ai=(AI); const int row=brow+ai*128+wr*64+m*16+fq*4; const int col=bcol+bj*128+wc*32+n*16+fr; \
;     f32x4& v=acc[ai][bj][m][n]; __VA_ARGS__ }
; #define EPI_SC4(ARR) float sc4[2][2]; _Pragma("unroll") for(int bj=0;bj<2;++bj) _Pragma("unroll") for(int n=0;n<2;++n) sc4[bj][n]=(ARR)[RSI(bcol+bj*128+wc*32+n*16+fr)];
; DEVI void run_phase(const int ph, const Params& P, char* shmc, const int wave_u) {
;     ...
;       EPI_SC4(rs2)
; #pragma unroll
;       for (int ah = 0; ah < 2; ++ah) {
;         u32x2 uu[2][4][2];
;         EPI_HALF(ah, { (void)v; uu[bj][m][n] = *reinterpret_cast<const u32x2*>(ub + (long)col * 2048 + row); })
;         EPI_HALF(ah, { const float sc = sc4[bj][n]; const u32x2 u = uu[bj][m][n];
;           st_bf4(T + (long)col * 2048 + row, __uint_as_float(u[0] << 16) * sigmoidf_(v[0] * sc), __uint_as_float(u[0] & 0xffff0000u) * sigmoidf_(v[1] * sc),
;                  __uint_as_float(u[1] << 16) * sigmoidf_(v[2] * sc), __uint_as_float(u[1] & 0xffff0000u) * sigmoidf_(v[3] * sc)); })
;       }
	v_lshlrev_b32_e32 v108, 16, v106
	v_and_b32_e32 v106, 0xffff0000, v106
	v_min_f32_e32 v63, 1.0, v63
	v_rcp_f32_e32 v59, v59
	v_add_f32_e32 v60, 1.0, v60
	v_exp_f32_e32 v56, v56
	v_mul_f32_e32 v57, 0xbfb8aa3b, v57
	v_mul_f32_e32 v50, v50, v193
	v_min_f32_e32 v62, 1.0, v62
	v_mul_f32_e32 v63, v63, v106
	v_lshlrev_b32_e32 v106, 16, v107
	v_min_f32_e32 v64, 1.0, v64
	v_rcp_f32_e32 v60, v60
	v_add_f32_e32 v61, 1.0, v61
	v_exp_f32_e32 v57, v57
	v_mul_f32_e32 v50, 0xbfb8aa3b, v50
	v_mul_f32_e32 v51, v51, v193
	v_mul_f32_e32 v62, v62, v108
	v_mul_f32_e32 v64, v64, v106
	v_and_b32_e32 v106, 0xffff0000, v107
	v_min_f32_e32 v65, 1.0, v65
	v_rcp_f32_e32 v61, v61
	v_add_f32_e32 v54, 1.0, v54
	v_exp_f32_e32 v50, v50
	v_mul_f32_e32 v51, 0xbfb8aa3b, v51
	v_mul_f32_e32 v52, v52, v193
	v_mul_f32_e32 v65, v65, v106
	v_cvt_pk_bf16_f32 v62, v62, v63
	v_cvt_pk_bf16_f32 v63, v64, v65
	v_lshlrev_b32_e32 v64, 16, v102
	v_min_f32_e32 v58, 1.0, v58
	v_rcp_f32_e32 v54, v54
	v_add_f32_e32 v55, 1.0, v55
	v_exp_f32_e32 v51, v51
	v_mul_f32_e32 v52, 0xbfb8aa3b, v52
	v_mul_f32_e32 v53, v53, v193
	v_lshl_add_u64 v[80:81], s[12:13], 0, v[104:105]
	v_mul_f32_e32 v58, v58, v64
	v_and_b32_e32 v64, 0xffff0000, v102
	v_min_f32_e32 v59, 1.0, v59
	v_rcp_f32_e32 v55, v55
	v_add_f32_e32 v56, 1.0, v56
	v_exp_f32_e32 v52, v52
	v_mul_f32_e32 v53, 0xbfb8aa3b, v53
	v_mul_f32_e32 v46, v46, v194
	v_lshl_add_u64 v[104:105], v[80:81], 0, v[136:137]
	v_mul_f32_e32 v59, v59, v64
	v_lshlrev_b32_e32 v64, 16, v103
	v_min_f32_e32 v60, 1.0, v60
	v_rcp_f32_e32 v56, v56
	v_add_f32_e32 v57, 1.0, v57
	v_exp_f32_e32 v53, v53
	v_mul_f32_e32 v46, 0xbfb8aa3b, v46
	v_mul_f32_e32 v47, v47, v194
	v_mov_b32_e32 v196, v62
	v_mov_b32_e32 v197, v63
	v_lshl_add_u64 v[212:213], v[104:105], 0, v[222:223]
	v_lshl_add_u64 v[62:63], v[80:81], 0, v[134:135]
	v_mul_f32_e32 v60, v60, v64
	v_and_b32_e32 v64, 0xffff0000, v103
	v_min_f32_e32 v61, 1.0, v61
	v_rcp_f32_e32 v57, v57
	v_add_f32_e32 v50, 1.0, v50
	v_exp_f32_e32 v46, v46
	v_mul_f32_e32 v47, 0xbfb8aa3b, v47
	v_mul_f32_e32 v48, v48, v194
	v_mul_f32_e32 v61, v61, v64
	v_cvt_pk_bf16_f32 v58, v58, v59
	v_cvt_pk_bf16_f32 v59, v60, v61
	v_mov_b32_e32 v200, v58
	v_mov_b32_e32 v201, v59
	v_lshl_add_u64 v[216:217], v[62:63], 0, v[222:223]
	v_lshlrev_b32_e32 v62, 16, v98
	v_min_f32_e32 v54, 1.0, v54
	v_rcp_f32_e32 v50, v50
	v_add_f32_e32 v51, 1.0, v51
	v_exp_f32_e32 v47, v47
	v_mul_f32_e32 v48, 0xbfb8aa3b, v48
	v_mul_f32_e32 v49, v49, v194
	v_mul_f32_e32 v54, v54, v62
	v_and_b32_e32 v62, 0xffff0000, v98
	v_min_f32_e32 v55, 1.0, v55
	v_rcp_f32_e32 v51, v51
	v_add_f32_e32 v52, 1.0, v52
	v_exp_f32_e32 v48, v48
	v_mul_f32_e32 v49, 0xbfb8aa3b, v49
	v_mul_f32_e32 v42, v42, v193
	v_mul_f32_e32 v55, v55, v62
	v_lshlrev_b32_e32 v62, 16, v99
	v_min_f32_e32 v56, 1.0, v56
	v_rcp_f32_e32 v52, v52
	v_add_f32_e32 v53, 1.0, v53
	v_exp_f32_e32 v49, v49
	v_mul_f32_e32 v42, 0xbfb8aa3b, v42
	v_mul_f32_e32 v43, v43, v193
	v_mul_f32_e32 v56, v56, v62
	v_and_b32_e32 v62, 0xffff0000, v99
	v_min_f32_e32 v57, 1.0, v57
	v_rcp_f32_e32 v53, v53
	v_add_f32_e32 v46, 1.0, v46
	v_exp_f32_e32 v42, v42
	v_mul_f32_e32 v43, 0xbfb8aa3b, v43
	v_mul_f32_e32 v44, v44, v193
	v_mul_f32_e32 v57, v57, v62
	v_cvt_pk_bf16_f32 v54, v54, v55
	v_cvt_pk_bf16_f32 v55, v56, v57
	v_lshlrev_b32_e32 v56, 16, v96
	v_min_f32_e32 v50, 1.0, v50
	v_rcp_f32_e32 v46, v46
	v_add_f32_e32 v47, 1.0, v47
	v_exp_f32_e32 v43, v43
	v_mul_f32_e32 v44, 0xbfb8aa3b, v44
	v_mul_f32_e32 v45, v45, v193
	v_lshl_add_u64 v[58:59], s[12:13], 0, v[100:101]
	v_mul_f32_e32 v50, v50, v56
	v_and_b32_e32 v56, 0xffff0000, v96
	v_min_f32_e32 v51, 1.0, v51
	v_rcp_f32_e32 v47, v47
	v_add_f32_e32 v48, 1.0, v48
	v_exp_f32_e32 v44, v44
	v_mul_f32_e32 v45, 0xbfb8aa3b, v45
	v_mul_f32_e32 v38, v38, v194
	v_lshl_add_u64 v[60:61], v[58:59], 0, v[136:137]
	v_mul_f32_e32 v51, v51, v56
	v_lshlrev_b32_e32 v56, 16, v97
	v_min_f32_e32 v52, 1.0, v52
	v_rcp_f32_e32 v48, v48
	v_add_f32_e32 v49, 1.0, v49
	v_exp_f32_e32 v45, v45
	v_mul_f32_e32 v38, 0xbfb8aa3b, v38
	v_mul_f32_e32 v39, v39, v194
	v_mov_b32_e32 v198, v54
	v_mov_b32_e32 v199, v55
	s_nop 1
	v_permlane16_swap_b32_e32 v196, v198
	v_permlane16_swap_b32_e32 v197, v199
	flat_store_dwordx4 v[212:213], v[196:199]
	v_lshl_add_u64 v[54:55], v[58:59], 0, v[134:135]
	v_mul_f32_e32 v52, v52, v56
	v_and_b32_e32 v56, 0xffff0000, v97
	v_min_f32_e32 v53, 1.0, v53
	v_rcp_f32_e32 v49, v49
	v_add_f32_e32 v42, 1.0, v42
	v_exp_f32_e32 v38, v38
	v_mul_f32_e32 v39, 0xbfb8aa3b, v39
	v_mul_f32_e32 v40, v40, v194
	v_mul_f32_e32 v53, v53, v56
	v_cvt_pk_bf16_f32 v50, v50, v51
	v_cvt_pk_bf16_f32 v51, v52, v53
	v_mov_b32_e32 v202, v50
	v_mov_b32_e32 v203, v51
	s_nop 1
	v_permlane16_swap_b32_e32 v200, v202
	v_permlane16_swap_b32_e32 v201, v203
	flat_store_dwordx4 v[216:217], v[200:203]
	v_lshlrev_b32_e32 v54, 16, v92
	v_min_f32_e32 v46, 1.0, v46
	v_rcp_f32_e32 v42, v42
	v_add_f32_e32 v43, 1.0, v43
	v_exp_f32_e32 v39, v39
	v_mul_f32_e32 v40, 0xbfb8aa3b, v40
	v_mul_f32_e32 v41, v41, v194
	v_mul_f32_e32 v46, v46, v54
	v_and_b32_e32 v54, 0xffff0000, v92
	v_min_f32_e32 v47, 1.0, v47
	v_rcp_f32_e32 v43, v43
	v_add_f32_e32 v44, 1.0, v44
	v_exp_f32_e32 v40, v40
	v_mul_f32_e32 v41, 0xbfb8aa3b, v41
	v_mul_f32_e32 v34, v34, v193
	v_mul_f32_e32 v47, v47, v54
	v_lshlrev_b32_e32 v54, 16, v93
	v_min_f32_e32 v48, 1.0, v48
	v_rcp_f32_e32 v44, v44
	v_add_f32_e32 v45, 1.0, v45
	v_exp_f32_e32 v41, v41
	v_mul_f32_e32 v34, 0xbfb8aa3b, v34
	v_mul_f32_e32 v35, v35, v193
	v_mul_f32_e32 v48, v48, v54
	v_and_b32_e32 v54, 0xffff0000, v93
	v_min_f32_e32 v49, 1.0, v49
	v_rcp_f32_e32 v45, v45
	v_add_f32_e32 v38, 1.0, v38
	v_exp_f32_e32 v34, v34
	v_mul_f32_e32 v35, 0xbfb8aa3b, v35
; DEVI float sigmoidf_(float x) { return fminf(__builtin_amdgcn_rcpf(1.f + __builtin_amdgcn_exp2f(-LOG2E * x)), 1.f); }
; #define EPI_HALF(AI, ...) _Pragma("unroll") for(int bj=0;bj<2;++bj) _Pragma("unroll") for(int m=0;m<4;++m) _Pragma("unroll") for(int n=0;n<2;++n) { \
;     const int ai=(AI); const int row=brow+ai*128+wr*64+m*16+fq*4; const int col=bcol+bj*128+wc*32+n*16+fr; \
;     f32x4& v=acc[ai][bj][m][n]; __VA_ARGS__ }
; #define EPI_SC4(ARR) float sc4[2][2]; _Pragma("unroll") for(int bj=0;bj<2;++bj) _Pragma("unroll") for(int n=0;n<2;++n) sc4[bj][n]=(ARR)[RSI(bcol+bj*128+wc*32+n*16+fr)];
; DEVI void run_phase(const int ph, const Params& P, char* shmc, const int wave_u) {
;     ...
;       EPI_SC4(rs2)
; #pragma unroll
;       for (int ah = 0; ah < 2; ++ah) {
;         u32x2 uu[2][4][2];
;         EPI_HALF(ah, { (void)v; uu[bj][m][n] = *reinterpret_cast<const u32x2*>(ub + (long)col * 2048 + row); })
;         EPI_HALF(ah, { const float sc = sc4[bj][n]; const u32x2 u = uu[bj][m][n];
;           st_bf4(T + (long)col * 2048 + row, __uint_as_float(u[0] << 16) * sigmoidf_(v[0] * sc), __uint_as_float(u[0] & 0xffff0000u) * sigmoidf_(v[1] * sc),
;                  __uint_as_float(u[1] << 16) * sigmoidf_(v[2] * sc), __uint_as_float(u[1] & 0xffff0000u) * sigmoidf_(v[3] * sc)); })
;       }
	v_mul_f32_e32 v36, v36, v193
	v_mul_f32_e32 v49, v49, v54
	v_cvt_pk_bf16_f32 v46, v46, v47
	v_cvt_pk_bf16_f32 v47, v48, v49
	v_lshlrev_b32_e32 v48, 16, v90
	v_min_f32_e32 v42, 1.0, v42
	v_rcp_f32_e32 v38, v38
	v_add_f32_e32 v39, 1.0, v39
	v_exp_f32_e32 v35, v35
	v_mul_f32_e32 v36, 0xbfb8aa3b, v36
	v_mul_f32_e32 v37, v37, v193
	v_lshl_add_u64 v[50:51], s[12:13], 0, v[94:95]
	v_mul_f32_e32 v42, v42, v48
	v_and_b32_e32 v48, 0xffff0000, v90
	v_min_f32_e32 v43, 1.0, v43
	v_rcp_f32_e32 v39, v39
	v_add_f32_e32 v40, 1.0, v40
	v_exp_f32_e32 v36, v36
	v_mul_f32_e32 v37, 0xbfb8aa3b, v37
	v_mul_f32_e32 v28, v28, v192
	v_lshl_add_u64 v[52:53], v[50:51], 0, v[136:137]
	v_mul_f32_e32 v43, v43, v48
	v_lshlrev_b32_e32 v48, 16, v91
	v_min_f32_e32 v44, 1.0, v44
	v_rcp_f32_e32 v40, v40
	v_add_f32_e32 v41, 1.0, v41
	v_exp_f32_e32 v37, v37
	v_mul_f32_e32 v28, 0xbfb8aa3b, v28
	v_mul_f32_e32 v29, v29, v192
	v_mov_b32_e32 v204, v46
	v_mov_b32_e32 v205, v47
	v_lshl_add_u64 v[218:219], v[52:53], 0, v[222:223]
	v_lshl_add_u64 v[46:47], v[50:51], 0, v[134:135]
	v_mul_f32_e32 v44, v44, v48
	v_and_b32_e32 v48, 0xffff0000, v91
	v_min_f32_e32 v45, 1.0, v45
	v_rcp_f32_e32 v41, v41
	v_add_f32_e32 v34, 1.0, v34
	v_exp_f32_e32 v28, v28
	v_mul_f32_e32 v29, 0xbfb8aa3b, v29
	v_mul_f32_e32 v30, v30, v192
	v_mul_f32_e32 v45, v45, v48
	v_cvt_pk_bf16_f32 v42, v42, v43
	v_cvt_pk_bf16_f32 v43, v44, v45
	v_mov_b32_e32 v208, v42
	v_mov_b32_e32 v209, v43
	v_lshl_add_u64 v[220:221], v[46:47], 0, v[222:223]
	v_lshlrev_b32_e32 v46, 16, v88
	v_min_f32_e32 v38, 1.0, v38
	v_rcp_f32_e32 v34, v34
	v_add_f32_e32 v35, 1.0, v35
	v_exp_f32_e32 v29, v29
	v_mul_f32_e32 v30, 0xbfb8aa3b, v30
	v_mul_f32_e32 v31, v31, v192
	v_mul_f32_e32 v38, v38, v46
	v_and_b32_e32 v46, 0xffff0000, v88
	v_min_f32_e32 v39, 1.0, v39
	v_rcp_f32_e32 v35, v35
	v_add_f32_e32 v36, 1.0, v36
	v_exp_f32_e32 v30, v30
	v_mul_f32_e32 v31, 0xbfb8aa3b, v31
	v_mul_f32_e32 v24, v24, v32
	v_mul_f32_e32 v39, v39, v46
	v_lshlrev_b32_e32 v46, 16, v89
	v_min_f32_e32 v40, 1.0, v40
	v_rcp_f32_e32 v36, v36
	v_add_f32_e32 v37, 1.0, v37
	v_exp_f32_e32 v31, v31
	v_mul_f32_e32 v24, 0xbfb8aa3b, v24
	v_mul_f32_e32 v25, v25, v32
	v_mul_f32_e32 v40, v40, v46
	v_and_b32_e32 v46, 0xffff0000, v89
	v_min_f32_e32 v41, 1.0, v41
	v_rcp_f32_e32 v37, v37
	v_add_f32_e32 v28, 1.0, v28
	v_exp_f32_e32 v24, v24
	v_mul_f32_e32 v25, 0xbfb8aa3b, v25
	v_mul_f32_e32 v26, v26, v32
	v_mul_f32_e32 v41, v41, v46
	v_cvt_pk_bf16_f32 v38, v38, v39
	v_cvt_pk_bf16_f32 v39, v40, v41
	v_lshlrev_b32_e32 v40, 16, v84
	v_min_f32_e32 v34, 1.0, v34
	v_rcp_f32_e32 v28, v28
	v_add_f32_e32 v29, 1.0, v29
	v_exp_f32_e32 v25, v25
	v_mul_f32_e32 v26, 0xbfb8aa3b, v26
	v_mul_f32_e32 v27, v27, v32
	v_mul_f32_e32 v34, v34, v40
	v_and_b32_e32 v40, 0xffff0000, v84
	v_min_f32_e32 v35, 1.0, v35
	v_rcp_f32_e32 v29, v29
	v_add_f32_e32 v30, 1.0, v30
	v_exp_f32_e32 v26, v26
	v_mul_f32_e32 v27, 0xbfb8aa3b, v27
	v_mul_f32_e32 v20, v20, v192
	v_lshl_add_u64 v[42:43], s[12:13], 0, v[86:87]
	v_mul_f32_e32 v35, v35, v40
	v_lshlrev_b32_e32 v40, 16, v85
	v_min_f32_e32 v36, 1.0, v36
	v_rcp_f32_e32 v30, v30
	v_add_f32_e32 v31, 1.0, v31
	v_exp_f32_e32 v27, v27
	v_mul_f32_e32 v20, 0xbfb8aa3b, v20
	v_mul_f32_e32 v21, v21, v192
	v_lshl_add_u64 v[44:45], v[42:43], 0, v[136:137]
	v_mul_f32_e32 v36, v36, v40
	v_and_b32_e32 v40, 0xffff0000, v85
	v_min_f32_e32 v37, 1.0, v37
	v_rcp_f32_e32 v31, v31
	v_add_f32_e32 v24, 1.0, v24
	v_exp_f32_e32 v20, v20
	v_mul_f32_e32 v21, 0xbfb8aa3b, v21
	v_mul_f32_e32 v22, v22, v192
	v_mov_b32_e32 v206, v38
	v_mov_b32_e32 v207, v39
	s_nop 1
	v_permlane16_swap_b32_e32 v204, v206
	v_permlane16_swap_b32_e32 v205, v207
	flat_store_dwordx4 v[218:219], v[204:207]
	v_mul_f32_e32 v37, v37, v40
	v_cvt_pk_bf16_f32 v34, v34, v35
	v_cvt_pk_bf16_f32 v35, v36, v37
	v_lshlrev_b32_e32 v36, 16, v82
	v_min_f32_e32 v28, 1.0, v28
	v_rcp_f32_e32 v24, v24
	v_add_f32_e32 v25, 1.0, v25
	v_exp_f32_e32 v21, v21
	v_mul_f32_e32 v22, 0xbfb8aa3b, v22
	v_mul_f32_e32 v23, v23, v192
	v_mul_f32_e32 v28, v28, v36
	v_and_b32_e32 v36, 0xffff0000, v82
	v_min_f32_e32 v29, 1.0, v29
	v_rcp_f32_e32 v25, v25
	v_add_f32_e32 v26, 1.0, v26
	v_exp_f32_e32 v22, v22
	v_mul_f32_e32 v23, 0xbfb8aa3b, v23
	v_mul_f32_e32 v16, v16, v32
	v_mul_f32_e32 v29, v29, v36
	v_lshlrev_b32_e32 v36, 16, v83
	v_min_f32_e32 v30, 1.0, v30
	v_rcp_f32_e32 v26, v26
	v_add_f32_e32 v27, 1.0, v27
	v_exp_f32_e32 v23, v23
	v_mul_f32_e32 v16, 0xbfb8aa3b, v16
	v_mul_f32_e32 v17, v17, v32
	v_lshl_add_u64 v[38:39], v[42:43], 0, v[134:135]
	v_mul_f32_e32 v30, v30, v36
	v_and_b32_e32 v36, 0xffff0000, v83
	v_min_f32_e32 v31, 1.0, v31
	v_rcp_f32_e32 v27, v27
	v_add_f32_e32 v20, 1.0, v20
	v_exp_f32_e32 v16, v16
	v_mul_f32_e32 v17, 0xbfb8aa3b, v17
	v_mul_f32_e32 v18, v18, v32
	v_mov_b32_e32 v210, v34
	v_mov_b32_e32 v211, v35
	s_nop 1
	v_permlane16_swap_b32_e32 v208, v210
	v_permlane16_swap_b32_e32 v209, v211
	flat_store_dwordx4 v[220:221], v[208:211]
	v_mul_f32_e32 v31, v31, v36
	v_cvt_pk_bf16_f32 v28, v28, v29
	v_cvt_pk_bf16_f32 v29, v30, v31
	v_lshlrev_b32_e32 v30, 16, v78
	v_min_f32_e32 v24, 1.0, v24
	v_rcp_f32_e32 v20, v20
	v_add_f32_e32 v21, 1.0, v21
	v_exp_f32_e32 v17, v17
	v_mul_f32_e32 v18, 0xbfb8aa3b, v18
	v_mul_f32_e32 v19, v19, v32
	v_mul_f32_e32 v24, v24, v30
	v_and_b32_e32 v30, 0xffff0000, v78
	v_min_f32_e32 v25, 1.0, v25
	v_rcp_f32_e32 v21, v21
	v_add_f32_e32 v22, 1.0, v22
	v_exp_f32_e32 v18, v18
	v_mul_f32_e32 v19, 0xbfb8aa3b, v19
	v_mul_f32_e32 v12, v12, v192
	v_mul_f32_e32 v25, v25, v30
	v_lshlrev_b32_e32 v30, 16, v79
	v_min_f32_e32 v26, 1.0, v26
	v_rcp_f32_e32 v22, v22
	v_add_f32_e32 v23, 1.0, v23
	v_exp_f32_e32 v19, v19
	v_mul_f32_e32 v12, 0xbfb8aa3b, v12
; DEVI float sigmoidf_(float x) { return fminf(__builtin_amdgcn_rcpf(1.f + __builtin_amdgcn_exp2f(-LOG2E * x)), 1.f); }
; #define EPI_HALF(AI, ...) _Pragma("unroll") for(int bj=0;bj<2;++bj) _Pragma("unroll") for(int m=0;m<4;++m) _Pragma("unroll") for(int n=0;n<2;++n) { \
;     const int ai=(AI); const int row=brow+ai*128+wr*64+m*16+fq*4; const int col=bcol+bj*128+wc*32+n*16+fr; \
;     f32x4& v=acc[ai][bj][m][n]; __VA_ARGS__ }
; #define EPI_SC4(ARR) float sc4[2][2]; _Pragma("unroll") for(int bj=0;bj<2;++bj) _Pragma("unroll") for(int n=0;n<2;++n) sc4[bj][n]=(ARR)[RSI(bcol+bj*128+wc*32+n*16+fr)];
; DEVI void run_phase(const int ph, const Params& P, char* shmc, const int wave_u) {
;     ...
;       EPI_SC4(rs2)
; #pragma unroll
;       for (int ah = 0; ah < 2; ++ah) {
;         u32x2 uu[2][4][2];
;         EPI_HALF(ah, { (void)v; uu[bj][m][n] = *reinterpret_cast<const u32x2*>(ub + (long)col * 2048 + row); })
;         EPI_HALF(ah, { const float sc = sc4[bj][n]; const u32x2 u = uu[bj][m][n];
;           st_bf4(T + (long)col * 2048 + row, __uint_as_float(u[0] << 16) * sigmoidf_(v[0] * sc), __uint_as_float(u[0] & 0xffff0000u) * sigmoidf_(v[1] * sc),
;                  __uint_as_float(u[1] << 16) * sigmoidf_(v[2] * sc), __uint_as_float(u[1] & 0xffff0000u) * sigmoidf_(v[3] * sc)); })
;       }
	v_mul_f32_e32 v13, v13, v192
	v_lshl_add_u64 v[34:35], v[80:81], 0, v[132:133]
	v_mul_f32_e32 v26, v26, v30
	v_and_b32_e32 v30, 0xffff0000, v79
	v_min_f32_e32 v27, 1.0, v27
	v_rcp_f32_e32 v23, v23
	v_add_f32_e32 v16, 1.0, v16
	v_exp_f32_e32 v12, v12
	v_mul_f32_e32 v13, 0xbfb8aa3b, v13
	v_mul_f32_e32 v14, v14, v192
	v_mov_b32_e32 v196, v28
	v_mov_b32_e32 v197, v29
	v_lshl_add_u64 v[212:213], v[34:35], 0, v[222:223]
	v_mul_f32_e32 v27, v27, v30
	v_cvt_pk_bf16_f32 v24, v24, v25
	v_cvt_pk_bf16_f32 v25, v26, v27
	v_lshlrev_b32_e32 v26, 16, v76
	v_min_f32_e32 v20, 1.0, v20
	v_rcp_f32_e32 v16, v16
	v_add_f32_e32 v17, 1.0, v17
	v_exp_f32_e32 v13, v13
	v_mul_f32_e32 v14, 0xbfb8aa3b, v14
	v_mul_f32_e32 v15, v15, v192
	v_mul_f32_e32 v20, v20, v26
	v_and_b32_e32 v26, 0xffff0000, v76
	v_min_f32_e32 v21, 1.0, v21
	v_rcp_f32_e32 v17, v17
	v_add_f32_e32 v18, 1.0, v18
	v_exp_f32_e32 v14, v14
	v_mul_f32_e32 v15, 0xbfb8aa3b, v15
	v_mul_f32_e32 v8, v8, v32
	v_mul_f32_e32 v21, v21, v26
	v_lshlrev_b32_e32 v26, 16, v77
	v_min_f32_e32 v22, 1.0, v22
	v_rcp_f32_e32 v18, v18
	v_add_f32_e32 v19, 1.0, v19
	v_exp_f32_e32 v15, v15
	v_mul_f32_e32 v8, 0xbfb8aa3b, v8
	v_mul_f32_e32 v9, v9, v32
	v_lshl_add_u64 v[28:29], v[80:81], 0, v[130:131]
	v_mul_f32_e32 v22, v22, v26
	v_and_b32_e32 v26, 0xffff0000, v77
	v_min_f32_e32 v23, 1.0, v23
	v_rcp_f32_e32 v19, v19
	v_add_f32_e32 v12, 1.0, v12
	v_exp_f32_e32 v8, v8
	v_mul_f32_e32 v9, 0xbfb8aa3b, v9
	v_mul_f32_e32 v10, v10, v32
	v_mov_b32_e32 v200, v24
	v_mov_b32_e32 v201, v25
	v_lshl_add_u64 v[216:217], v[28:29], 0, v[222:223]
	v_mul_f32_e32 v23, v23, v26
	v_cvt_pk_bf16_f32 v20, v20, v21
	v_cvt_pk_bf16_f32 v21, v22, v23
	v_lshlrev_b32_e32 v22, 16, v74
	v_min_f32_e32 v16, 1.0, v16
	v_rcp_f32_e32 v12, v12
	v_add_f32_e32 v13, 1.0, v13
	v_exp_f32_e32 v9, v9
	v_mul_f32_e32 v10, 0xbfb8aa3b, v10
	v_mul_f32_e32 v11, v11, v32
	v_mul_f32_e32 v16, v16, v22
	v_and_b32_e32 v22, 0xffff0000, v74
	v_min_f32_e32 v17, 1.0, v17
	v_rcp_f32_e32 v13, v13
	v_add_f32_e32 v14, 1.0, v14
	v_exp_f32_e32 v10, v10
	v_mul_f32_e32 v11, 0xbfb8aa3b, v11
	v_mul_f32_e32 v4, v4, v192
	v_mul_f32_e32 v17, v17, v22
	v_lshlrev_b32_e32 v22, 16, v75
	v_min_f32_e32 v18, 1.0, v18
	v_rcp_f32_e32 v14, v14
	v_add_f32_e32 v15, 1.0, v15
	v_exp_f32_e32 v11, v11
	v_mul_f32_e32 v4, 0xbfb8aa3b, v4
	v_mul_f32_e32 v5, v5, v192
	v_lshl_add_u64 v[24:25], v[58:59], 0, v[132:133]
	v_mul_f32_e32 v18, v18, v22
	v_and_b32_e32 v22, 0xffff0000, v75
	v_min_f32_e32 v19, 1.0, v19
	v_rcp_f32_e32 v15, v15
	v_add_f32_e32 v8, 1.0, v8
	v_exp_f32_e32 v4, v4
	v_mul_f32_e32 v5, 0xbfb8aa3b, v5
	v_mul_f32_e32 v6, v6, v192
	v_mov_b32_e32 v198, v20
	v_mov_b32_e32 v199, v21
	s_nop 1
	v_permlane16_swap_b32_e32 v196, v198
	v_permlane16_swap_b32_e32 v197, v199
	flat_store_dwordx4 v[212:213], v[196:199]
	v_mul_f32_e32 v19, v19, v22
	v_cvt_pk_bf16_f32 v16, v16, v17
	v_cvt_pk_bf16_f32 v17, v18, v19
	v_lshlrev_b32_e32 v18, 16, v72
	v_min_f32_e32 v12, 1.0, v12
	v_rcp_f32_e32 v8, v8
	v_add_f32_e32 v9, 1.0, v9
	v_exp_f32_e32 v5, v5
	v_mul_f32_e32 v6, 0xbfb8aa3b, v6
	v_mul_f32_e32 v7, v7, v192
	v_mul_f32_e32 v12, v12, v18
	v_and_b32_e32 v18, 0xffff0000, v72
	v_min_f32_e32 v13, 1.0, v13
	v_rcp_f32_e32 v9, v9
	v_add_f32_e32 v10, 1.0, v10
	v_exp_f32_e32 v6, v6
	v_mul_f32_e32 v7, 0xbfb8aa3b, v7
	v_mul_f32_e32 v0, v0, v32
	v_mul_f32_e32 v13, v13, v18
	v_lshlrev_b32_e32 v18, 16, v73
	v_min_f32_e32 v14, 1.0, v14
	v_rcp_f32_e32 v10, v10
	v_add_f32_e32 v11, 1.0, v11
	v_exp_f32_e32 v7, v7
	v_mul_f32_e32 v0, 0xbfb8aa3b, v0
	v_mul_f32_e32 v1, v1, v32
	v_lshl_add_u64 v[20:21], v[58:59], 0, v[130:131]
	v_mul_f32_e32 v14, v14, v18
	v_and_b32_e32 v18, 0xffff0000, v73
	v_min_f32_e32 v15, 1.0, v15
	v_rcp_f32_e32 v11, v11
	v_add_f32_e32 v4, 1.0, v4
	v_exp_f32_e32 v0, v0
	v_mul_f32_e32 v1, 0xbfb8aa3b, v1
	v_mul_f32_e32 v2, v2, v32
	v_mov_b32_e32 v202, v16
	v_mov_b32_e32 v203, v17
	s_nop 1
	v_permlane16_swap_b32_e32 v200, v202
	v_permlane16_swap_b32_e32 v201, v203
	flat_store_dwordx4 v[216:217], v[200:203]
	v_mul_f32_e32 v15, v15, v18
	v_cvt_pk_bf16_f32 v12, v12, v13
	v_cvt_pk_bf16_f32 v13, v14, v15
	v_lshlrev_b32_e32 v14, 16, v70
	v_min_f32_e32 v8, 1.0, v8
	v_rcp_f32_e32 v4, v4
	v_add_f32_e32 v5, 1.0, v5
	v_exp_f32_e32 v1, v1
	v_mul_f32_e32 v2, 0xbfb8aa3b, v2
	v_mul_f32_e32 v3, v3, v32
	v_mul_f32_e32 v8, v8, v14
	v_and_b32_e32 v14, 0xffff0000, v70
	v_min_f32_e32 v9, 1.0, v9
	v_rcp_f32_e32 v5, v5
	v_add_f32_e32 v6, 1.0, v6
	v_exp_f32_e32 v2, v2
	v_mul_f32_e32 v3, 0xbfb8aa3b, v3
	v_mul_f32_e32 v9, v9, v14
	v_lshlrev_b32_e32 v14, 16, v71
	v_min_f32_e32 v10, 1.0, v10
	v_rcp_f32_e32 v6, v6
	v_add_f32_e32 v7, 1.0, v7
	v_exp_f32_e32 v3, v3
	v_lshl_add_u64 v[16:17], v[50:51], 0, v[132:133]
	v_mul_f32_e32 v10, v10, v14
	v_and_b32_e32 v14, 0xffff0000, v71
	v_min_f32_e32 v11, 1.0, v11
	v_rcp_f32_e32 v7, v7
	v_add_f32_e32 v0, 1.0, v0
	v_mov_b32_e32 v204, v12
	v_mov_b32_e32 v205, v13
	v_lshl_add_u64 v[218:219], v[16:17], 0, v[222:223]
	v_mul_f32_e32 v11, v11, v14
	v_cvt_pk_bf16_f32 v8, v8, v9
	v_cvt_pk_bf16_f32 v9, v10, v11
	v_lshlrev_b32_e32 v10, 16, v68
	v_min_f32_e32 v4, 1.0, v4
	v_rcp_f32_e32 v0, v0
	v_add_f32_e32 v1, 1.0, v1
	v_mul_f32_e32 v4, v4, v10
	v_and_b32_e32 v10, 0xffff0000, v68
	v_min_f32_e32 v5, 1.0, v5
	v_rcp_f32_e32 v1, v1
	v_add_f32_e32 v2, 1.0, v2
	v_mul_f32_e32 v5, v5, v10
	v_lshlrev_b32_e32 v10, 16, v69
	v_min_f32_e32 v6, 1.0, v6
	v_rcp_f32_e32 v2, v2
	v_add_f32_e32 v3, 1.0, v3
	v_lshl_add_u64 v[12:13], v[50:51], 0, v[130:131]
	v_mul_f32_e32 v6, v6, v10
	v_and_b32_e32 v10, 0xffff0000, v69
	v_min_f32_e32 v7, 1.0, v7
	v_rcp_f32_e32 v3, v3
	v_mov_b32_e32 v208, v8
	v_mov_b32_e32 v209, v9
	v_lshl_add_u64 v[220:221], v[12:13], 0, v[222:223]
	v_mul_f32_e32 v7, v7, v10
	v_cvt_pk_bf16_f32 v4, v4, v5
	v_cvt_pk_bf16_f32 v5, v6, v7
	v_lshlrev_b32_e32 v6, 16, v66
	v_min_f32_e32 v0, 1.0, v0
	v_mul_f32_e32 v0, v0, v6
	v_and_b32_e32 v6, 0xffff0000, v66
	v_min_f32_e32 v1, 1.0, v1
	v_lshl_add_u64 v[8:9], v[42:43], 0, v[132:133]
	v_mul_f32_e32 v1, v1, v6
	v_lshlrev_b32_e32 v6, 16, v67
	v_min_f32_e32 v2, 1.0, v2
	v_mov_b32_e32 v206, v4
	v_mov_b32_e32 v207, v5
	s_nop 1
	v_permlane16_swap_b32_e32 v204, v206
	v_permlane16_swap_b32_e32 v205, v207
	flat_store_dwordx4 v[218:219], v[204:207]
	v_lshl_add_u64 v[4:5], v[42:43], 0, v[130:131]
	v_mul_f32_e32 v2, v2, v6
	v_and_b32_e32 v6, 0xffff0000, v67
	v_min_f32_e32 v3, 1.0, v3
	v_mul_f32_e32 v3, v3, v6
	v_cvt_pk_bf16_f32 v0, v0, v1
	v_cvt_pk_bf16_f32 v1, v2, v3
	v_mov_b32_e32 v210, v0
	v_mov_b32_e32 v211, v1
	s_nop 1
	v_permlane16_swap_b32_e32 v208, v210
	v_permlane16_swap_b32_e32 v209, v211
	flat_store_dwordx4 v[220:221], v[208:211]
	s_cbranch_scc1 .LBB0_42

; #define EPI_LOOP(...) _Pragma("unroll") for(int ai=0;ai<2;++ai) _Pragma("unroll") for(int bj=0;bj<2;++bj) \
;   _Pragma("unroll") for(int m=0;m<4;++m) _Pragma("unroll") for(int n=0;n<2;++n) { \
;     const int row=brow+ai*128+wr*64+m*16+fq*4; const int col=bcol+bj*128+wc*32+n*16+fr; \
;     f32x4& v=acc[ai][bj][m][n]; __VA_ARGS__ if (n == 1 && (m & 1)) __builtin_amdgcn_sched_barrier(0); }
; DEVI void run_phase(const int ph, const Params& P, char* shmc, const int wave_u) {
;     ...
;       { GEMM_IDS
;       EPI_LOOP({ st_bf4(ub + (long)col * 2048 + row, v[0], v[1], v[2], v[3]); })
;       }
.LBB0_64:
	s_or_b64 exec, exec, s[8:9]
	v_mbcnt_lo_u32_b32 v178, -1, 0
	v_mbcnt_hi_u32_b32 v178, -1, v178
	v_bfe_u32 v178, v178, 4, 1
	v_mul_u32_u24_e32 v178, 24, v178
	v_mov_b32_e32 v179, 0
	v_mbcnt_lo_u32_b32 v32, -1, 0
	v_mbcnt_hi_u32_b32 v32, -1, v32
	v_cvt_pk_bf16_f32 v126, v126, v127
	v_cvt_pk_bf16_f32 v127, v128, v129
	s_nop 0
	v_or_b32_e32 v131, s5, v32
	v_and_b32_e32 v132, 15, v32
	v_ashrrev_i32_e32 v130, 2, v131
	v_lshrrev_b32_e32 v32, 2, v32
	v_and_b32_e32 v130, 0xffffffc0, v130
	v_and_or_b32 v32, v32, 12, s0
	v_add_u32_e32 v130, v32, v130
	v_lshrrev_b32_e32 v32, 1, v131
	v_and_b32_e32 v32, 0x60, v32
	v_or3_b32 v132, v132, v32, s6
	v_ashrrev_i32_e32 v131, 31, v130
	v_ashrrev_i32_e32 v133, 31, v132
	v_lshl_add_u64 v[134:135], v[130:131], 1, s[82:83]
	v_lshlrev_b64 v[136:137], 12, v[132:133]
	v_lshl_add_u64 v[138:139], v[134:135], 0, v[136:137]
	v_mov_b32_e32 v156, v126
	v_mov_b32_e32 v157, v127
	v_lshl_add_u64 v[142:143], v[138:139], 0, v[178:179]
	v_or_b32_e32 v126, 16, v132
	v_ashrrev_i32_e32 v127, 31, v126
	v_lshlrev_b64 v[126:127], 12, v[126:127]
	v_lshl_add_u64 v[128:129], v[134:135], 0, v[126:127]
	v_cvt_pk_bf16_f32 v122, v122, v123
	v_cvt_pk_bf16_f32 v123, v124, v125
	v_mov_b32_e32 v160, v122
	v_mov_b32_e32 v161, v123
	v_lshl_add_u64 v[172:173], v[128:129], 0, v[178:179]
	v_cvt_pk_bf16_f32 v118, v118, v119
	v_cvt_pk_bf16_f32 v119, v120, v121
	v_mov_b32_e32 v158, v118
	v_mov_b32_e32 v159, v119
	s_nop 1
	v_permlane16_swap_b32_e32 v156, v158
	v_permlane16_swap_b32_e32 v157, v159
	flat_store_dwordx4 v[142:143], v[156:159]
	v_cvt_pk_bf16_f32 v114, v114, v115
	v_cvt_pk_bf16_f32 v115, v116, v117
	v_mov_b32_e32 v162, v114
	v_mov_b32_e32 v163, v115
	s_nop 1
	v_permlane16_swap_b32_e32 v160, v162
	v_permlane16_swap_b32_e32 v161, v163
	flat_store_dwordx4 v[172:173], v[160:163]
	v_cvt_pk_bf16_f32 v110, v110, v111
	v_cvt_pk_bf16_f32 v111, v112, v113
	v_mov_b32_e32 v164, v110
	v_mov_b32_e32 v165, v111
	v_lshl_add_u64 v[174:175], v[138:139], 0, v[178:179]
	v_cvt_pk_bf16_f32 v106, v106, v107
	v_cvt_pk_bf16_f32 v107, v108, v109
	v_mov_b32_e32 v168, v106
	v_mov_b32_e32 v169, v107
	v_lshl_add_u64 v[176:177], v[128:129], 0, v[178:179]
	v_cvt_pk_bf16_f32 v102, v102, v103
	v_cvt_pk_bf16_f32 v103, v104, v105
	v_mov_b32_e32 v166, v102
	v_mov_b32_e32 v167, v103
	s_nop 1
	v_permlane16_swap_b32_e32 v164, v166
	v_permlane16_swap_b32_e32 v165, v167
	flat_store_dwordx4 v[174:175], v[164:167] offset:64
	v_cvt_pk_bf16_f32 v98, v98, v99
	v_cvt_pk_bf16_f32 v99, v100, v101
	v_mov_b32_e32 v170, v98
	v_mov_b32_e32 v171, v99
	s_nop 1
	v_permlane16_swap_b32_e32 v168, v170
	v_permlane16_swap_b32_e32 v169, v171
	flat_store_dwordx4 v[176:177], v[168:171] offset:64
	v_or_b32_e32 v98, 0x80, v132
	v_ashrrev_i32_e32 v99, 31, v98
	v_lshlrev_b64 v[98:99], 12, v[98:99]
	v_lshl_add_u64 v[100:101], v[134:135], 0, v[98:99]
	v_cvt_pk_bf16_f32 v94, v94, v95
	v_cvt_pk_bf16_f32 v95, v96, v97
	v_mov_b32_e32 v156, v94
	v_mov_b32_e32 v157, v95
	v_lshl_add_u64 v[142:143], v[100:101], 0, v[178:179]
	v_or_b32_e32 v94, 0x90, v132
	v_ashrrev_i32_e32 v95, 31, v94
	v_lshlrev_b64 v[94:95], 12, v[94:95]
	v_lshl_add_u64 v[96:97], v[134:135], 0, v[94:95]
	v_cvt_pk_bf16_f32 v90, v90, v91
	v_cvt_pk_bf16_f32 v91, v92, v93
	v_mov_b32_e32 v160, v90
	v_mov_b32_e32 v161, v91
	v_lshl_add_u64 v[172:173], v[96:97], 0, v[178:179]
	v_cvt_pk_bf16_f32 v86, v86, v87
	v_cvt_pk_bf16_f32 v87, v88, v89
	v_mov_b32_e32 v158, v86
	v_mov_b32_e32 v159, v87
	s_nop 1
	v_permlane16_swap_b32_e32 v156, v158
	v_permlane16_swap_b32_e32 v157, v159
	flat_store_dwordx4 v[142:143], v[156:159]
	v_cvt_pk_bf16_f32 v82, v82, v83
	v_cvt_pk_bf16_f32 v83, v84, v85
	v_mov_b32_e32 v162, v82
	v_mov_b32_e32 v163, v83
	s_nop 1
	v_permlane16_swap_b32_e32 v160, v162
	v_permlane16_swap_b32_e32 v161, v163
	flat_store_dwordx4 v[172:173], v[160:163]
	v_cvt_pk_bf16_f32 v78, v78, v79
	v_cvt_pk_bf16_f32 v79, v80, v81
	v_mov_b32_e32 v164, v78
	v_mov_b32_e32 v165, v79
	v_lshl_add_u64 v[174:175], v[100:101], 0, v[178:179]
	v_cvt_pk_bf16_f32 v74, v74, v75
	v_cvt_pk_bf16_f32 v75, v76, v77
	v_mov_b32_e32 v168, v74
	v_mov_b32_e32 v169, v75
	v_lshl_add_u64 v[176:177], v[96:97], 0, v[178:179]
	v_cvt_pk_bf16_f32 v70, v70, v71
	v_cvt_pk_bf16_f32 v71, v72, v73
	v_mov_b32_e32 v166, v70
	v_mov_b32_e32 v167, v71
	s_nop 1
	v_permlane16_swap_b32_e32 v164, v166
	v_permlane16_swap_b32_e32 v165, v167
	flat_store_dwordx4 v[174:175], v[164:167] offset:64
	v_cvt_pk_bf16_f32 v66, v66, v67
	v_cvt_pk_bf16_f32 v67, v68, v69
	v_mov_b32_e32 v170, v66
	v_mov_b32_e32 v171, v67
	s_nop 1
	v_permlane16_swap_b32_e32 v168, v170
	v_permlane16_swap_b32_e32 v169, v171
	flat_store_dwordx4 v[176:177], v[168:171] offset:64
	v_add_u32_e32 v66, 0x80, v130
	v_ashrrev_i32_e32 v67, 31, v66
	v_lshl_add_u64 v[66:67], v[66:67], 1, s[82:83]
	v_lshl_add_u64 v[68:69], v[66:67], 0, v[136:137]
	v_cvt_pk_bf16_f32 v62, v62, v63
	v_cvt_pk_bf16_f32 v63, v64, v65
	v_mov_b32_e32 v156, v62
	v_mov_b32_e32 v157, v63
	v_lshl_add_u64 v[142:143], v[68:69], 0, v[178:179]
	v_lshl_add_u64 v[62:63], v[66:67], 0, v[126:127]
	v_cvt_pk_bf16_f32 v58, v58, v59
	v_cvt_pk_bf16_f32 v59, v60, v61
	v_mov_b32_e32 v160, v58
	v_mov_b32_e32 v161, v59
	v_lshl_add_u64 v[172:173], v[62:63], 0, v[178:179]
	v_add_u32_e32 v58, 0x90, v130
	v_ashrrev_i32_e32 v59, 31, v58
	v_lshl_add_u64 v[58:59], v[58:59], 1, s[82:83]
	v_lshl_add_u64 v[60:61], v[58:59], 0, v[136:137]
	v_cvt_pk_bf16_f32 v54, v54, v55
	v_cvt_pk_bf16_f32 v55, v56, v57
	v_mov_b32_e32 v158, v54
	v_mov_b32_e32 v159, v55
	s_nop 1
	v_permlane16_swap_b32_e32 v156, v158
	v_permlane16_swap_b32_e32 v157, v159
	flat_store_dwordx4 v[142:143], v[156:159]
	v_lshl_add_u64 v[54:55], v[58:59], 0, v[126:127]
;   #define STAGE(P,BASE,LD,br,kt) do{const char* _ub=(const char*)((BASE)+(long)(br)*(LD)+(long)(kt)*BK); \
;     for(int _i=0;_i<2;++_i){int _b=tidg*16+_i*8192;int _r,_c;stage_rc(_b,_r,_c); \
;       const unsigned _vo=(unsigned)(_r*(int)(LD)+_c)*2u; \
;       __builtin_amdgcn_global_load_lds((const unsigned*)(_ub+_vo), \
;         (unsigned*)((char*)(P)+_b),16,0,0);}}while(0)
;   #define WAIT_V(n) asm volatile("s_waitcnt vmcnt(" #n ")":::"memory")
;   #define BAR __builtin_amdgcn_s_barrier()
; #define EPI_LOOP(...) _Pragma("unroll") for(int ai=0;ai<2;++ai) _Pragma("unroll") for(int bj=0;bj<2;++bj) \
;   _Pragma("unroll") for(int m=0;m<4;++m) _Pragma("unroll") for(int n=0;n<2;++n) { \
;     const int row=brow+ai*128+wr*64+m*16+fq*4; const int col=bcol+bj*128+wc*32+n*16+fr; \
;     f32x4& v=acc[ai][bj][m][n]; __VA_ARGS__ if (n == 1 && (m & 1)) __builtin_amdgcn_sched_barrier(0); }
; DEVI void gemm_core(const bf16* __restrict__ A, const long lda, const bf16* __restrict__ Bt, const long ldb, const int K,
;                     acc_t& acc, bf16* shm, const int wave_u) {
;     ...
;   int tidg = get_tid(wave_u);
;   const int wid=tidg>>6,lane=tidg&63,wr=wid>>2,wc=wid&3,fr=lane&15,fq=lane>>4;
;   bf16x8 At[4][2],B0[2][2],B1[2][2];
;   const int nt=K/BK;
;   WAIT_V(0);
;   STAGE(SB(0,0),Bt,ldb,0,0); STAGE(SA(0,0),A,lda,0,0);
;   STAGE(SB(0,1),Bt,ldb,HALF,0); STAGE(SA(0,1),A,lda,HALF,0);
;   if(wr==1)BAR;
; DEVI void run_phase(const int ph, const Params& P, char* shmc, const int wave_u) {
;     ...
;       { GEMM_IDS
;       EPI_LOOP({ st_bf4(ub + (long)col * 2048 + row, v[0], v[1], v[2], v[3]); })
;       }
	v_cvt_pk_bf16_f32 v50, v50, v51
	v_cvt_pk_bf16_f32 v51, v52, v53
	v_mov_b32_e32 v162, v50
	v_mov_b32_e32 v163, v51
	s_nop 1
	v_permlane16_swap_b32_e32 v160, v162
	v_permlane16_swap_b32_e32 v161, v163
	flat_store_dwordx4 v[172:173], v[160:163]
	v_add_u32_e32 v50, 0xa0, v130
	v_ashrrev_i32_e32 v51, 31, v50
	v_lshl_add_u64 v[50:51], v[50:51], 1, s[82:83]
	v_lshl_add_u64 v[52:53], v[50:51], 0, v[136:137]
	v_cvt_pk_bf16_f32 v46, v46, v47
	v_cvt_pk_bf16_f32 v47, v48, v49
	v_mov_b32_e32 v164, v46
	v_mov_b32_e32 v165, v47
	v_lshl_add_u64 v[174:175], v[52:53], 0, v[178:179]
	v_lshl_add_u64 v[46:47], v[50:51], 0, v[126:127]
	v_cvt_pk_bf16_f32 v42, v42, v43
	v_cvt_pk_bf16_f32 v43, v44, v45
	v_mov_b32_e32 v168, v42
	v_mov_b32_e32 v169, v43
	v_lshl_add_u64 v[176:177], v[46:47], 0, v[178:179]
	v_add_u32_e32 v42, 0xb0, v130
	v_ashrrev_i32_e32 v43, 31, v42
	v_lshl_add_u64 v[42:43], v[42:43], 1, s[82:83]
	v_lshl_add_u64 v[44:45], v[42:43], 0, v[136:137]
	v_cvt_pk_bf16_f32 v38, v38, v39
	v_cvt_pk_bf16_f32 v39, v40, v41
	v_mov_b32_e32 v166, v38
	v_mov_b32_e32 v167, v39
	s_nop 1
	v_permlane16_swap_b32_e32 v164, v166
	v_permlane16_swap_b32_e32 v165, v167
	flat_store_dwordx4 v[174:175], v[164:167]
	v_lshl_add_u64 v[38:39], v[42:43], 0, v[126:127]
	v_cvt_pk_bf16_f32 v34, v34, v35
	v_cvt_pk_bf16_f32 v35, v36, v37
	v_mov_b32_e32 v170, v34
	v_mov_b32_e32 v171, v35
	s_nop 1
	v_permlane16_swap_b32_e32 v168, v170
	v_permlane16_swap_b32_e32 v169, v171
	flat_store_dwordx4 v[176:177], v[168:171]
	v_lshl_add_u64 v[34:35], v[66:67], 0, v[98:99]
	v_cvt_pk_bf16_f32 v28, v28, v29
	v_cvt_pk_bf16_f32 v29, v30, v31
	v_mov_b32_e32 v156, v28
	v_mov_b32_e32 v157, v29
	v_lshl_add_u64 v[142:143], v[34:35], 0, v[178:179]
	v_lshl_add_u64 v[28:29], v[66:67], 0, v[94:95]
	v_cvt_pk_bf16_f32 v24, v24, v25
	v_cvt_pk_bf16_f32 v25, v26, v27
	v_mov_b32_e32 v160, v24
	v_mov_b32_e32 v161, v25
	v_lshl_add_u64 v[172:173], v[28:29], 0, v[178:179]
	v_lshl_add_u64 v[24:25], v[58:59], 0, v[98:99]
	v_cvt_pk_bf16_f32 v20, v20, v21
	v_cvt_pk_bf16_f32 v21, v22, v23
	v_mov_b32_e32 v158, v20
	v_mov_b32_e32 v159, v21
	s_nop 1
	v_permlane16_swap_b32_e32 v156, v158
	v_permlane16_swap_b32_e32 v157, v159
	flat_store_dwordx4 v[142:143], v[156:159]
	v_lshl_add_u64 v[20:21], v[58:59], 0, v[94:95]
	v_cvt_pk_bf16_f32 v16, v16, v17
	v_cvt_pk_bf16_f32 v17, v18, v19
	v_mov_b32_e32 v162, v16
	v_mov_b32_e32 v163, v17
	s_nop 1
	v_permlane16_swap_b32_e32 v160, v162
	v_permlane16_swap_b32_e32 v161, v163
	flat_store_dwordx4 v[172:173], v[160:163]
	v_lshl_add_u64 v[16:17], v[50:51], 0, v[98:99]
	v_cvt_pk_bf16_f32 v12, v12, v13
	v_cvt_pk_bf16_f32 v13, v14, v15
	v_mov_b32_e32 v164, v12
	v_mov_b32_e32 v165, v13
	v_lshl_add_u64 v[174:175], v[16:17], 0, v[178:179]
	v_lshl_add_u64 v[12:13], v[50:51], 0, v[94:95]
	v_cvt_pk_bf16_f32 v8, v8, v9
	v_cvt_pk_bf16_f32 v9, v10, v11
	v_mov_b32_e32 v168, v8
	v_mov_b32_e32 v169, v9
	v_lshl_add_u64 v[176:177], v[12:13], 0, v[178:179]
	v_lshl_add_u64 v[8:9], v[42:43], 0, v[98:99]
	v_cvt_pk_bf16_f32 v4, v4, v5
	v_cvt_pk_bf16_f32 v5, v6, v7
	v_mov_b32_e32 v166, v4
	v_mov_b32_e32 v167, v5
	s_nop 1
	v_permlane16_swap_b32_e32 v164, v166
	v_permlane16_swap_b32_e32 v165, v167
	flat_store_dwordx4 v[174:175], v[164:167]
	v_lshl_add_u64 v[4:5], v[42:43], 0, v[94:95]
	v_cvt_pk_bf16_f32 v0, v0, v1
	v_cvt_pk_bf16_f32 v1, v2, v3
	v_mov_b32_e32 v170, v0
	v_mov_b32_e32 v171, v1
	s_nop 1
	v_permlane16_swap_b32_e32 v168, v170
	v_permlane16_swap_b32_e32 v169, v171
	flat_store_dwordx4 v[176:177], v[168:171]
	v_mov_b32_e32 v0, v33
	v_mbcnt_lo_u32_b32 v10, -1, 0
	v_mbcnt_hi_u32_b32 v10, -1, v10
	s_lshl_b64 s[8:9], s[0:1], 12
	v_or_b32_e32 v140, s5, v10
	v_bfe_i32 v2, v140, 27, 1
	v_lshlrev_b32_e32 v14, 4, v140
	v_lshrrev_b32_e32 v2, 22, v2
	v_add_u32_e32 v2, v14, v2
	v_and_b32_e32 v2, 0xfffffc00, v2
	v_sub_u32_e32 v2, v14, v2
	v_lshrrev_b32_e32 v3, 4, v2
	v_ashrrev_i32_e32 v1, 31, v140
	v_bitop3_b32 v2, v3, v2, 32 bitop3:0x6c
	v_lshrrev_b32_e32 v1, 26, v1
	v_ashrrev_i32_e32 v4, 31, v2
	v_add_u32_e32 v1, v140, v1
	v_lshrrev_b32_e32 v4, 26, v4
	v_ashrrev_i32_e32 v1, 6, v1
	v_add_u32_e32 v4, v2, v4
	v_lshlrev_b32_e32 v3, 3, v1
	v_ashrrev_i32_e32 v11, 6, v4
	v_and_b32_e32 v4, 0xc0, v4
	v_and_b32_e32 v3, 0xffff0, v3
	v_lshlrev_b32_e32 v5, 5, v1
	v_sub_u32_e32 v2, v2, v4
	v_add_u32_e32 v3, v11, v3
	v_and_b32_e32 v12, 32, v5
	v_ashrrev_i16_sdwa v2, v187, sext(v2) dst_sel:DWORD dst_unused:UNUSED_PAD src0_sel:DWORD src1_sel:BYTE_0
	v_bfe_i32 v13, v2, 0, 16
	v_lshl_or_b32 v2, v3, 11, v12
	v_add_lshl_u32 v32, v2, v13, 1
	v_add_u32_e32 v2, 0x2000, v14
	v_ashrrev_i32_e32 v3, 31, v2
	v_lshrrev_b32_e32 v3, 22, v3
	v_add_u32_e32 v3, v2, v3
	v_ashrrev_i32_e32 v15, 10, v3
	v_mul_i32_i24_e32 v3, 0x400, v15
	v_sub_u32_e32 v3, v2, v3
	v_lshrrev_b32_e32 v4, 4, v3
	v_bitop3_b32 v3, v4, v3, 32 bitop3:0x6c
	v_ashrrev_i32_e32 v5, 31, v3
	v_lshrrev_b32_e32 v5, 26, v5
	v_add_u32_e32 v5, v3, v5
	v_lshlrev_b32_e32 v4, 3, v15
	v_ashrrev_i32_e32 v16, 6, v5
	v_and_b32_e32 v5, 0xc0, v5
	v_readlane_b32 s16, v255, 21
	v_and_b32_e32 v4, 0xffff0, v4
	v_lshlrev_b32_e32 v6, 5, v15
	v_sub_u32_e32 v3, v3, v5
	v_readlane_b32 s17, v255, 22
	s_add_u32 s38, s16, s8
	v_add_u32_e32 v4, v16, v4
	v_and_b32_e32 v17, 32, v6
	v_ashrrev_i16_sdwa v3, v187, sext(v3) dst_sel:DWORD dst_unused:UNUSED_PAD src0_sel:DWORD src1_sel:BYTE_0
	s_addc_u32 s39, s17, s9
	s_lshl_b64 s[68:69], s[6:7], 12
	v_readlane_b32 s16, v255, 17
	v_add_u32_e32 v145, s33, v14
	v_bfe_i32 v18, v3, 0, 16
	v_lshl_or_b32 v3, v4, 11, v17
	v_readlane_b32 s17, v255, 18
	s_add_u32 s70, s16, s68
	v_readfirstlane_b32 s1, v145
	v_add_lshl_u32 v130, v3, v18, 1
	v_add_u32_e32 v3, s33, v2
	s_addc_u32 s71, s17, s69
	s_waitcnt vmcnt(0)
	s_mov_b32 m0, s1
	v_readfirstlane_b32 s1, v3
	v_add_u32_e32 v149, 16, v14
	global_load_lds_dwordx4 v32, s[70:71]
	s_mov_b32 m0, s1
	v_readfirstlane_b32 s1, v149
	v_add_u32_e32 v150, 0x2000, v149
	global_load_lds_dwordx4 v130, s[70:71]
	s_mov_b32 m0, s1
	v_readfirstlane_b32 s1, v150
	v_add_u32_e32 v152, s74, v14
	global_load_lds_dwordx4 v32, s[38:39]
	s_mov_b32 m0, s1
	s_add_u32 s72, s70, 0x80000
	v_readfirstlane_b32 s1, v152
	v_add_u32_e32 v2, s74, v2
	global_load_lds_dwordx4 v130, s[38:39]
	s_addc_u32 s73, s71, 0
	s_mov_b32 m0, s1
	v_readfirstlane_b32 s1, v2
	global_load_lds_dwordx4 v32, s[72:73]
	s_mov_b32 m0, s1
	v_add_u32_e32 v153, 0x4000, v149
	global_load_lds_dwordx4 v130, s[72:73]
	s_add_u32 s72, s38, 0x80000
	v_readfirstlane_b32 s1, v153
	v_add_u32_e32 v154, 0x6000, v149
	s_addc_u32 s73, s39, 0
	s_mov_b32 m0, s1
	v_readfirstlane_b32 s1, v154
	global_load_lds_dwordx4 v32, s[72:73]
	s_mov_b32 m0, s1
	v_mov_b32_e32 v131, v33
	global_load_lds_dwordx4 v130, s[72:73]
	v_ashrrev_i32_e32 v19, 8, v140
	v_lshl_add_u64 v[8:9], s[70:71], 0, v[32:33]
	v_lshl_add_u64 v[6:7], s[70:71], 0, v[130:131]
	v_lshl_add_u64 v[4:5], s[38:39], 0, v[32:33]
	v_lshl_add_u64 v[2:3], s[38:39], 0, v[130:131]
	v_cmp_eq_u32_e32 vcc, 1, v19
	s_and_saveexec_b64 s[72:73], vcc
	s_cbranch_execz .LBB0_66
	s_barrier

; #define ACC_ZERO(acc) { float z_ = 0.f; asm volatile("" : "+v"(z_)); _Pragma("unroll") for(int ai=0;ai<2;++ai) _Pragma("unroll") for(int bj=0;bj<2;++bj) \
;   _Pragma("unroll") for(int m=0;m<4;++m) _Pragma("unroll") for(int n=0;n<2;++n) acc[ai][bj][m][n]=f32x4{z_,z_,z_,z_}; }
; #define EPI_LOOP(...) _Pragma("unroll") for(int ai=0;ai<2;++ai) _Pragma("unroll") for(int bj=0;bj<2;++bj) \
;   _Pragma("unroll") for(int m=0;m<4;++m) _Pragma("unroll") for(int n=0;n<2;++n) { \
;     const int row=brow+ai*128+wr*64+m*16+fq*4; const int col=bcol+bj*128+wc*32+n*16+fr; \
;     f32x4& v=acc[ai][bj][m][n]; __VA_ARGS__ if (n == 1 && (m & 1)) __builtin_amdgcn_sched_barrier(0); }
; DEVI void run_phase(const int ph, const Params& P, char* shmc, const int wave_u) {
;     ...
;       } else {
;         const int r = j - 128;
;         const int brow = (r & 7) * 256, bcol = MP + (r >> 3) * 256;
;         acc_t acc; ACC_ZERO(acc)
;         gemm_core(w_ple_t + (long)brow * 256, 256, pb + (long)bcol * 256, 256, 256, acc, shm, wave_u);
;         GEMM_IDS
;         EPI_LOOP({ st_bf4(ub + (long)col * 2048 + row, v[0], v[1], v[2], v[3]); })
;       }
.LBB0_77:
	s_or_b64 exec, exec, s[0:1]
	v_mbcnt_lo_u32_b32 v160, -1, 0
	v_mbcnt_hi_u32_b32 v160, -1, v160
	v_bfe_u32 v160, v160, 4, 1
	v_mul_u32_u24_e32 v160, 24, v160
	v_mov_b32_e32 v161, 0
	v_mbcnt_lo_u32_b32 v32, -1, 0
	v_mbcnt_hi_u32_b32 v32, -1, v32
	v_readlane_b32 s0, v254, 47
	v_or_b32_e32 v131, s5, v32
	v_and_b32_e32 v132, 15, v32
	v_ashrrev_i32_e32 v130, 2, v131
	v_lshrrev_b32_e32 v32, 2, v32
	v_and_b32_e32 v130, 0xffffffc0, v130
	v_and_or_b32 v32, v32, 12, s38
	v_add_u32_e32 v130, v32, v130
	v_lshrrev_b32_e32 v32, 1, v131
	v_and_b32_e32 v32, 0x60, v32
	v_or3_b32 v32, v132, v32, s0
	v_ashrrev_i32_e32 v131, 31, v130
	v_lshl_add_u64 v[130:131], v[130:131], 1, s[82:83]
	v_lshlrev_b64 v[132:133], 12, v[32:33]
	v_lshl_add_u64 v[132:133], v[130:131], 0, v[132:133]
	v_cvt_pk_bf16_f32 v126, v126, v127
	v_cvt_pk_bf16_f32 v127, v128, v129
	v_mov_b32_e32 v136, v126
	v_mov_b32_e32 v137, v127
	v_lshl_add_u64 v[134:135], v[132:133], 0, v[160:161]
	v_or_b32_e32 v126, 16, v32
	v_mov_b32_e32 v127, v33
	v_lshlrev_b64 v[126:127], 12, v[126:127]
	v_readlane_b32 s1, v254, 48
	v_lshl_add_u64 v[126:127], v[130:131], 0, v[126:127]
	v_cvt_pk_bf16_f32 v122, v122, v123
	v_cvt_pk_bf16_f32 v123, v124, v125
	v_mov_b32_e32 v140, v122
	v_mov_b32_e32 v141, v123
	v_lshl_add_u64 v[144:145], v[126:127], 0, v[160:161]
	v_cvt_pk_bf16_f32 v118, v118, v119
	v_cvt_pk_bf16_f32 v119, v120, v121
	v_mov_b32_e32 v138, v118
	v_mov_b32_e32 v139, v119
	s_nop 1
	v_permlane16_swap_b32_e32 v136, v138
	v_permlane16_swap_b32_e32 v137, v139
	flat_store_dwordx4 v[134:135], v[136:139]
	v_cvt_pk_bf16_f32 v114, v114, v115
	v_cvt_pk_bf16_f32 v115, v116, v117
	v_mov_b32_e32 v142, v114
	v_mov_b32_e32 v143, v115
	s_nop 1
	v_permlane16_swap_b32_e32 v140, v142
	v_permlane16_swap_b32_e32 v141, v143
	flat_store_dwordx4 v[144:145], v[140:143]
	v_cvt_pk_bf16_f32 v110, v110, v111
	v_cvt_pk_bf16_f32 v111, v112, v113
	v_mov_b32_e32 v148, v110
	v_mov_b32_e32 v149, v111
	v_lshl_add_u64 v[156:157], v[132:133], 0, v[160:161]
	v_cvt_pk_bf16_f32 v106, v106, v107
	v_cvt_pk_bf16_f32 v107, v108, v109
	v_mov_b32_e32 v152, v106
	v_mov_b32_e32 v153, v107
	v_lshl_add_u64 v[158:159], v[126:127], 0, v[160:161]
	v_cvt_pk_bf16_f32 v102, v102, v103
	v_cvt_pk_bf16_f32 v103, v104, v105
	v_mov_b32_e32 v150, v102
	v_mov_b32_e32 v151, v103
	s_nop 1
	v_permlane16_swap_b32_e32 v148, v150
	v_permlane16_swap_b32_e32 v149, v151
	flat_store_dwordx4 v[156:157], v[148:151] offset:64
	v_cvt_pk_bf16_f32 v98, v98, v99
	v_cvt_pk_bf16_f32 v99, v100, v101
	v_mov_b32_e32 v154, v98
	v_mov_b32_e32 v155, v99
	s_nop 1
	v_permlane16_swap_b32_e32 v152, v154
	v_permlane16_swap_b32_e32 v153, v155
	flat_store_dwordx4 v[158:159], v[152:155] offset:64
	v_or_b32_e32 v98, 0x80, v32
	v_mov_b32_e32 v99, v33
	v_lshlrev_b64 v[98:99], 12, v[98:99]
	v_lshl_add_u64 v[98:99], v[130:131], 0, v[98:99]
	v_cvt_pk_bf16_f32 v94, v94, v95
	v_cvt_pk_bf16_f32 v95, v96, v97
	v_or_b32_e32 v32, 0x90, v32
	v_mov_b32_e32 v136, v94
	v_mov_b32_e32 v137, v95
	v_lshl_add_u64 v[134:135], v[98:99], 0, v[160:161]
	v_lshlrev_b64 v[94:95], 12, v[32:33]
	v_lshl_add_u64 v[94:95], v[130:131], 0, v[94:95]
	v_cvt_pk_bf16_f32 v90, v90, v91
	v_cvt_pk_bf16_f32 v91, v92, v93
	v_mov_b32_e32 v140, v90
	v_mov_b32_e32 v141, v91
	v_lshl_add_u64 v[144:145], v[94:95], 0, v[160:161]
	v_cvt_pk_bf16_f32 v86, v86, v87
	v_cvt_pk_bf16_f32 v87, v88, v89
	v_mov_b32_e32 v138, v86
	v_mov_b32_e32 v139, v87
	s_nop 1
	v_permlane16_swap_b32_e32 v136, v138
	v_permlane16_swap_b32_e32 v137, v139
	flat_store_dwordx4 v[134:135], v[136:139]
	v_cvt_pk_bf16_f32 v82, v82, v83
	v_cvt_pk_bf16_f32 v83, v84, v85
	v_mov_b32_e32 v142, v82
	v_mov_b32_e32 v143, v83
	s_nop 1
	v_permlane16_swap_b32_e32 v140, v142
	v_permlane16_swap_b32_e32 v141, v143
	flat_store_dwordx4 v[144:145], v[140:143]
	v_cvt_pk_bf16_f32 v78, v78, v79
	v_cvt_pk_bf16_f32 v79, v80, v81
	v_mov_b32_e32 v148, v78
	v_mov_b32_e32 v149, v79
	v_lshl_add_u64 v[156:157], v[98:99], 0, v[160:161]
	v_cvt_pk_bf16_f32 v74, v74, v75
	v_cvt_pk_bf16_f32 v75, v76, v77
; #define ACC_ZERO(acc) { float z_ = 0.f; asm volatile("" : "+v"(z_)); _Pragma("unroll") for(int ai=0;ai<2;++ai) _Pragma("unroll") for(int bj=0;bj<2;++bj) \
;   _Pragma("unroll") for(int m=0;m<4;++m) _Pragma("unroll") for(int n=0;n<2;++n) acc[ai][bj][m][n]=f32x4{z_,z_,z_,z_}; }
; #define EPI_LOOP(...) _Pragma("unroll") for(int ai=0;ai<2;++ai) _Pragma("unroll") for(int bj=0;bj<2;++bj) \
;   _Pragma("unroll") for(int m=0;m<4;++m) _Pragma("unroll") for(int n=0;n<2;++n) { \
;     const int row=brow+ai*128+wr*64+m*16+fq*4; const int col=bcol+bj*128+wc*32+n*16+fr; \
;     f32x4& v=acc[ai][bj][m][n]; __VA_ARGS__ if (n == 1 && (m & 1)) __builtin_amdgcn_sched_barrier(0); }
; DEVI void run_phase(const int ph, const Params& P, char* shmc, const int wave_u) {
;     ...
;       } else {
;         const int r = j - 128;
;         const int brow = (r & 7) * 256, bcol = MP + (r >> 3) * 256;
;         acc_t acc; ACC_ZERO(acc)
;         gemm_core(w_ple_t + (long)brow * 256, 256, pb + (long)bcol * 256, 256, 256, acc, shm, wave_u);
;         GEMM_IDS
;         EPI_LOOP({ st_bf4(ub + (long)col * 2048 + row, v[0], v[1], v[2], v[3]); })
;       }
	v_mov_b32_e32 v152, v74
	v_mov_b32_e32 v153, v75
	v_lshl_add_u64 v[158:159], v[94:95], 0, v[160:161]
	v_cvt_pk_bf16_f32 v70, v70, v71
	v_cvt_pk_bf16_f32 v71, v72, v73
	v_mov_b32_e32 v150, v70
	v_mov_b32_e32 v151, v71
	s_nop 1
	v_permlane16_swap_b32_e32 v148, v150
	v_permlane16_swap_b32_e32 v149, v151
	flat_store_dwordx4 v[156:157], v[148:151] offset:64
	v_cvt_pk_bf16_f32 v62, v62, v63
	v_cvt_pk_bf16_f32 v63, v64, v65
	v_mov_b32_e32 v154, v62
	v_mov_b32_e32 v155, v63
	s_nop 1
	v_permlane16_swap_b32_e32 v152, v154
	v_permlane16_swap_b32_e32 v153, v155
	flat_store_dwordx4 v[158:159], v[152:155] offset:64
	v_cvt_pk_bf16_f32 v62, v66, v67
	v_cvt_pk_bf16_f32 v63, v68, v69
	v_mov_b32_e32 v136, v62
	v_mov_b32_e32 v137, v63
	v_lshl_add_u64 v[134:135], v[132:133], 0, v[160:161]
	v_cvt_pk_bf16_f32 v58, v58, v59
	v_cvt_pk_bf16_f32 v59, v60, v61
	v_mov_b32_e32 v140, v58
	v_mov_b32_e32 v141, v59
	v_lshl_add_u64 v[144:145], v[126:127], 0, v[160:161]
	v_cvt_pk_bf16_f32 v54, v54, v55
	v_cvt_pk_bf16_f32 v55, v56, v57
	v_mov_b32_e32 v138, v54
	v_mov_b32_e32 v139, v55
	s_nop 1
	v_permlane16_swap_b32_e32 v136, v138
	v_permlane16_swap_b32_e32 v137, v139
	flat_store_dwordx4 v[134:135], v[136:139] offset:256
	v_cvt_pk_bf16_f32 v50, v50, v51
	v_cvt_pk_bf16_f32 v51, v52, v53
	v_mov_b32_e32 v142, v50
	v_mov_b32_e32 v143, v51
	s_nop 1
	v_permlane16_swap_b32_e32 v140, v142
	v_permlane16_swap_b32_e32 v141, v143
	flat_store_dwordx4 v[144:145], v[140:143] offset:256
	v_cvt_pk_bf16_f32 v46, v46, v47
	v_cvt_pk_bf16_f32 v47, v48, v49
	v_mov_b32_e32 v148, v46
	v_mov_b32_e32 v149, v47
	v_lshl_add_u64 v[156:157], v[132:133], 0, v[160:161]
	v_cvt_pk_bf16_f32 v42, v42, v43
	v_cvt_pk_bf16_f32 v43, v44, v45
	v_mov_b32_e32 v152, v42
	v_mov_b32_e32 v153, v43
	v_lshl_add_u64 v[158:159], v[126:127], 0, v[160:161]
	v_cvt_pk_bf16_f32 v38, v38, v39
	v_cvt_pk_bf16_f32 v39, v40, v41
	v_mov_b32_e32 v150, v38
	v_mov_b32_e32 v151, v39
	s_nop 1
	v_permlane16_swap_b32_e32 v148, v150
	v_permlane16_swap_b32_e32 v149, v151
	flat_store_dwordx4 v[156:157], v[148:151] offset:320
	v_cvt_pk_bf16_f32 v34, v34, v35
	v_cvt_pk_bf16_f32 v35, v36, v37
	v_mov_b32_e32 v154, v34
	v_mov_b32_e32 v155, v35
	s_nop 1
	v_permlane16_swap_b32_e32 v152, v154
	v_permlane16_swap_b32_e32 v153, v155
	flat_store_dwordx4 v[158:159], v[152:155] offset:320
	v_cvt_pk_bf16_f32 v28, v28, v29
	v_cvt_pk_bf16_f32 v29, v30, v31
	v_mov_b32_e32 v136, v28
	v_mov_b32_e32 v137, v29
	v_lshl_add_u64 v[134:135], v[98:99], 0, v[160:161]
	v_cvt_pk_bf16_f32 v24, v24, v25
	v_cvt_pk_bf16_f32 v25, v26, v27
	v_mov_b32_e32 v140, v24
	v_mov_b32_e32 v141, v25
	v_lshl_add_u64 v[144:145], v[94:95], 0, v[160:161]
	v_cvt_pk_bf16_f32 v20, v20, v21
	v_cvt_pk_bf16_f32 v21, v22, v23
	v_mov_b32_e32 v138, v20
	v_mov_b32_e32 v139, v21
	s_nop 1
	v_permlane16_swap_b32_e32 v136, v138
	v_permlane16_swap_b32_e32 v137, v139
	flat_store_dwordx4 v[134:135], v[136:139] offset:256
	v_cvt_pk_bf16_f32 v16, v16, v17
	v_cvt_pk_bf16_f32 v17, v18, v19
	v_mov_b32_e32 v142, v16
	v_mov_b32_e32 v143, v17
	s_nop 1
	v_permlane16_swap_b32_e32 v140, v142
	v_permlane16_swap_b32_e32 v141, v143
	flat_store_dwordx4 v[144:145], v[140:143] offset:256
	v_cvt_pk_bf16_f32 v12, v12, v13
	v_cvt_pk_bf16_f32 v13, v14, v15
	v_mov_b32_e32 v148, v12
	v_mov_b32_e32 v149, v13
	v_lshl_add_u64 v[156:157], v[98:99], 0, v[160:161]
	v_cvt_pk_bf16_f32 v8, v8, v9
	v_cvt_pk_bf16_f32 v9, v10, v11
	v_mov_b32_e32 v152, v8
	v_mov_b32_e32 v153, v9
	v_lshl_add_u64 v[158:159], v[94:95], 0, v[160:161]
	v_cvt_pk_bf16_f32 v4, v4, v5
	v_cvt_pk_bf16_f32 v5, v6, v7
	v_mov_b32_e32 v150, v4
	v_mov_b32_e32 v151, v5
	s_nop 1
	v_permlane16_swap_b32_e32 v148, v150
	v_permlane16_swap_b32_e32 v149, v151
	flat_store_dwordx4 v[156:157], v[148:151] offset:320
	v_cvt_pk_bf16_f32 v0, v0, v1
	v_cvt_pk_bf16_f32 v1, v2, v3
	v_mov_b32_e32 v154, v0
	v_mov_b32_e32 v155, v1
	s_nop 1
	v_permlane16_swap_b32_e32 v152, v154
	v_permlane16_swap_b32_e32 v153, v155
	flat_store_dwordx4 v[158:159], v[152:155] offset:320
	s_mov_b64 s[0:1], 0

; #define EPI_LOOP(...) _Pragma("unroll") for(int ai=0;ai<2;++ai) _Pragma("unroll") for(int bj=0;bj<2;++bj) \
;   _Pragma("unroll") for(int m=0;m<4;++m) _Pragma("unroll") for(int n=0;n<2;++n) { \
;     const int row=brow+ai*128+wr*64+m*16+fq*4; const int col=bcol+bj*128+wc*32+n*16+fr; \
;     f32x4& v=acc[ai][bj][m][n]; __VA_ARGS__ if (n == 1 && (m & 1)) __builtin_amdgcn_sched_barrier(0); }
; DEVI void run_phase(const int ph, const Params& P, char* shmc, const int wave_u) {
;     ...
;       gemm_core(w_out_t + (long)brow * 2048, 2048, merged + (long)bcol * 2048, 2048, 2048, acc, shm, wave_u);
;       GEMM_IDS
;       EPI_LOOP({ st_bf4(T + (long)col * 2048 + row, v[0], v[1], v[2], v[3]); })
.LBB0_96:
	s_or_b64 exec, exec, s[6:7]
	v_mbcnt_lo_u32_b32 v166, -1, 0
	v_mbcnt_hi_u32_b32 v166, -1, v166
	v_bfe_u32 v166, v166, 4, 1
	v_mul_u32_u24_e32 v166, 24, v166
	v_mov_b32_e32 v167, 0
	v_mbcnt_lo_u32_b32 v32, -1, 0
	v_mbcnt_hi_u32_b32 v32, -1, v32
	v_cvt_pk_bf16_f32 v126, v126, v127
	v_cvt_pk_bf16_f32 v127, v128, v129
	s_nop 0
	v_or_b32_e32 v131, s5, v32
	v_and_b32_e32 v132, 15, v32
	v_ashrrev_i32_e32 v130, 2, v131
	v_lshrrev_b32_e32 v32, 2, v32
	v_and_b32_e32 v130, 0xffffffc0, v130
	v_and_or_b32 v32, v32, 12, s38
	v_add_u32_e32 v130, v32, v130
	v_lshrrev_b32_e32 v32, 1, v131
	v_and_b32_e32 v32, 0x60, v32
	v_or3_b32 v132, v132, v32, s68
	v_ashrrev_i32_e32 v131, 31, v130
	v_ashrrev_i32_e32 v133, 31, v132
	v_lshl_add_u64 v[134:135], v[130:131], 1, s[12:13]
	v_lshlrev_b64 v[136:137], 12, v[132:133]
	v_lshl_add_u64 v[138:139], v[134:135], 0, v[136:137]
	v_mov_b32_e32 v140, v126
	v_mov_b32_e32 v141, v127
	v_lshl_add_u64 v[144:145], v[138:139], 0, v[166:167]
	v_or_b32_e32 v126, 16, v132
	v_ashrrev_i32_e32 v127, 31, v126
	v_lshlrev_b64 v[126:127], 12, v[126:127]
	v_lshl_add_u64 v[128:129], v[134:135], 0, v[126:127]
	v_cvt_pk_bf16_f32 v122, v122, v123
	v_cvt_pk_bf16_f32 v123, v124, v125
	v_mov_b32_e32 v148, v122
	v_mov_b32_e32 v149, v123
	v_lshl_add_u64 v[160:161], v[128:129], 0, v[166:167]
	v_cvt_pk_bf16_f32 v118, v118, v119
	v_cvt_pk_bf16_f32 v119, v120, v121
	v_mov_b32_e32 v142, v118
	v_mov_b32_e32 v143, v119
	s_nop 1
	v_permlane16_swap_b32_e32 v140, v142
	v_permlane16_swap_b32_e32 v141, v143
	flat_store_dwordx4 v[144:145], v[140:143]
	v_cvt_pk_bf16_f32 v114, v114, v115
	v_cvt_pk_bf16_f32 v115, v116, v117
	v_mov_b32_e32 v150, v114
	v_mov_b32_e32 v151, v115
	s_nop 1
	v_permlane16_swap_b32_e32 v148, v150
	v_permlane16_swap_b32_e32 v149, v151
	flat_store_dwordx4 v[160:161], v[148:151]
	v_cvt_pk_bf16_f32 v110, v110, v111
	v_cvt_pk_bf16_f32 v111, v112, v113
	v_mov_b32_e32 v152, v110
	v_mov_b32_e32 v153, v111
	v_lshl_add_u64 v[162:163], v[138:139], 0, v[166:167]
	v_cvt_pk_bf16_f32 v106, v106, v107
	v_cvt_pk_bf16_f32 v107, v108, v109
	v_mov_b32_e32 v156, v106
	v_mov_b32_e32 v157, v107
	v_lshl_add_u64 v[164:165], v[128:129], 0, v[166:167]
	v_cvt_pk_bf16_f32 v102, v102, v103
	v_cvt_pk_bf16_f32 v103, v104, v105
	v_mov_b32_e32 v154, v102
	v_mov_b32_e32 v155, v103
	s_nop 1
	v_permlane16_swap_b32_e32 v152, v154
	v_permlane16_swap_b32_e32 v153, v155
	flat_store_dwordx4 v[162:163], v[152:155] offset:64
	v_cvt_pk_bf16_f32 v98, v98, v99
	v_cvt_pk_bf16_f32 v99, v100, v101
	v_mov_b32_e32 v158, v98
	v_mov_b32_e32 v159, v99
	s_nop 1
	v_permlane16_swap_b32_e32 v156, v158
	v_permlane16_swap_b32_e32 v157, v159
	flat_store_dwordx4 v[164:165], v[156:159] offset:64
	v_or_b32_e32 v98, 0x80, v132
	v_ashrrev_i32_e32 v99, 31, v98
	v_lshlrev_b64 v[98:99], 12, v[98:99]
	v_lshl_add_u64 v[100:101], v[134:135], 0, v[98:99]
	v_cvt_pk_bf16_f32 v94, v94, v95
	v_cvt_pk_bf16_f32 v95, v96, v97
	v_mov_b32_e32 v140, v94
	v_mov_b32_e32 v141, v95
	v_lshl_add_u64 v[144:145], v[100:101], 0, v[166:167]
	v_or_b32_e32 v94, 0x90, v132
	v_ashrrev_i32_e32 v95, 31, v94
	v_lshlrev_b64 v[94:95], 12, v[94:95]
	v_lshl_add_u64 v[96:97], v[134:135], 0, v[94:95]
	v_cvt_pk_bf16_f32 v90, v90, v91
	v_cvt_pk_bf16_f32 v91, v92, v93
	v_mov_b32_e32 v148, v90
	v_mov_b32_e32 v149, v91
	v_lshl_add_u64 v[160:161], v[96:97], 0, v[166:167]
	v_cvt_pk_bf16_f32 v86, v86, v87
	v_cvt_pk_bf16_f32 v87, v88, v89
	v_mov_b32_e32 v142, v86
	v_mov_b32_e32 v143, v87
	s_nop 1
	v_permlane16_swap_b32_e32 v140, v142
	v_permlane16_swap_b32_e32 v141, v143
	flat_store_dwordx4 v[144:145], v[140:143]
	v_cvt_pk_bf16_f32 v82, v82, v83
	v_cvt_pk_bf16_f32 v83, v84, v85
	v_mov_b32_e32 v150, v82
	v_mov_b32_e32 v151, v83
	s_nop 1
	v_permlane16_swap_b32_e32 v148, v150
	v_permlane16_swap_b32_e32 v149, v151
	flat_store_dwordx4 v[160:161], v[148:151]
	v_cvt_pk_bf16_f32 v78, v78, v79
	v_cvt_pk_bf16_f32 v79, v80, v81
	v_mov_b32_e32 v152, v78
	v_mov_b32_e32 v153, v79
	v_lshl_add_u64 v[162:163], v[100:101], 0, v[166:167]
	v_cvt_pk_bf16_f32 v74, v74, v75
	v_cvt_pk_bf16_f32 v75, v76, v77
	v_mov_b32_e32 v156, v74
	v_mov_b32_e32 v157, v75
	v_lshl_add_u64 v[164:165], v[96:97], 0, v[166:167]
	v_cvt_pk_bf16_f32 v70, v70, v71
	v_cvt_pk_bf16_f32 v71, v72, v73
	v_mov_b32_e32 v154, v70
	v_mov_b32_e32 v155, v71
	s_nop 1
	v_permlane16_swap_b32_e32 v152, v154
	v_permlane16_swap_b32_e32 v153, v155
	flat_store_dwordx4 v[162:163], v[152:155] offset:64
	v_cvt_pk_bf16_f32 v66, v66, v67
	v_cvt_pk_bf16_f32 v67, v68, v69
	v_mov_b32_e32 v158, v66
	v_mov_b32_e32 v159, v67
	s_nop 1
	v_permlane16_swap_b32_e32 v156, v158
	v_permlane16_swap_b32_e32 v157, v159
	flat_store_dwordx4 v[164:165], v[156:159] offset:64
; #define EPI_LOOP(...) _Pragma("unroll") for(int ai=0;ai<2;++ai) _Pragma("unroll") for(int bj=0;bj<2;++bj) \
;   _Pragma("unroll") for(int m=0;m<4;++m) _Pragma("unroll") for(int n=0;n<2;++n) { \
;     const int row=brow+ai*128+wr*64+m*16+fq*4; const int col=bcol+bj*128+wc*32+n*16+fr; \
;     f32x4& v=acc[ai][bj][m][n]; __VA_ARGS__ if (n == 1 && (m & 1)) __builtin_amdgcn_sched_barrier(0); }
; DEVI void run_phase(const int ph, const Params& P, char* shmc, const int wave_u) {
;     ...
;       gemm_core(w_out_t + (long)brow * 2048, 2048, merged + (long)bcol * 2048, 2048, 2048, acc, shm, wave_u);
;       GEMM_IDS
;       EPI_LOOP({ st_bf4(T + (long)col * 2048 + row, v[0], v[1], v[2], v[3]); })
	v_add_u32_e32 v66, 0x80, v130
	v_ashrrev_i32_e32 v67, 31, v66
	v_lshl_add_u64 v[66:67], v[66:67], 1, s[12:13]
	v_lshl_add_u64 v[68:69], v[66:67], 0, v[136:137]
	v_cvt_pk_bf16_f32 v62, v62, v63
	v_cvt_pk_bf16_f32 v63, v64, v65
	v_mov_b32_e32 v140, v62
	v_mov_b32_e32 v141, v63
	v_lshl_add_u64 v[144:145], v[68:69], 0, v[166:167]
	v_lshl_add_u64 v[62:63], v[66:67], 0, v[126:127]
	v_cvt_pk_bf16_f32 v58, v58, v59
	v_cvt_pk_bf16_f32 v59, v60, v61
	v_mov_b32_e32 v148, v58
	v_mov_b32_e32 v149, v59
	v_lshl_add_u64 v[160:161], v[62:63], 0, v[166:167]
	v_add_u32_e32 v58, 0x90, v130
	v_ashrrev_i32_e32 v59, 31, v58
	v_lshl_add_u64 v[58:59], v[58:59], 1, s[12:13]
	v_lshl_add_u64 v[60:61], v[58:59], 0, v[136:137]
	v_cvt_pk_bf16_f32 v54, v54, v55
	v_cvt_pk_bf16_f32 v55, v56, v57
	v_mov_b32_e32 v142, v54
	v_mov_b32_e32 v143, v55
	s_nop 1
	v_permlane16_swap_b32_e32 v140, v142
	v_permlane16_swap_b32_e32 v141, v143
	flat_store_dwordx4 v[144:145], v[140:143]
	v_lshl_add_u64 v[54:55], v[58:59], 0, v[126:127]
	v_cvt_pk_bf16_f32 v50, v50, v51
	v_cvt_pk_bf16_f32 v51, v52, v53
	v_mov_b32_e32 v150, v50
	v_mov_b32_e32 v151, v51
	s_nop 1
	v_permlane16_swap_b32_e32 v148, v150
	v_permlane16_swap_b32_e32 v149, v151
	flat_store_dwordx4 v[160:161], v[148:151]
	v_add_u32_e32 v50, 0xa0, v130
	v_ashrrev_i32_e32 v51, 31, v50
	v_lshl_add_u64 v[50:51], v[50:51], 1, s[12:13]
	v_lshl_add_u64 v[52:53], v[50:51], 0, v[136:137]
	v_cvt_pk_bf16_f32 v46, v46, v47
	v_cvt_pk_bf16_f32 v47, v48, v49
	v_mov_b32_e32 v152, v46
	v_mov_b32_e32 v153, v47
	v_lshl_add_u64 v[162:163], v[52:53], 0, v[166:167]
	v_lshl_add_u64 v[46:47], v[50:51], 0, v[126:127]
	v_cvt_pk_bf16_f32 v42, v42, v43
	v_cvt_pk_bf16_f32 v43, v44, v45
	v_mov_b32_e32 v156, v42
	v_mov_b32_e32 v157, v43
	v_lshl_add_u64 v[164:165], v[46:47], 0, v[166:167]
	v_add_u32_e32 v42, 0xb0, v130
	v_ashrrev_i32_e32 v43, 31, v42
	v_lshl_add_u64 v[42:43], v[42:43], 1, s[12:13]
	v_lshl_add_u64 v[44:45], v[42:43], 0, v[136:137]
	v_cvt_pk_bf16_f32 v38, v38, v39
	v_cvt_pk_bf16_f32 v39, v40, v41
	v_mov_b32_e32 v154, v38
	v_mov_b32_e32 v155, v39
	s_nop 1
	v_permlane16_swap_b32_e32 v152, v154
	v_permlane16_swap_b32_e32 v153, v155
	flat_store_dwordx4 v[162:163], v[152:155]
	v_lshl_add_u64 v[38:39], v[42:43], 0, v[126:127]
	v_cvt_pk_bf16_f32 v34, v34, v35
	v_cvt_pk_bf16_f32 v35, v36, v37
	v_mov_b32_e32 v158, v34
	v_mov_b32_e32 v159, v35
	s_nop 1
	v_permlane16_swap_b32_e32 v156, v158
	v_permlane16_swap_b32_e32 v157, v159
	flat_store_dwordx4 v[164:165], v[156:159]
	v_lshl_add_u64 v[34:35], v[66:67], 0, v[98:99]
	v_cvt_pk_bf16_f32 v28, v28, v29
	v_cvt_pk_bf16_f32 v29, v30, v31
	v_mov_b32_e32 v140, v28
	v_mov_b32_e32 v141, v29
	v_lshl_add_u64 v[144:145], v[34:35], 0, v[166:167]
	v_lshl_add_u64 v[28:29], v[66:67], 0, v[94:95]
	v_cvt_pk_bf16_f32 v24, v24, v25
	v_cvt_pk_bf16_f32 v25, v26, v27
	v_mov_b32_e32 v148, v24
	v_mov_b32_e32 v149, v25
	v_lshl_add_u64 v[160:161], v[28:29], 0, v[166:167]
	v_lshl_add_u64 v[24:25], v[58:59], 0, v[98:99]
	v_cvt_pk_bf16_f32 v20, v20, v21
	v_cvt_pk_bf16_f32 v21, v22, v23
	v_mov_b32_e32 v142, v20
	v_mov_b32_e32 v143, v21
	s_nop 1
	v_permlane16_swap_b32_e32 v140, v142
	v_permlane16_swap_b32_e32 v141, v143
	flat_store_dwordx4 v[144:145], v[140:143]
	v_lshl_add_u64 v[20:21], v[58:59], 0, v[94:95]
	v_cvt_pk_bf16_f32 v16, v16, v17
	v_cvt_pk_bf16_f32 v17, v18, v19
	v_mov_b32_e32 v150, v16
	v_mov_b32_e32 v151, v17
	s_nop 1
	v_permlane16_swap_b32_e32 v148, v150
	v_permlane16_swap_b32_e32 v149, v151
	flat_store_dwordx4 v[160:161], v[148:151]
	v_lshl_add_u64 v[16:17], v[50:51], 0, v[98:99]
	v_cvt_pk_bf16_f32 v12, v12, v13
	v_cvt_pk_bf16_f32 v13, v14, v15
	v_mov_b32_e32 v152, v12
	v_mov_b32_e32 v153, v13
	v_lshl_add_u64 v[162:163], v[16:17], 0, v[166:167]
	v_lshl_add_u64 v[12:13], v[50:51], 0, v[94:95]
	v_cvt_pk_bf16_f32 v8, v8, v9
	v_cvt_pk_bf16_f32 v9, v10, v11
	v_mov_b32_e32 v156, v8
	v_mov_b32_e32 v157, v9
	v_lshl_add_u64 v[164:165], v[12:13], 0, v[166:167]
	v_lshl_add_u64 v[8:9], v[42:43], 0, v[98:99]
	v_cvt_pk_bf16_f32 v4, v4, v5
	v_cvt_pk_bf16_f32 v5, v6, v7
	v_mov_b32_e32 v154, v4
	v_mov_b32_e32 v155, v5
	s_nop 1
	v_permlane16_swap_b32_e32 v152, v154
	v_permlane16_swap_b32_e32 v153, v155
	flat_store_dwordx4 v[162:163], v[152:155]
	v_lshl_add_u64 v[4:5], v[42:43], 0, v[94:95]
	v_cvt_pk_bf16_f32 v0, v0, v1
	v_cvt_pk_bf16_f32 v1, v2, v3
	v_mov_b32_e32 v158, v0
	v_mov_b32_e32 v159, v1
	s_nop 1
	v_permlane16_swap_b32_e32 v156, v158
	v_permlane16_swap_b32_e32 v157, v159
	flat_store_dwordx4 v[164:165], v[156:159]
	v_readlane_b32 s4, v254, 26
	s_add_i32 s75, s75, s4
	s_cmpk_gt_i32 s75, 0x1ff
	v_readlane_b32 s5, v254, 27
	s_cbranch_scc1 .LBB0_89

; #define EPI_LOOP(...) _Pragma("unroll") for(int ai=0;ai<2;++ai) _Pragma("unroll") for(int bj=0;bj<2;++bj) \
;   _Pragma("unroll") for(int m=0;m<4;++m) _Pragma("unroll") for(int n=0;n<2;++n) { \
;     const int row=brow+ai*128+wr*64+m*16+fq*4; const int col=bcol+bj*128+wc*32+n*16+fr; \
;     f32x4& v=acc[ai][bj][m][n]; __VA_ARGS__ if (n == 1 && (m & 1)) __builtin_amdgcn_sched_barrier(0); }
; #define EPI_SC4(ARR) float sc4[2][2]; _Pragma("unroll") for(int bj=0;bj<2;++bj) _Pragma("unroll") for(int n=0;n<2;++n) sc4[bj][n]=(ARR)[RSI(bcol+bj*128+wc*32+n*16+fr)];
; DEVI void run_phase(const int ph, const Params& P, char* shmc, const int wave_u) {
;     ...
;       EPI_SC4(rs1)
;       EPI_LOOP({ const float sc = sc4[bj][n]; float a = fmaxf(v[0] * sc, 0.f), b = fmaxf(v[1] * sc, 0.f), c = fmaxf(v[2] * sc, 0.f), d = fmaxf(v[3] * sc, 0.f);
;         st_bf4(hid + (long)col * DFF + row, a * a, b * b, c * c, d * d); })
.LBB0_114:
	s_or_b64 exec, exec, s[6:7]
	v_mbcnt_lo_u32_b32 v170, -1, 0
	v_mbcnt_hi_u32_b32 v170, -1, v170
	v_bfe_u32 v170, v170, 4, 1
	v_mul_u32_u24_e32 v170, 24, v170
	v_mov_b32_e32 v171, 0
	v_mbcnt_lo_u32_b32 v133, -1, 0
	v_mbcnt_hi_u32_b32 v133, -1, v133
	s_movk_i32 s4, 0xfda0
	v_or_b32_e32 v134, s5, v133
	v_lshrrev_b32_e32 v130, 1, v134
	v_and_b32_e32 v32, 15, v133
	v_and_b32_e32 v130, 0x60, v130
	v_or3_b32 v132, v32, v130, s68
	v_and_b32_e32 v32, 7, v133
	v_lshlrev_b32_e32 v130, 2, v132
	v_and_or_b32 v130, v130, s4, v32
	v_readlane_b32 s6, v255, 25
	v_ashrrev_i32_e32 v131, 31, v130
	v_readlane_b32 s7, v255, 26
	s_nop 1
	v_lshl_add_u64 v[130:131], v[130:131], 2, s[6:7]
	flat_load_dword v138, v[130:131]
	flat_load_dword v137, v[130:131] offset:256
	flat_load_dword v136, v[130:131] offset:2048
	flat_load_dword v32, v[130:131] offset:2304
	v_ashrrev_i32_e32 v130, 2, v134
	v_lshrrev_b32_e32 v131, 2, v133
	v_and_b32_e32 v130, 0xffffffc0, v130
	v_and_or_b32 v131, v131, 12, s38
	v_add_u32_e32 v130, v131, v130
	v_ashrrev_i32_e32 v131, 31, v130
	v_lshl_add_u64 v[134:135], v[130:131], 1, s[82:83]
	v_ashrrev_i32_e32 v133, 31, v132
	s_waitcnt vmcnt(0) lgkmcnt(0)
	v_mul_f32_e32 v126, v126, v138
	v_max_f32_e32 v131, 0, v126
	v_mul_f32_e32 v126, v127, v138
	v_max_f32_e32 v139, 0, v126
	v_mul_f32_e32 v126, v128, v138
	v_max_f32_e32 v140, 0, v126
	v_mul_f32_e32 v126, v129, v138
	v_max_f32_e32 v141, 0, v126
	v_lshlrev_b64 v[126:127], 14, v[132:133]
	v_mul_f32_e32 v131, v131, v131
	v_mul_f32_e32 v122, v122, v137
	v_lshl_add_u64 v[128:129], v[134:135], 0, v[126:127]
	v_mul_f32_e32 v133, v139, v139
	v_mul_f32_e32 v139, v140, v140
	v_mul_f32_e32 v141, v141, v141
	v_cvt_pk_bf16_f32 v140, v131, v133
	v_max_f32_e32 v131, 0, v122
	v_mul_f32_e32 v122, v123, v137
	v_cvt_pk_bf16_f32 v141, v139, v141
	v_mov_b32_e32 v148, v140
	v_mov_b32_e32 v149, v141
	v_lshl_add_u64 v[144:145], v[128:129], 0, v[170:171]
	v_or_b32_e32 v140, 16, v132
	v_max_f32_e32 v133, 0, v122
	v_mul_f32_e32 v122, v124, v137
	v_max_f32_e32 v139, 0, v122
	v_mul_f32_e32 v122, v125, v137
	v_ashrrev_i32_e32 v141, 31, v140
	v_mul_f32_e32 v118, v118, v138
	v_mul_f32_e32 v119, v119, v138
	v_mul_f32_e32 v114, v114, v137
	v_mul_f32_e32 v115, v115, v137
	v_max_f32_e32 v142, 0, v122
	v_lshlrev_b64 v[122:123], 14, v[140:141]
	v_max_f32_e32 v118, 0, v118
	v_max_f32_e32 v119, 0, v119
	v_mul_f32_e32 v120, v120, v138
	v_mul_f32_e32 v121, v121, v138
	v_max_f32_e32 v114, 0, v114
	v_max_f32_e32 v115, 0, v115
	v_mul_f32_e32 v116, v116, v137
	v_mul_f32_e32 v117, v117, v137
	v_lshl_add_u64 v[124:125], v[134:135], 0, v[122:123]
	v_mul_f32_e32 v141, v142, v142
	v_max_f32_e32 v120, 0, v120
	v_max_f32_e32 v121, 0, v121
	v_mul_f32_e32 v118, v118, v118
	v_mul_f32_e32 v119, v119, v119
	v_max_f32_e32 v116, 0, v116
	v_max_f32_e32 v117, 0, v117
	v_mul_f32_e32 v114, v114, v114
	v_mul_f32_e32 v115, v115, v115
	v_mul_f32_e32 v131, v131, v131
	v_mul_f32_e32 v133, v133, v133
	v_mul_f32_e32 v139, v139, v139
	v_cvt_pk_bf16_f32 v140, v131, v133
	v_cvt_pk_bf16_f32 v141, v139, v141
	v_mov_b32_e32 v152, v140
	v_mov_b32_e32 v153, v141
	v_lshl_add_u64 v[164:165], v[124:125], 0, v[170:171]
	v_mul_f32_e32 v120, v120, v120
	v_mul_f32_e32 v121, v121, v121
	v_cvt_pk_bf16_f32 v118, v118, v119
	v_cvt_pk_bf16_f32 v119, v120, v121
	v_mov_b32_e32 v150, v118
	v_mov_b32_e32 v151, v119
	s_nop 1
	v_permlane16_swap_b32_e32 v148, v150
	v_permlane16_swap_b32_e32 v149, v151
	flat_store_dwordx4 v[144:145], v[148:151]
	v_mul_f32_e32 v116, v116, v116
	v_mul_f32_e32 v117, v117, v117
	v_cvt_pk_bf16_f32 v114, v114, v115
	v_cvt_pk_bf16_f32 v115, v116, v117
	v_mov_b32_e32 v154, v114
	v_mov_b32_e32 v155, v115
	s_nop 1
	v_permlane16_swap_b32_e32 v152, v154
	v_permlane16_swap_b32_e32 v153, v155
	flat_store_dwordx4 v[164:165], v[152:155]
	v_mul_f32_e32 v110, v110, v138
	v_mul_f32_e32 v111, v111, v138
	v_mul_f32_e32 v106, v106, v137
	v_mul_f32_e32 v107, v107, v137
	v_mul_f32_e32 v102, v102, v138
	v_mul_f32_e32 v103, v103, v138
	v_mul_f32_e32 v98, v98, v137
	v_mul_f32_e32 v99, v99, v137
	v_max_f32_e32 v110, 0, v110
	v_max_f32_e32 v111, 0, v111
	v_mul_f32_e32 v112, v112, v138
	v_mul_f32_e32 v113, v113, v138
	v_max_f32_e32 v106, 0, v106
	v_max_f32_e32 v107, 0, v107
	v_mul_f32_e32 v108, v108, v137
	v_mul_f32_e32 v109, v109, v137
	v_max_f32_e32 v102, 0, v102
	v_max_f32_e32 v103, 0, v103
	v_mul_f32_e32 v104, v104, v138
	v_mul_f32_e32 v105, v105, v138
	v_max_f32_e32 v98, 0, v98
	v_max_f32_e32 v99, 0, v99
	v_mul_f32_e32 v100, v100, v137
	v_mul_f32_e32 v101, v101, v137
	v_max_f32_e32 v112, 0, v112
	v_max_f32_e32 v113, 0, v113
	v_mul_f32_e32 v110, v110, v110
	v_mul_f32_e32 v111, v111, v111
	v_max_f32_e32 v108, 0, v108
	v_max_f32_e32 v109, 0, v109
	v_mul_f32_e32 v106, v106, v106
	v_mul_f32_e32 v107, v107, v107
	v_max_f32_e32 v104, 0, v104
	v_max_f32_e32 v105, 0, v105
	v_mul_f32_e32 v102, v102, v102
	v_mul_f32_e32 v103, v103, v103
	v_max_f32_e32 v100, 0, v100
	v_max_f32_e32 v101, 0, v101
	v_mul_f32_e32 v98, v98, v98
	v_mul_f32_e32 v99, v99, v99
	v_mul_f32_e32 v112, v112, v112
	v_mul_f32_e32 v113, v113, v113
	v_cvt_pk_bf16_f32 v110, v110, v111
	v_cvt_pk_bf16_f32 v111, v112, v113
	v_mov_b32_e32 v156, v110
	v_mov_b32_e32 v157, v111
	v_lshl_add_u64 v[166:167], v[128:129], 0, v[170:171]
	v_mul_f32_e32 v108, v108, v108
	v_mul_f32_e32 v109, v109, v109
	v_cvt_pk_bf16_f32 v106, v106, v107
	v_cvt_pk_bf16_f32 v107, v108, v109
	v_mov_b32_e32 v160, v106
	v_mov_b32_e32 v161, v107
	v_lshl_add_u64 v[168:169], v[124:125], 0, v[170:171]
	v_mul_f32_e32 v104, v104, v104
	v_mul_f32_e32 v105, v105, v105
	v_cvt_pk_bf16_f32 v102, v102, v103
	v_cvt_pk_bf16_f32 v103, v104, v105
	v_mov_b32_e32 v158, v102
; #define EPI_LOOP(...) _Pragma("unroll") for(int ai=0;ai<2;++ai) _Pragma("unroll") for(int bj=0;bj<2;++bj) \
;   _Pragma("unroll") for(int m=0;m<4;++m) _Pragma("unroll") for(int n=0;n<2;++n) { \
;     const int row=brow+ai*128+wr*64+m*16+fq*4; const int col=bcol+bj*128+wc*32+n*16+fr; \
;     f32x4& v=acc[ai][bj][m][n]; __VA_ARGS__ if (n == 1 && (m & 1)) __builtin_amdgcn_sched_barrier(0); }
; #define EPI_SC4(ARR) float sc4[2][2]; _Pragma("unroll") for(int bj=0;bj<2;++bj) _Pragma("unroll") for(int n=0;n<2;++n) sc4[bj][n]=(ARR)[RSI(bcol+bj*128+wc*32+n*16+fr)];
; DEVI void run_phase(const int ph, const Params& P, char* shmc, const int wave_u) {
;     ...
;       EPI_SC4(rs1)
;       EPI_LOOP({ const float sc = sc4[bj][n]; float a = fmaxf(v[0] * sc, 0.f), b = fmaxf(v[1] * sc, 0.f), c = fmaxf(v[2] * sc, 0.f), d = fmaxf(v[3] * sc, 0.f);
;         st_bf4(hid + (long)col * DFF + row, a * a, b * b, c * c, d * d); })
	v_mov_b32_e32 v159, v103
	s_nop 1
	v_permlane16_swap_b32_e32 v156, v158
	v_permlane16_swap_b32_e32 v157, v159
	flat_store_dwordx4 v[166:167], v[156:159] offset:64
	v_mul_f32_e32 v100, v100, v100
	v_mul_f32_e32 v101, v101, v101
	v_cvt_pk_bf16_f32 v98, v98, v99
	v_cvt_pk_bf16_f32 v99, v100, v101
	v_mov_b32_e32 v162, v98
	v_mov_b32_e32 v163, v99
	s_nop 1
	v_permlane16_swap_b32_e32 v160, v162
	v_permlane16_swap_b32_e32 v161, v163
	flat_store_dwordx4 v[168:169], v[160:163] offset:64
	v_mul_f32_e32 v94, v94, v136
	v_max_f32_e32 v100, 0, v94
	v_mul_f32_e32 v94, v95, v136
	v_or_b32_e32 v98, 0x80, v132
	v_max_f32_e32 v101, 0, v94
	v_mul_f32_e32 v94, v96, v136
	v_max_f32_e32 v102, 0, v94
	v_mul_f32_e32 v94, v97, v136
	v_ashrrev_i32_e32 v99, 31, v98
	v_max_f32_e32 v103, 0, v94
	v_lshlrev_b64 v[94:95], 14, v[98:99]
	v_mul_f32_e32 v98, v100, v100
	v_mul_f32_e32 v99, v101, v101
	v_mul_f32_e32 v100, v102, v102
	v_mul_f32_e32 v90, v90, v32
	v_lshl_add_u64 v[96:97], v[134:135], 0, v[94:95]
	v_mul_f32_e32 v101, v103, v103
	v_cvt_pk_bf16_f32 v98, v98, v99
	v_cvt_pk_bf16_f32 v99, v100, v101
	v_max_f32_e32 v100, 0, v90
	v_mul_f32_e32 v90, v91, v32
	v_mov_b32_e32 v148, v98
	v_mov_b32_e32 v149, v99
	v_lshl_add_u64 v[144:145], v[96:97], 0, v[170:171]
	v_or_b32_e32 v98, 0x90, v132
	v_max_f32_e32 v101, 0, v90
	v_mul_f32_e32 v90, v92, v32
	v_max_f32_e32 v102, 0, v90
	v_mul_f32_e32 v90, v93, v32
	v_ashrrev_i32_e32 v99, 31, v98
	v_mul_f32_e32 v86, v86, v136
	v_mul_f32_e32 v87, v87, v136
	v_mul_f32_e32 v82, v82, v32
	v_mul_f32_e32 v83, v83, v32
	v_max_f32_e32 v103, 0, v90
	v_lshlrev_b64 v[90:91], 14, v[98:99]
	v_max_f32_e32 v86, 0, v86
	v_max_f32_e32 v87, 0, v87
	v_mul_f32_e32 v88, v88, v136
	v_mul_f32_e32 v89, v89, v136
	v_max_f32_e32 v82, 0, v82
	v_max_f32_e32 v83, 0, v83
	v_mul_f32_e32 v84, v84, v32
	v_mul_f32_e32 v85, v85, v32
	v_lshl_add_u64 v[92:93], v[134:135], 0, v[90:91]
	v_mul_f32_e32 v98, v100, v100
	v_mul_f32_e32 v99, v101, v101
	v_max_f32_e32 v88, 0, v88
	v_max_f32_e32 v89, 0, v89
	v_mul_f32_e32 v86, v86, v86
	v_mul_f32_e32 v87, v87, v87
	v_max_f32_e32 v84, 0, v84
	v_max_f32_e32 v85, 0, v85
	v_mul_f32_e32 v82, v82, v82
	v_mul_f32_e32 v83, v83, v83
	v_mul_f32_e32 v100, v102, v102
	v_mul_f32_e32 v101, v103, v103
	v_cvt_pk_bf16_f32 v98, v98, v99
	v_cvt_pk_bf16_f32 v99, v100, v101
	v_mov_b32_e32 v152, v98
	v_mov_b32_e32 v153, v99
	v_lshl_add_u64 v[164:165], v[92:93], 0, v[170:171]
	v_mul_f32_e32 v88, v88, v88
	v_mul_f32_e32 v89, v89, v89
	v_cvt_pk_bf16_f32 v86, v86, v87
	v_cvt_pk_bf16_f32 v87, v88, v89
	v_mov_b32_e32 v150, v86
	v_mov_b32_e32 v151, v87
	s_nop 1
	v_permlane16_swap_b32_e32 v148, v150
	v_permlane16_swap_b32_e32 v149, v151
	flat_store_dwordx4 v[144:145], v[148:151]
	v_mul_f32_e32 v84, v84, v84
	v_mul_f32_e32 v85, v85, v85
	v_cvt_pk_bf16_f32 v82, v82, v83
	v_cvt_pk_bf16_f32 v83, v84, v85
	v_mov_b32_e32 v154, v82
	v_mov_b32_e32 v155, v83
	s_nop 1
	v_permlane16_swap_b32_e32 v152, v154
	v_permlane16_swap_b32_e32 v153, v155
	flat_store_dwordx4 v[164:165], v[152:155]
	v_mul_f32_e32 v78, v78, v136
	v_mul_f32_e32 v79, v79, v136
	v_mul_f32_e32 v74, v74, v32
	v_mul_f32_e32 v75, v75, v32
	v_mul_f32_e32 v70, v70, v136
	v_mul_f32_e32 v71, v71, v136
	v_mul_f32_e32 v66, v66, v32
	v_mul_f32_e32 v67, v67, v32
	v_max_f32_e32 v78, 0, v78
	v_max_f32_e32 v79, 0, v79
	v_mul_f32_e32 v80, v80, v136
	v_mul_f32_e32 v81, v81, v136
	v_max_f32_e32 v74, 0, v74
	v_max_f32_e32 v75, 0, v75
	v_mul_f32_e32 v76, v76, v32
	v_mul_f32_e32 v77, v77, v32
	v_max_f32_e32 v70, 0, v70
	v_max_f32_e32 v71, 0, v71
	v_mul_f32_e32 v72, v72, v136
	v_mul_f32_e32 v73, v73, v136
	v_max_f32_e32 v66, 0, v66
	v_max_f32_e32 v67, 0, v67
	v_mul_f32_e32 v68, v68, v32
	v_mul_f32_e32 v69, v69, v32
	v_max_f32_e32 v80, 0, v80
	v_max_f32_e32 v81, 0, v81
	v_mul_f32_e32 v78, v78, v78
	v_mul_f32_e32 v79, v79, v79
	v_max_f32_e32 v76, 0, v76
	v_max_f32_e32 v77, 0, v77
	v_mul_f32_e32 v74, v74, v74
	v_mul_f32_e32 v75, v75, v75
	v_max_f32_e32 v72, 0, v72
	v_max_f32_e32 v73, 0, v73
	v_mul_f32_e32 v70, v70, v70
	v_mul_f32_e32 v71, v71, v71
	v_max_f32_e32 v68, 0, v68
	v_max_f32_e32 v69, 0, v69
	v_mul_f32_e32 v66, v66, v66
	v_mul_f32_e32 v67, v67, v67
	v_mul_f32_e32 v80, v80, v80
	v_mul_f32_e32 v81, v81, v81
	v_cvt_pk_bf16_f32 v78, v78, v79
	v_cvt_pk_bf16_f32 v79, v80, v81
	v_mov_b32_e32 v156, v78
	v_mov_b32_e32 v157, v79
	v_lshl_add_u64 v[166:167], v[96:97], 0, v[170:171]
	v_mul_f32_e32 v76, v76, v76
	v_mul_f32_e32 v77, v77, v77
	v_cvt_pk_bf16_f32 v74, v74, v75
	v_cvt_pk_bf16_f32 v75, v76, v77
	v_mov_b32_e32 v160, v74
	v_mov_b32_e32 v161, v75
	v_lshl_add_u64 v[168:169], v[92:93], 0, v[170:171]
	v_mul_f32_e32 v72, v72, v72
	v_mul_f32_e32 v73, v73, v73
	v_cvt_pk_bf16_f32 v70, v70, v71
	v_cvt_pk_bf16_f32 v71, v72, v73
	v_mov_b32_e32 v158, v70
	v_mov_b32_e32 v159, v71
	s_nop 1
	v_permlane16_swap_b32_e32 v156, v158
	v_permlane16_swap_b32_e32 v157, v159
	flat_store_dwordx4 v[166:167], v[156:159] offset:64
	v_mul_f32_e32 v68, v68, v68
	v_mul_f32_e32 v69, v69, v69
	v_cvt_pk_bf16_f32 v66, v66, v67
	v_cvt_pk_bf16_f32 v67, v68, v69
	v_mov_b32_e32 v162, v66
	v_mov_b32_e32 v163, v67
	s_nop 1
	v_permlane16_swap_b32_e32 v160, v162
	v_permlane16_swap_b32_e32 v161, v163
	flat_store_dwordx4 v[168:169], v[160:163] offset:64
	v_mul_f32_e32 v62, v62, v138
	v_max_f32_e32 v68, 0, v62
	v_mul_f32_e32 v62, v63, v138
	v_add_u32_e32 v66, 0x80, v130
	v_max_f32_e32 v69, 0, v62
	v_mul_f32_e32 v62, v64, v138
	v_ashrrev_i32_e32 v67, 31, v66
	v_max_f32_e32 v64, 0, v62
	v_mul_f32_e32 v62, v65, v138
	v_lshl_add_u64 v[66:67], v[66:67], 1, s[82:83]
	v_max_f32_e32 v65, 0, v62
	v_lshl_add_u64 v[62:63], v[66:67], 0, v[126:127]
	v_mul_f32_e32 v65, v65, v65
; #define EPI_LOOP(...) _Pragma("unroll") for(int ai=0;ai<2;++ai) _Pragma("unroll") for(int bj=0;bj<2;++bj) \
;   _Pragma("unroll") for(int m=0;m<4;++m) _Pragma("unroll") for(int n=0;n<2;++n) { \
;     const int row=brow+ai*128+wr*64+m*16+fq*4; const int col=bcol+bj*128+wc*32+n*16+fr; \
;     f32x4& v=acc[ai][bj][m][n]; __VA_ARGS__ if (n == 1 && (m & 1)) __builtin_amdgcn_sched_barrier(0); }
; #define EPI_SC4(ARR) float sc4[2][2]; _Pragma("unroll") for(int bj=0;bj<2;++bj) _Pragma("unroll") for(int n=0;n<2;++n) sc4[bj][n]=(ARR)[RSI(bcol+bj*128+wc*32+n*16+fr)];
; DEVI void run_phase(const int ph, const Params& P, char* shmc, const int wave_u) {
;     ...
;       EPI_SC4(rs1)
;       EPI_LOOP({ const float sc = sc4[bj][n]; float a = fmaxf(v[0] * sc, 0.f), b = fmaxf(v[1] * sc, 0.f), c = fmaxf(v[2] * sc, 0.f), d = fmaxf(v[3] * sc, 0.f);
;         st_bf4(hid + (long)col * DFF + row, a * a, b * b, c * c, d * d); })
	v_mul_f32_e32 v58, v58, v137
	v_mul_f32_e32 v68, v68, v68
	v_mul_f32_e32 v69, v69, v69
	v_mul_f32_e32 v70, v64, v64
	v_cvt_pk_bf16_f32 v64, v68, v69
	v_cvt_pk_bf16_f32 v65, v70, v65
	v_mov_b32_e32 v148, v64
	v_mov_b32_e32 v149, v65
	v_lshl_add_u64 v[144:145], v[62:63], 0, v[170:171]
	v_max_f32_e32 v62, 0, v58
	v_mul_f32_e32 v58, v59, v137
	v_max_f32_e32 v63, 0, v58
	v_mul_f32_e32 v58, v60, v137
	v_max_f32_e32 v60, 0, v58
	v_mul_f32_e32 v58, v61, v137
	v_max_f32_e32 v61, 0, v58
	v_lshl_add_u64 v[58:59], v[66:67], 0, v[122:123]
	v_mul_f32_e32 v62, v62, v62
	v_mul_f32_e32 v63, v63, v63
	v_mul_f32_e32 v64, v60, v60
	v_mul_f32_e32 v61, v61, v61
	v_cvt_pk_bf16_f32 v60, v62, v63
	v_mul_f32_e32 v54, v54, v138
	v_cvt_pk_bf16_f32 v61, v64, v61
	v_mov_b32_e32 v152, v60
	v_mov_b32_e32 v153, v61
	v_lshl_add_u64 v[164:165], v[58:59], 0, v[170:171]
	v_max_f32_e32 v60, 0, v54
	v_mul_f32_e32 v54, v55, v138
	v_add_u32_e32 v58, 0x90, v130
	v_max_f32_e32 v61, 0, v54
	v_mul_f32_e32 v54, v56, v138
	v_ashrrev_i32_e32 v59, 31, v58
	v_max_f32_e32 v56, 0, v54
	v_mul_f32_e32 v54, v57, v138
	v_lshl_add_u64 v[58:59], v[58:59], 1, s[82:83]
	v_max_f32_e32 v57, 0, v54
	v_lshl_add_u64 v[54:55], v[58:59], 0, v[126:127]
	v_mul_f32_e32 v57, v57, v57
	v_mul_f32_e32 v50, v50, v137
	v_mul_f32_e32 v60, v60, v60
	v_mul_f32_e32 v61, v61, v61
	v_mul_f32_e32 v62, v56, v56
	v_cvt_pk_bf16_f32 v56, v60, v61
	v_cvt_pk_bf16_f32 v57, v62, v57
	v_mov_b32_e32 v150, v56
	v_mov_b32_e32 v151, v57
	s_nop 1
	v_permlane16_swap_b32_e32 v148, v150
	v_permlane16_swap_b32_e32 v149, v151
	flat_store_dwordx4 v[144:145], v[148:151]
	v_max_f32_e32 v54, 0, v50
	v_mul_f32_e32 v50, v51, v137
	v_max_f32_e32 v55, 0, v50
	v_mul_f32_e32 v50, v52, v137
	v_max_f32_e32 v52, 0, v50
	v_mul_f32_e32 v50, v53, v137
	v_max_f32_e32 v53, 0, v50
	v_lshl_add_u64 v[50:51], v[58:59], 0, v[122:123]
	v_mul_f32_e32 v53, v53, v53
	v_mul_f32_e32 v54, v54, v54
	v_mul_f32_e32 v55, v55, v55
	v_mul_f32_e32 v56, v52, v52
	v_cvt_pk_bf16_f32 v52, v54, v55
	v_cvt_pk_bf16_f32 v53, v56, v53
	v_mov_b32_e32 v154, v52
	v_mov_b32_e32 v155, v53
	s_nop 1
	v_permlane16_swap_b32_e32 v152, v154
	v_permlane16_swap_b32_e32 v153, v155
	flat_store_dwordx4 v[164:165], v[152:155]
	v_mul_f32_e32 v46, v46, v138
	v_max_f32_e32 v52, 0, v46
	v_mul_f32_e32 v46, v47, v138
	v_add_u32_e32 v50, 0xa0, v130
	v_max_f32_e32 v53, 0, v46
	v_mul_f32_e32 v46, v48, v138
	v_ashrrev_i32_e32 v51, 31, v50
	v_max_f32_e32 v48, 0, v46
	v_mul_f32_e32 v46, v49, v138
	v_lshl_add_u64 v[50:51], v[50:51], 1, s[82:83]
	v_max_f32_e32 v49, 0, v46
	v_lshl_add_u64 v[46:47], v[50:51], 0, v[126:127]
	v_mul_f32_e32 v49, v49, v49
	v_mul_f32_e32 v42, v42, v137
	v_mul_f32_e32 v52, v52, v52
	v_mul_f32_e32 v53, v53, v53
	v_mul_f32_e32 v54, v48, v48
	v_cvt_pk_bf16_f32 v48, v52, v53
	v_cvt_pk_bf16_f32 v49, v54, v49
	v_mov_b32_e32 v156, v48
	v_mov_b32_e32 v157, v49
	v_lshl_add_u64 v[166:167], v[46:47], 0, v[170:171]
	v_max_f32_e32 v46, 0, v42
	v_mul_f32_e32 v42, v43, v137
	v_max_f32_e32 v47, 0, v42
	v_mul_f32_e32 v42, v44, v137
	v_max_f32_e32 v44, 0, v42
	v_mul_f32_e32 v42, v45, v137
	v_max_f32_e32 v45, 0, v42
	v_lshl_add_u64 v[42:43], v[50:51], 0, v[122:123]
	v_mul_f32_e32 v46, v46, v46
	v_mul_f32_e32 v47, v47, v47
	v_mul_f32_e32 v48, v44, v44
	v_mul_f32_e32 v45, v45, v45
	v_cvt_pk_bf16_f32 v44, v46, v47
	v_mul_f32_e32 v38, v38, v138
	v_cvt_pk_bf16_f32 v45, v48, v45
	v_mov_b32_e32 v160, v44
	v_mov_b32_e32 v161, v45
	v_lshl_add_u64 v[168:169], v[42:43], 0, v[170:171]
	v_max_f32_e32 v44, 0, v38
	v_mul_f32_e32 v38, v39, v138
	v_add_u32_e32 v42, 0xb0, v130
	v_max_f32_e32 v45, 0, v38
	v_mul_f32_e32 v38, v40, v138
	v_ashrrev_i32_e32 v43, 31, v42
	v_max_f32_e32 v40, 0, v38
	v_mul_f32_e32 v38, v41, v138
	v_lshl_add_u64 v[42:43], v[42:43], 1, s[82:83]
	v_max_f32_e32 v41, 0, v38
	v_lshl_add_u64 v[38:39], v[42:43], 0, v[126:127]
	v_mul_f32_e32 v41, v41, v41
	v_mul_f32_e32 v34, v34, v137
	v_mul_f32_e32 v44, v44, v44
	v_mul_f32_e32 v45, v45, v45
	v_mul_f32_e32 v46, v40, v40
	v_cvt_pk_bf16_f32 v40, v44, v45
	v_cvt_pk_bf16_f32 v41, v46, v41
	v_mov_b32_e32 v158, v40
	v_mov_b32_e32 v159, v41
	s_nop 1
	v_permlane16_swap_b32_e32 v156, v158
	v_permlane16_swap_b32_e32 v157, v159
	flat_store_dwordx4 v[166:167], v[156:159]
	v_max_f32_e32 v38, 0, v34
	v_mul_f32_e32 v34, v35, v137
	v_max_f32_e32 v39, 0, v34
	v_mul_f32_e32 v34, v36, v137
	v_max_f32_e32 v36, 0, v34
	v_mul_f32_e32 v34, v37, v137
	v_max_f32_e32 v37, 0, v34
	v_lshl_add_u64 v[34:35], v[42:43], 0, v[122:123]
	v_mul_f32_e32 v37, v37, v37
	v_mul_f32_e32 v38, v38, v38
	v_mul_f32_e32 v39, v39, v39
	v_mul_f32_e32 v40, v36, v36
	v_cvt_pk_bf16_f32 v36, v38, v39
	v_cvt_pk_bf16_f32 v37, v40, v37
	v_mov_b32_e32 v162, v36
	v_mov_b32_e32 v163, v37
	s_nop 1
	v_permlane16_swap_b32_e32 v160, v162
	v_permlane16_swap_b32_e32 v161, v163
	flat_store_dwordx4 v[168:169], v[160:163]
; #define EPI_LOOP(...) _Pragma("unroll") for(int ai=0;ai<2;++ai) _Pragma("unroll") for(int bj=0;bj<2;++bj) \
;   _Pragma("unroll") for(int m=0;m<4;++m) _Pragma("unroll") for(int n=0;n<2;++n) { \
;     const int row=brow+ai*128+wr*64+m*16+fq*4; const int col=bcol+bj*128+wc*32+n*16+fr; \
;     f32x4& v=acc[ai][bj][m][n]; __VA_ARGS__ if (n == 1 && (m & 1)) __builtin_amdgcn_sched_barrier(0); }
; #define EPI_SC4(ARR) float sc4[2][2]; _Pragma("unroll") for(int bj=0;bj<2;++bj) _Pragma("unroll") for(int n=0;n<2;++n) sc4[bj][n]=(ARR)[RSI(bcol+bj*128+wc*32+n*16+fr)];
; DEVI void run_phase(const int ph, const Params& P, char* shmc, const int wave_u) {
;     ...
;       EPI_SC4(rs1)
;       EPI_LOOP({ const float sc = sc4[bj][n]; float a = fmaxf(v[0] * sc, 0.f), b = fmaxf(v[1] * sc, 0.f), c = fmaxf(v[2] * sc, 0.f), d = fmaxf(v[3] * sc, 0.f);
;         st_bf4(hid + (long)col * DFF + row, a * a, b * b, c * c, d * d); })
;     }
	v_mul_f32_e32 v28, v28, v136
	v_max_f32_e32 v34, 0, v28
	v_mul_f32_e32 v28, v29, v136
	v_max_f32_e32 v35, 0, v28
	v_mul_f32_e32 v28, v30, v136
	v_max_f32_e32 v30, 0, v28
	v_mul_f32_e32 v28, v31, v136
	v_max_f32_e32 v31, 0, v28
	v_lshl_add_u64 v[28:29], v[66:67], 0, v[94:95]
	v_mul_f32_e32 v31, v31, v31
	v_mul_f32_e32 v24, v24, v32
	v_mul_f32_e32 v34, v34, v34
	v_mul_f32_e32 v35, v35, v35
	v_mul_f32_e32 v36, v30, v30
	v_cvt_pk_bf16_f32 v30, v34, v35
	v_cvt_pk_bf16_f32 v31, v36, v31
	v_mov_b32_e32 v148, v30
	v_mov_b32_e32 v149, v31
	v_lshl_add_u64 v[144:145], v[28:29], 0, v[170:171]
	v_max_f32_e32 v28, 0, v24
	v_mul_f32_e32 v24, v25, v32
	v_max_f32_e32 v29, 0, v24
	v_mul_f32_e32 v24, v26, v32
	v_max_f32_e32 v26, 0, v24
	v_mul_f32_e32 v24, v27, v32
	v_max_f32_e32 v27, 0, v24
	v_lshl_add_u64 v[24:25], v[66:67], 0, v[90:91]
	v_mul_f32_e32 v27, v27, v27
	v_mul_f32_e32 v20, v20, v136
	v_mul_f32_e32 v28, v28, v28
	v_mul_f32_e32 v29, v29, v29
	v_mul_f32_e32 v30, v26, v26
	v_cvt_pk_bf16_f32 v26, v28, v29
	v_cvt_pk_bf16_f32 v27, v30, v27
	v_mov_b32_e32 v152, v26
	v_mov_b32_e32 v153, v27
	v_lshl_add_u64 v[164:165], v[24:25], 0, v[170:171]
	v_max_f32_e32 v24, 0, v20
	v_mul_f32_e32 v20, v21, v136
	v_max_f32_e32 v25, 0, v20
	v_mul_f32_e32 v20, v22, v136
	v_max_f32_e32 v22, 0, v20
	v_mul_f32_e32 v20, v23, v136
	v_max_f32_e32 v23, 0, v20
	v_lshl_add_u64 v[20:21], v[58:59], 0, v[94:95]
	v_mul_f32_e32 v23, v23, v23
	v_mul_f32_e32 v16, v16, v32
	v_mul_f32_e32 v24, v24, v24
	v_mul_f32_e32 v25, v25, v25
	v_mul_f32_e32 v26, v22, v22
	v_cvt_pk_bf16_f32 v22, v24, v25
	v_cvt_pk_bf16_f32 v23, v26, v23
	v_mov_b32_e32 v150, v22
	v_mov_b32_e32 v151, v23
	s_nop 1
	v_permlane16_swap_b32_e32 v148, v150
	v_permlane16_swap_b32_e32 v149, v151
	flat_store_dwordx4 v[144:145], v[148:151]
	v_max_f32_e32 v20, 0, v16
	v_mul_f32_e32 v16, v17, v32
	v_max_f32_e32 v21, 0, v16
	v_mul_f32_e32 v16, v18, v32
	v_max_f32_e32 v18, 0, v16
	v_mul_f32_e32 v16, v19, v32
	v_max_f32_e32 v19, 0, v16
	v_lshl_add_u64 v[16:17], v[58:59], 0, v[90:91]
	v_mul_f32_e32 v19, v19, v19
	v_mul_f32_e32 v20, v20, v20
	v_mul_f32_e32 v21, v21, v21
	v_mul_f32_e32 v22, v18, v18
	v_cvt_pk_bf16_f32 v18, v20, v21
	v_cvt_pk_bf16_f32 v19, v22, v19
	v_mov_b32_e32 v154, v18
	v_mov_b32_e32 v155, v19
	s_nop 1
	v_permlane16_swap_b32_e32 v152, v154
	v_permlane16_swap_b32_e32 v153, v155
	flat_store_dwordx4 v[164:165], v[152:155]
	v_mul_f32_e32 v12, v12, v136
	v_max_f32_e32 v16, 0, v12
	v_mul_f32_e32 v12, v13, v136
	v_max_f32_e32 v17, 0, v12
	v_mul_f32_e32 v12, v14, v136
	v_max_f32_e32 v14, 0, v12
	v_mul_f32_e32 v12, v15, v136
	v_max_f32_e32 v15, 0, v12
	v_lshl_add_u64 v[12:13], v[50:51], 0, v[94:95]
	v_mul_f32_e32 v15, v15, v15
	v_mul_f32_e32 v8, v8, v32
	v_mul_f32_e32 v16, v16, v16
	v_mul_f32_e32 v17, v17, v17
	v_mul_f32_e32 v18, v14, v14
	v_cvt_pk_bf16_f32 v14, v16, v17
	v_cvt_pk_bf16_f32 v15, v18, v15
	v_mov_b32_e32 v156, v14
	v_mov_b32_e32 v157, v15
	v_lshl_add_u64 v[166:167], v[12:13], 0, v[170:171]
	v_max_f32_e32 v12, 0, v8
	v_mul_f32_e32 v8, v9, v32
	v_max_f32_e32 v13, 0, v8
	v_mul_f32_e32 v8, v10, v32
	v_max_f32_e32 v10, 0, v8
	v_mul_f32_e32 v8, v11, v32
	v_max_f32_e32 v11, 0, v8
	v_lshl_add_u64 v[8:9], v[50:51], 0, v[90:91]
	v_mul_f32_e32 v11, v11, v11
	v_mul_f32_e32 v4, v4, v136
	v_mul_f32_e32 v12, v12, v12
	v_mul_f32_e32 v13, v13, v13
	v_mul_f32_e32 v14, v10, v10
	v_cvt_pk_bf16_f32 v10, v12, v13
	v_cvt_pk_bf16_f32 v11, v14, v11
	v_mov_b32_e32 v160, v10
	v_mov_b32_e32 v161, v11
	v_lshl_add_u64 v[168:169], v[8:9], 0, v[170:171]
	v_max_f32_e32 v8, 0, v4
	v_mul_f32_e32 v4, v5, v136
	v_max_f32_e32 v9, 0, v4
	v_mul_f32_e32 v4, v6, v136
	v_max_f32_e32 v6, 0, v4
	v_mul_f32_e32 v4, v7, v136
	v_max_f32_e32 v7, 0, v4
	v_lshl_add_u64 v[4:5], v[42:43], 0, v[94:95]
	v_mul_f32_e32 v7, v7, v7
	v_mul_f32_e32 v0, v0, v32
	v_mul_f32_e32 v8, v8, v8
	v_mul_f32_e32 v9, v9, v9
	v_mul_f32_e32 v10, v6, v6
	v_cvt_pk_bf16_f32 v6, v8, v9
	v_cvt_pk_bf16_f32 v7, v10, v7
	v_mov_b32_e32 v158, v6
	v_mov_b32_e32 v159, v7
	s_nop 1
	v_permlane16_swap_b32_e32 v156, v158
	v_permlane16_swap_b32_e32 v157, v159
	flat_store_dwordx4 v[166:167], v[156:159]
	v_max_f32_e32 v4, 0, v0
	v_mul_f32_e32 v0, v1, v32
	v_max_f32_e32 v5, 0, v0
	v_mul_f32_e32 v0, v2, v32
	v_max_f32_e32 v2, 0, v0
	v_mul_f32_e32 v0, v3, v32
	v_max_f32_e32 v3, 0, v0
	v_lshl_add_u64 v[0:1], v[42:43], 0, v[90:91]
	v_mul_f32_e32 v3, v3, v3
	v_mul_f32_e32 v4, v4, v4
	v_mul_f32_e32 v5, v5, v5
	v_mul_f32_e32 v6, v2, v2
	v_cvt_pk_bf16_f32 v2, v4, v5
	v_cvt_pk_bf16_f32 v3, v6, v3
	v_mov_b32_e32 v162, v2
	v_mov_b32_e32 v163, v3
	s_nop 1
	v_permlane16_swap_b32_e32 v160, v162
	v_permlane16_swap_b32_e32 v161, v163
	flat_store_dwordx4 v[168:169], v[160:163]
	s_mov_b32 s16, s5
	v_readlane_b32 s4, v254, 26
	s_add_i32 s75, s75, s4
	s_cmpk_gt_i32 s75, 0x83f
	v_readlane_b32 s5, v254, 27
	s_cbranch_scc1 .LBB0_93

; #define ACC_ZERO(acc) { float z_ = 0.f; asm volatile("" : "+v"(z_)); _Pragma("unroll") for(int ai=0;ai<2;++ai) _Pragma("unroll") for(int bj=0;bj<2;++bj) \
;   _Pragma("unroll") for(int m=0;m<4;++m) _Pragma("unroll") for(int n=0;n<2;++n) acc[ai][bj][m][n]=f32x4{z_,z_,z_,z_}; }
; #define EPI_LOOP(...) _Pragma("unroll") for(int ai=0;ai<2;++ai) _Pragma("unroll") for(int bj=0;bj<2;++bj) \
;   _Pragma("unroll") for(int m=0;m<4;++m) _Pragma("unroll") for(int n=0;n<2;++n) { \
;     const int row=brow+ai*128+wr*64+m*16+fq*4; const int col=bcol+bj*128+wc*32+n*16+fr; \
;     f32x4& v=acc[ai][bj][m][n]; __VA_ARGS__ if (n == 1 && (m & 1)) __builtin_amdgcn_sched_barrier(0); }
; DEVI void run_phase(const int ph, const Params& P, char* shmc, const int wave_u) {
;     ...
;       acc_t acc; ACC_ZERO(acc)
;       gemm_core(w_dn_t + (long)brow * DFF, DFF, hid + (long)bcol * DFF, DFF, DFF, acc, shm, wave_u);
;       GEMM_IDS
;       EPI_LOOP({ st_bf4(T + (long)col * 2048 + row, v[0], v[1], v[2], v[3]); })
.LBB0_174:
	s_or_b64 exec, exec, s[6:7]
	v_mbcnt_lo_u32_b32 v166, -1, 0
	v_mbcnt_hi_u32_b32 v166, -1, v166
	v_bfe_u32 v166, v166, 4, 1
	v_mul_u32_u24_e32 v166, 24, v166
	v_mov_b32_e32 v167, 0
	v_mbcnt_lo_u32_b32 v32, -1, 0
	v_mbcnt_hi_u32_b32 v32, -1, v32
	v_cvt_pk_bf16_f32 v126, v126, v127
	v_cvt_pk_bf16_f32 v127, v128, v129
	s_nop 0
	v_or_b32_e32 v131, s5, v32
	v_and_b32_e32 v132, 15, v32
	v_ashrrev_i32_e32 v130, 2, v131
	v_lshrrev_b32_e32 v32, 2, v32
	v_and_b32_e32 v130, 0xffffffc0, v130
	v_and_or_b32 v32, v32, 12, s0
	v_add_u32_e32 v130, v32, v130
	v_lshrrev_b32_e32 v32, 1, v131
	v_and_b32_e32 v32, 0x60, v32
	v_or3_b32 v132, v132, v32, s8
	v_ashrrev_i32_e32 v131, 31, v130
	v_ashrrev_i32_e32 v133, 31, v132
	v_lshl_add_u64 v[134:135], v[130:131], 1, s[12:13]
	v_lshlrev_b64 v[136:137], 12, v[132:133]
	v_lshl_add_u64 v[138:139], v[134:135], 0, v[136:137]
	v_mov_b32_e32 v140, v126
	v_mov_b32_e32 v141, v127
	v_lshl_add_u64 v[144:145], v[138:139], 0, v[166:167]
	v_or_b32_e32 v126, 16, v132
	v_ashrrev_i32_e32 v127, 31, v126
	v_lshlrev_b64 v[126:127], 12, v[126:127]
	v_lshl_add_u64 v[128:129], v[134:135], 0, v[126:127]
	v_cvt_pk_bf16_f32 v122, v122, v123
	v_cvt_pk_bf16_f32 v123, v124, v125
	v_mov_b32_e32 v148, v122
	v_mov_b32_e32 v149, v123
	v_lshl_add_u64 v[160:161], v[128:129], 0, v[166:167]
	v_cvt_pk_bf16_f32 v118, v118, v119
	v_cvt_pk_bf16_f32 v119, v120, v121
	v_mov_b32_e32 v142, v118
	v_mov_b32_e32 v143, v119
	s_nop 1
	v_permlane16_swap_b32_e32 v140, v142
	v_permlane16_swap_b32_e32 v141, v143
	flat_store_dwordx4 v[144:145], v[140:143]
	v_cvt_pk_bf16_f32 v114, v114, v115
	v_cvt_pk_bf16_f32 v115, v116, v117
	v_mov_b32_e32 v150, v114
	v_mov_b32_e32 v151, v115
	s_nop 1
	v_permlane16_swap_b32_e32 v148, v150
	v_permlane16_swap_b32_e32 v149, v151
	flat_store_dwordx4 v[160:161], v[148:151]
	v_cvt_pk_bf16_f32 v110, v110, v111
	v_cvt_pk_bf16_f32 v111, v112, v113
	v_mov_b32_e32 v152, v110
	v_mov_b32_e32 v153, v111
	v_lshl_add_u64 v[162:163], v[138:139], 0, v[166:167]
	v_cvt_pk_bf16_f32 v106, v106, v107
	v_cvt_pk_bf16_f32 v107, v108, v109
	v_mov_b32_e32 v156, v106
	v_mov_b32_e32 v157, v107
	v_lshl_add_u64 v[164:165], v[128:129], 0, v[166:167]
	v_cvt_pk_bf16_f32 v102, v102, v103
	v_cvt_pk_bf16_f32 v103, v104, v105
	v_mov_b32_e32 v154, v102
	v_mov_b32_e32 v155, v103
	s_nop 1
	v_permlane16_swap_b32_e32 v152, v154
	v_permlane16_swap_b32_e32 v153, v155
	flat_store_dwordx4 v[162:163], v[152:155] offset:64
	v_cvt_pk_bf16_f32 v98, v98, v99
	v_cvt_pk_bf16_f32 v99, v100, v101
	v_mov_b32_e32 v158, v98
	v_mov_b32_e32 v159, v99
	s_nop 1
	v_permlane16_swap_b32_e32 v156, v158
	v_permlane16_swap_b32_e32 v157, v159
	flat_store_dwordx4 v[164:165], v[156:159] offset:64
	v_or_b32_e32 v98, 0x80, v132
	v_ashrrev_i32_e32 v99, 31, v98
	v_lshlrev_b64 v[98:99], 12, v[98:99]
	v_lshl_add_u64 v[100:101], v[134:135], 0, v[98:99]
	v_cvt_pk_bf16_f32 v94, v94, v95
	v_cvt_pk_bf16_f32 v95, v96, v97
	v_mov_b32_e32 v140, v94
	v_mov_b32_e32 v141, v95
	v_lshl_add_u64 v[144:145], v[100:101], 0, v[166:167]
	v_or_b32_e32 v94, 0x90, v132
	v_ashrrev_i32_e32 v95, 31, v94
	v_lshlrev_b64 v[94:95], 12, v[94:95]
	v_lshl_add_u64 v[96:97], v[134:135], 0, v[94:95]
	v_cvt_pk_bf16_f32 v90, v90, v91
	v_cvt_pk_bf16_f32 v91, v92, v93
	v_mov_b32_e32 v148, v90
	v_mov_b32_e32 v149, v91
	v_lshl_add_u64 v[160:161], v[96:97], 0, v[166:167]
	v_cvt_pk_bf16_f32 v86, v86, v87
	v_cvt_pk_bf16_f32 v87, v88, v89
	v_mov_b32_e32 v142, v86
	v_mov_b32_e32 v143, v87
	s_nop 1
	v_permlane16_swap_b32_e32 v140, v142
	v_permlane16_swap_b32_e32 v141, v143
	flat_store_dwordx4 v[144:145], v[140:143]
	v_cvt_pk_bf16_f32 v82, v82, v83
	v_cvt_pk_bf16_f32 v83, v84, v85
	v_mov_b32_e32 v150, v82
	v_mov_b32_e32 v151, v83
	s_nop 1
	v_permlane16_swap_b32_e32 v148, v150
	v_permlane16_swap_b32_e32 v149, v151
	flat_store_dwordx4 v[160:161], v[148:151]
	v_cvt_pk_bf16_f32 v78, v78, v79
	v_cvt_pk_bf16_f32 v79, v80, v81
	v_mov_b32_e32 v152, v78
	v_mov_b32_e32 v153, v79
	v_lshl_add_u64 v[162:163], v[100:101], 0, v[166:167]
	v_cvt_pk_bf16_f32 v74, v74, v75
	v_cvt_pk_bf16_f32 v75, v76, v77
	v_mov_b32_e32 v156, v74
	v_mov_b32_e32 v157, v75
	v_lshl_add_u64 v[164:165], v[96:97], 0, v[166:167]
	v_cvt_pk_bf16_f32 v70, v70, v71
	v_cvt_pk_bf16_f32 v71, v72, v73
	v_mov_b32_e32 v154, v70
	v_mov_b32_e32 v155, v71
	s_nop 1
	v_permlane16_swap_b32_e32 v152, v154
	v_permlane16_swap_b32_e32 v153, v155
	flat_store_dwordx4 v[162:163], v[152:155] offset:64
	v_cvt_pk_bf16_f32 v66, v66, v67
	v_cvt_pk_bf16_f32 v67, v68, v69
	v_mov_b32_e32 v158, v66
	v_mov_b32_e32 v159, v67
	s_nop 1
	v_permlane16_swap_b32_e32 v156, v158
	v_permlane16_swap_b32_e32 v157, v159
	flat_store_dwordx4 v[164:165], v[156:159] offset:64
; #define ACC_ZERO(acc) { float z_ = 0.f; asm volatile("" : "+v"(z_)); _Pragma("unroll") for(int ai=0;ai<2;++ai) _Pragma("unroll") for(int bj=0;bj<2;++bj) \
;   _Pragma("unroll") for(int m=0;m<4;++m) _Pragma("unroll") for(int n=0;n<2;++n) acc[ai][bj][m][n]=f32x4{z_,z_,z_,z_}; }
; #define EPI_LOOP(...) _Pragma("unroll") for(int ai=0;ai<2;++ai) _Pragma("unroll") for(int bj=0;bj<2;++bj) \
;   _Pragma("unroll") for(int m=0;m<4;++m) _Pragma("unroll") for(int n=0;n<2;++n) { \
;     const int row=brow+ai*128+wr*64+m*16+fq*4; const int col=bcol+bj*128+wc*32+n*16+fr; \
;     f32x4& v=acc[ai][bj][m][n]; __VA_ARGS__ if (n == 1 && (m & 1)) __builtin_amdgcn_sched_barrier(0); }
; DEVI void run_phase(const int ph, const Params& P, char* shmc, const int wave_u) {
;     ...
;       acc_t acc; ACC_ZERO(acc)
;       gemm_core(w_dn_t + (long)brow * DFF, DFF, hid + (long)bcol * DFF, DFF, DFF, acc, shm, wave_u);
;       GEMM_IDS
;       EPI_LOOP({ st_bf4(T + (long)col * 2048 + row, v[0], v[1], v[2], v[3]); })
	v_add_u32_e32 v66, 0x80, v130
	v_ashrrev_i32_e32 v67, 31, v66
	v_lshl_add_u64 v[66:67], v[66:67], 1, s[12:13]
	v_lshl_add_u64 v[68:69], v[66:67], 0, v[136:137]
	v_cvt_pk_bf16_f32 v62, v62, v63
	v_cvt_pk_bf16_f32 v63, v64, v65
	v_mov_b32_e32 v140, v62
	v_mov_b32_e32 v141, v63
	v_lshl_add_u64 v[144:145], v[68:69], 0, v[166:167]
	v_lshl_add_u64 v[62:63], v[66:67], 0, v[126:127]
	v_cvt_pk_bf16_f32 v58, v58, v59
	v_cvt_pk_bf16_f32 v59, v60, v61
	v_mov_b32_e32 v148, v58
	v_mov_b32_e32 v149, v59
	v_lshl_add_u64 v[160:161], v[62:63], 0, v[166:167]
	v_add_u32_e32 v58, 0x90, v130
	v_ashrrev_i32_e32 v59, 31, v58
	v_lshl_add_u64 v[58:59], v[58:59], 1, s[12:13]
	v_lshl_add_u64 v[60:61], v[58:59], 0, v[136:137]
	v_cvt_pk_bf16_f32 v54, v54, v55
	v_cvt_pk_bf16_f32 v55, v56, v57
	v_mov_b32_e32 v142, v54
	v_mov_b32_e32 v143, v55
	s_nop 1
	v_permlane16_swap_b32_e32 v140, v142
	v_permlane16_swap_b32_e32 v141, v143
	flat_store_dwordx4 v[144:145], v[140:143]
	v_lshl_add_u64 v[54:55], v[58:59], 0, v[126:127]
	v_cvt_pk_bf16_f32 v50, v50, v51
	v_cvt_pk_bf16_f32 v51, v52, v53
	v_mov_b32_e32 v150, v50
	v_mov_b32_e32 v151, v51
	s_nop 1
	v_permlane16_swap_b32_e32 v148, v150
	v_permlane16_swap_b32_e32 v149, v151
	flat_store_dwordx4 v[160:161], v[148:151]
	v_add_u32_e32 v50, 0xa0, v130
	v_ashrrev_i32_e32 v51, 31, v50
	v_lshl_add_u64 v[50:51], v[50:51], 1, s[12:13]
	v_lshl_add_u64 v[52:53], v[50:51], 0, v[136:137]
	v_cvt_pk_bf16_f32 v46, v46, v47
	v_cvt_pk_bf16_f32 v47, v48, v49
	v_mov_b32_e32 v152, v46
	v_mov_b32_e32 v153, v47
	v_lshl_add_u64 v[162:163], v[52:53], 0, v[166:167]
	v_lshl_add_u64 v[46:47], v[50:51], 0, v[126:127]
	v_cvt_pk_bf16_f32 v42, v42, v43
	v_cvt_pk_bf16_f32 v43, v44, v45
	v_mov_b32_e32 v156, v42
	v_mov_b32_e32 v157, v43
	v_lshl_add_u64 v[164:165], v[46:47], 0, v[166:167]
	v_add_u32_e32 v42, 0xb0, v130
	v_ashrrev_i32_e32 v43, 31, v42
	v_lshl_add_u64 v[42:43], v[42:43], 1, s[12:13]
	v_lshl_add_u64 v[44:45], v[42:43], 0, v[136:137]
	v_cvt_pk_bf16_f32 v38, v38, v39
	v_cvt_pk_bf16_f32 v39, v40, v41
	v_mov_b32_e32 v154, v38
	v_mov_b32_e32 v155, v39
	s_nop 1
	v_permlane16_swap_b32_e32 v152, v154
	v_permlane16_swap_b32_e32 v153, v155
	flat_store_dwordx4 v[162:163], v[152:155]
	v_lshl_add_u64 v[38:39], v[42:43], 0, v[126:127]
	v_cvt_pk_bf16_f32 v34, v34, v35
	v_cvt_pk_bf16_f32 v35, v36, v37
	v_mov_b32_e32 v158, v34
	v_mov_b32_e32 v159, v35
	s_nop 1
	v_permlane16_swap_b32_e32 v156, v158
	v_permlane16_swap_b32_e32 v157, v159
	flat_store_dwordx4 v[164:165], v[156:159]
	v_lshl_add_u64 v[34:35], v[66:67], 0, v[98:99]
	v_cvt_pk_bf16_f32 v28, v28, v29
	v_cvt_pk_bf16_f32 v29, v30, v31
	v_mov_b32_e32 v140, v28
	v_mov_b32_e32 v141, v29
	v_lshl_add_u64 v[144:145], v[34:35], 0, v[166:167]
	v_lshl_add_u64 v[28:29], v[66:67], 0, v[94:95]
	v_cvt_pk_bf16_f32 v24, v24, v25
	v_cvt_pk_bf16_f32 v25, v26, v27
	v_mov_b32_e32 v148, v24
	v_mov_b32_e32 v149, v25
	v_lshl_add_u64 v[160:161], v[28:29], 0, v[166:167]
	v_lshl_add_u64 v[24:25], v[58:59], 0, v[98:99]
	v_cvt_pk_bf16_f32 v20, v20, v21
	v_cvt_pk_bf16_f32 v21, v22, v23
	v_mov_b32_e32 v142, v20
	v_mov_b32_e32 v143, v21
	s_nop 1
	v_permlane16_swap_b32_e32 v140, v142
	v_permlane16_swap_b32_e32 v141, v143
	flat_store_dwordx4 v[144:145], v[140:143]
	v_lshl_add_u64 v[20:21], v[58:59], 0, v[94:95]
	v_cvt_pk_bf16_f32 v16, v16, v17
	v_cvt_pk_bf16_f32 v17, v18, v19
	v_mov_b32_e32 v150, v16
	v_mov_b32_e32 v151, v17
	s_nop 1
	v_permlane16_swap_b32_e32 v148, v150
	v_permlane16_swap_b32_e32 v149, v151
	flat_store_dwordx4 v[160:161], v[148:151]
	v_lshl_add_u64 v[16:17], v[50:51], 0, v[98:99]
	v_cvt_pk_bf16_f32 v12, v12, v13
	v_cvt_pk_bf16_f32 v13, v14, v15
	v_mov_b32_e32 v152, v12
	v_mov_b32_e32 v153, v13
	v_lshl_add_u64 v[162:163], v[16:17], 0, v[166:167]
	v_lshl_add_u64 v[12:13], v[50:51], 0, v[94:95]
	v_cvt_pk_bf16_f32 v8, v8, v9
	v_cvt_pk_bf16_f32 v9, v10, v11
	v_mov_b32_e32 v156, v8
	v_mov_b32_e32 v157, v9
	v_lshl_add_u64 v[164:165], v[12:13], 0, v[166:167]
	v_lshl_add_u64 v[8:9], v[42:43], 0, v[98:99]
	v_cvt_pk_bf16_f32 v4, v4, v5
	v_cvt_pk_bf16_f32 v5, v6, v7
	v_mov_b32_e32 v154, v4
	v_mov_b32_e32 v155, v5
	s_nop 1
	v_permlane16_swap_b32_e32 v152, v154
	v_permlane16_swap_b32_e32 v153, v155
	flat_store_dwordx4 v[162:163], v[152:155]
	v_lshl_add_u64 v[4:5], v[42:43], 0, v[94:95]
	v_cvt_pk_bf16_f32 v0, v0, v1
	v_cvt_pk_bf16_f32 v1, v2, v3
	v_mov_b32_e32 v158, v0
	v_mov_b32_e32 v159, v1
	s_nop 1
	v_permlane16_swap_b32_e32 v156, v158
	v_permlane16_swap_b32_e32 v157, v159
	flat_store_dwordx4 v[164:165], v[156:159]
	v_readlane_b32 s0, v254, 26
	s_add_i32 s75, s75, s0
	s_cmpk_gt_i32 s75, 0x1ff
	v_readlane_b32 s1, v254, 27
	s_cbranch_scc1 .LBB0_169

; #define EPI_HALF(AI, ...) _Pragma("unroll") for(int bj=0;bj<2;++bj) _Pragma("unroll") for(int m=0;m<4;++m) _Pragma("unroll") for(int n=0;n<2;++n) { \
;     const int ai=(AI); const int row=brow+ai*128+wr*64+m*16+fq*4; const int col=bcol+bj*128+wc*32+n*16+fr; \
;     f32x4& v=acc[ai][bj][m][n]; __VA_ARGS__ }
; DEVI void run_phase(const int ph, const Params& P, char* shmc, const int wave_u) {
;     ...
;       GEMM_IDS
; #pragma unroll
;       for (int ah = 0; ah < 2; ++ah) {
;         u32x2 gb[2][4][2], tq[2][4][2];
;         EPI_HALF(ah, { (void)v; gb[bj][m][n] = *reinterpret_cast<const u32x2*>(gates + (long)col * 4096 + 2048 + row);
;           tq[bj][m][n] = *reinterpret_cast<const u32x2*>(tmp5 + (long)col * 2048 + row); })
.LBB0_213:
	s_or_b64 exec, exec, s[8:9]
	v_mbcnt_lo_u32_b32 v246, -1, 0
	v_mbcnt_hi_u32_b32 v246, -1, v246
	v_bfe_u32 v246, v246, 4, 1
	v_mul_u32_u24_e32 v246, 24, v246
	v_mov_b32_e32 v247, 0
	v_mbcnt_lo_u32_b32 v32, -1, 0
	v_mbcnt_hi_u32_b32 v32, -1, v32
	s_nop 0
	v_or_b32_e32 v130, s5, v32
	v_ashrrev_i32_e32 v132, 2, v130
	v_and_b32_e32 v132, 0xffffffc0, v132
	v_and_b32_e32 v131, 15, v32
	v_add_u32_e32 v132, s6, v132
	v_lshrrev_b32_e32 v32, 2, v32
	v_and_or_b32 v138, v32, 12, v132
	v_lshrrev_b32_e32 v32, 1, v130
	v_and_b32_e32 v32, 0x60, v32
	v_or3_b32 v130, v131, v32, s0
	v_ashrrev_i32_e32 v131, 31, v130
	v_readlane_b32 s6, v255, 13
	v_lshlrev_b64 v[132:133], 13, v[130:131]
	v_readlane_b32 s7, v255, 14
	s_mov_b64 s[0:1], 0x1000
	v_ashrrev_i32_e32 v139, 31, v138
	v_lshl_add_u64 v[132:133], s[6:7], 0, v[132:133]
	v_lshl_add_u64 v[140:141], v[132:133], 0, s[0:1]
	v_lshlrev_b64 v[178:179], 1, v[138:139]
	v_lshl_add_u64 v[154:155], s[84:85], 0, v[178:179]
	v_lshl_add_u64 v[132:133], v[140:141], 0, v[178:179]
	v_lshlrev_b64 v[136:137], 12, v[130:131]
	flat_load_dwordx2 v[180:181], v[132:133]
	v_lshl_add_u64 v[132:133], v[154:155], 0, v[136:137]
	flat_load_dwordx2 v[182:183], v[132:133]
	v_or_b32_e32 v132, 16, v130
	v_ashrrev_i32_e32 v133, 31, v132
	v_lshlrev_b64 v[134:135], 13, v[132:133]
	v_lshl_add_u64 v[134:135], s[6:7], 0, v[134:135]
	v_lshl_add_u64 v[142:143], v[134:135], 0, s[0:1]
	v_lshl_add_u64 v[134:135], v[142:143], 0, v[178:179]
	flat_load_dwordx2 v[192:193], v[134:135]
	v_lshlrev_b64 v[134:135], 12, v[132:133]
	v_lshl_add_u64 v[132:133], v[154:155], 0, v[134:135]
	flat_load_dwordx2 v[194:195], v[132:133]
	v_or_b32_e32 v132, 16, v138
	v_ashrrev_i32_e32 v133, 31, v132
	v_lshlrev_b64 v[156:157], 1, v[132:133]
	v_lshl_add_u64 v[132:133], v[140:141], 0, v[156:157]
	flat_load_dwordx2 v[196:197], v[132:133]
	v_lshl_add_u64 v[132:133], s[84:85], 0, v[136:137]
	v_lshl_add_u64 v[144:145], v[132:133], 0, v[156:157]
	flat_load_dwordx2 v[198:199], v[144:145]
	v_lshl_add_u64 v[144:145], v[142:143], 0, v[156:157]
	flat_load_dwordx2 v[200:201], v[144:145]
	v_lshl_add_u64 v[144:145], s[84:85], 0, v[134:135]
	v_lshl_add_u64 v[148:149], v[144:145], 0, v[156:157]
	flat_load_dwordx2 v[202:203], v[148:149]
	v_or_b32_e32 v148, 32, v138
	v_ashrrev_i32_e32 v149, 31, v148
	v_lshlrev_b64 v[152:153], 1, v[148:149]
	v_lshl_add_u64 v[148:149], v[140:141], 0, v[152:153]
	flat_load_dwordx2 v[204:205], v[148:149]
	v_lshl_add_u64 v[148:149], v[132:133], 0, v[152:153]
	flat_load_dwordx2 v[206:207], v[148:149]
	v_lshl_add_u64 v[148:149], v[142:143], 0, v[152:153]
	flat_load_dwordx2 v[208:209], v[148:149]
	v_lshl_add_u64 v[148:149], v[144:145], 0, v[152:153]
	flat_load_dwordx2 v[210:211], v[148:149]
	v_or_b32_e32 v148, 48, v138
	v_ashrrev_i32_e32 v149, 31, v148
	v_lshlrev_b64 v[150:151], 1, v[148:149]
	v_lshl_add_u64 v[132:133], v[132:133], 0, v[150:151]
	v_lshl_add_u64 v[148:149], v[140:141], 0, v[150:151]
	flat_load_dwordx2 v[214:215], v[132:133]
	v_lshl_add_u64 v[132:133], v[142:143], 0, v[150:151]
	flat_load_dwordx2 v[212:213], v[148:149]
	flat_load_dwordx2 v[216:217], v[132:133]
	v_lshl_add_u64 v[132:133], v[144:145], 0, v[150:151]
	flat_load_dwordx2 v[218:219], v[132:133]
	v_or_b32_e32 v132, 0x80, v130
	v_ashrrev_i32_e32 v133, 31, v132
	v_lshlrev_b64 v[144:145], 13, v[132:133]
	v_lshl_add_u64 v[144:145], s[6:7], 0, v[144:145]
	v_lshl_add_u64 v[144:145], v[144:145], 0, s[0:1]
	v_lshl_add_u64 v[148:149], v[144:145], 0, v[178:179]
	v_lshlrev_b64 v[132:133], 12, v[132:133]
	v_or_b32_e32 v130, 0x90, v130
	flat_load_dwordx2 v[220:221], v[148:149]
	v_lshl_add_u64 v[148:149], v[154:155], 0, v[132:133]
	v_ashrrev_i32_e32 v131, 31, v130
	flat_load_dwordx2 v[222:223], v[148:149]
	v_lshlrev_b64 v[148:149], 13, v[130:131]
	v_lshl_add_u64 v[148:149], s[6:7], 0, v[148:149]
	v_lshl_add_u64 v[148:149], v[148:149], 0, s[0:1]
	v_lshlrev_b64 v[130:131], 12, v[130:131]
	v_lshl_add_u64 v[158:159], v[148:149], 0, v[178:179]
	v_lshl_add_u64 v[154:155], v[154:155], 0, v[130:131]
	flat_load_dwordx2 v[224:225], v[158:159]
	flat_load_dwordx2 v[226:227], v[154:155]
	v_lshl_add_u64 v[154:155], v[144:145], 0, v[156:157]
	flat_load_dwordx2 v[176:177], v[154:155]
	v_lshl_add_u64 v[154:155], s[84:85], 0, v[132:133]
	v_lshl_add_u64 v[158:159], v[154:155], 0, v[156:157]
	flat_load_dwordx2 v[228:229], v[158:159]
	v_lshl_add_u64 v[158:159], v[148:149], 0, v[156:157]
	flat_load_dwordx2 v[172:173], v[158:159]
	v_lshl_add_u64 v[158:159], s[84:85], 0, v[130:131]
	v_lshl_add_u64 v[160:161], v[158:159], 0, v[156:157]
	flat_load_dwordx2 v[174:175], v[160:161]
	v_lshl_add_u64 v[160:161], v[144:145], 0, v[152:153]
	flat_load_dwordx2 v[168:169], v[160:161]
	v_lshl_add_u64 v[160:161], v[154:155], 0, v[152:153]
	flat_load_dwordx2 v[170:171], v[160:161]
	v_lshl_add_u64 v[160:161], v[148:149], 0, v[152:153]
	flat_load_dwordx2 v[164:165], v[160:161]
	v_lshl_add_u64 v[160:161], v[158:159], 0, v[152:153]
	flat_load_dwordx2 v[166:167], v[160:161]
	v_lshl_add_u64 v[154:155], v[154:155], 0, v[150:151]
	v_lshl_add_u64 v[158:159], v[158:159], 0, v[150:151]
	flat_load_dwordx2 v[162:163], v[154:155]
	s_waitcnt vmcnt(0) lgkmcnt(0)
; #define EPI_HALF(AI, ...) _Pragma("unroll") for(int bj=0;bj<2;++bj) _Pragma("unroll") for(int m=0;m<4;++m) _Pragma("unroll") for(int n=0;n<2;++n) { \
;     const int ai=(AI); const int row=brow+ai*128+wr*64+m*16+fq*4; const int col=bcol+bj*128+wc*32+n*16+fr; \
;     f32x4& v=acc[ai][bj][m][n]; __VA_ARGS__ }
; DEVI void run_phase(const int ph, const Params& P, char* shmc, const int wave_u) {
;     ...
;       for (int ah = 0; ah < 2; ++ah) {
;         u32x2 gb[2][4][2], tq[2][4][2];
;         EPI_HALF(ah, { (void)v; gb[bj][m][n] = *reinterpret_cast<const u32x2*>(gates + (long)col * 4096 + 2048 + row);
;           tq[bj][m][n] = *reinterpret_cast<const u32x2*>(tmp5 + (long)col * 2048 + row); })
;         EPI_HALF(ah, { const u32x2 b = gb[bj][m][n]; const u32x2 tw = tq[bj][m][n];
;           const f32x4 t0 = {__uint_as_float(tw[0] << 16), __uint_as_float(tw[0] & 0xffff0000u), __uint_as_float(tw[1] << 16), __uint_as_float(tw[1] & 0xffff0000u)};
;           st_bf4(merged + (long)col * 2048 + row, t0[0] + v[0] * __uint_as_float(b[0] << 16), t0[1] + v[1] * __uint_as_float(b[0] & 0xffff0000u),
;                  t0[2] + v[2] * __uint_as_float(b[1] << 16), t0[3] + v[3] * __uint_as_float(b[1] & 0xffff0000u)); })
;       }
	v_lshlrev_b32_e32 v32, 16, v182
	flat_load_dwordx2 v[158:159], v[158:159]
	v_lshl_add_u64 v[160:161], v[144:145], 0, v[150:151]
	flat_load_dwordx2 v[160:161], v[160:161]
	v_lshl_add_u64 v[154:155], v[148:149], 0, v[150:151]
	flat_load_dwordx2 v[154:155], v[154:155]
	v_lshlrev_b32_e32 v232, 16, v180
	v_and_b32_e32 v139, 0xffff0000, v182
	v_fmac_f32_e32 v32, v126, v232
	v_and_b32_e32 v126, 0xffff0000, v180
	v_lshlrev_b32_e32 v230, 16, v183
	v_fmac_f32_e32 v139, v127, v126
	v_lshlrev_b32_e32 v126, 16, v181
	v_and_b32_e32 v231, 0xffff0000, v183
	v_fmac_f32_e32 v230, v128, v126
	v_and_b32_e32 v126, 0xffff0000, v181
	v_fmac_f32_e32 v231, v129, v126
	v_cvt_pk_bf16_f32 v126, v32, v139
	v_lshlrev_b32_e32 v32, 16, v194
	v_lshlrev_b32_e32 v180, 16, v192
	v_and_b32_e32 v128, 0xffff0000, v194
	v_fmac_f32_e32 v32, v122, v180
	v_and_b32_e32 v122, 0xffff0000, v192
	v_lshl_add_u64 v[178:179], s[82:83], 0, v[178:179]
	v_lshlrev_b32_e32 v129, 16, v195
	v_fmac_f32_e32 v128, v123, v122
	v_lshlrev_b32_e32 v122, 16, v193
	v_lshl_add_u64 v[182:183], v[178:179], 0, v[136:137]
	v_cvt_pk_bf16_f32 v127, v230, v231
	v_and_b32_e32 v139, 0xffff0000, v195
	v_fmac_f32_e32 v129, v124, v122
	v_and_b32_e32 v122, 0xffff0000, v193
	v_mov_b32_e32 v236, v126
	v_mov_b32_e32 v237, v127
	v_lshl_add_u64 v[234:235], v[182:183], 0, v[246:247]
	v_lshl_add_u64 v[126:127], v[178:179], 0, v[134:135]
	v_fmac_f32_e32 v139, v125, v122
	v_cvt_pk_bf16_f32 v122, v32, v128
	v_cvt_pk_bf16_f32 v123, v129, v139
	v_lshlrev_b32_e32 v32, 16, v198
	v_lshlrev_b32_e32 v129, 16, v196
	v_mov_b32_e32 v240, v122
	v_mov_b32_e32 v241, v123
	v_lshl_add_u64 v[244:245], v[126:127], 0, v[246:247]
	v_and_b32_e32 v126, 0xffff0000, v198
	v_fmac_f32_e32 v32, v118, v129
	v_and_b32_e32 v118, 0xffff0000, v196
	v_lshlrev_b32_e32 v127, 16, v199
	v_fmac_f32_e32 v126, v119, v118
	v_lshlrev_b32_e32 v118, 16, v197
	v_and_b32_e32 v128, 0xffff0000, v199
	v_lshl_add_u64 v[122:123], s[82:83], 0, v[136:137]
	v_fmac_f32_e32 v127, v120, v118
	v_and_b32_e32 v118, 0xffff0000, v197
	v_lshl_add_u64 v[124:125], v[122:123], 0, v[156:157]
	v_fmac_f32_e32 v128, v121, v118
	v_cvt_pk_bf16_f32 v118, v32, v126
	v_cvt_pk_bf16_f32 v119, v127, v128
	v_lshlrev_b32_e32 v32, 16, v202
	v_lshlrev_b32_e32 v127, 16, v200
	v_mov_b32_e32 v238, v118
	v_mov_b32_e32 v239, v119
	s_nop 1
	v_permlane16_swap_b32_e32 v236, v238
	v_permlane16_swap_b32_e32 v237, v239
	flat_store_dwordx4 v[234:235], v[236:239]
	v_and_b32_e32 v124, 0xffff0000, v202
	v_fmac_f32_e32 v32, v114, v127
	v_and_b32_e32 v114, 0xffff0000, v200
	v_lshlrev_b32_e32 v125, 16, v203
	v_lshl_add_u64 v[118:119], s[82:83], 0, v[134:135]
	v_fmac_f32_e32 v124, v115, v114
	v_lshlrev_b32_e32 v114, 16, v201
	v_and_b32_e32 v126, 0xffff0000, v203
	v_lshl_add_u64 v[120:121], v[118:119], 0, v[156:157]
	v_fmac_f32_e32 v125, v116, v114
	v_and_b32_e32 v114, 0xffff0000, v201
	v_fmac_f32_e32 v126, v117, v114
	v_cvt_pk_bf16_f32 v114, v32, v124
	v_cvt_pk_bf16_f32 v115, v125, v126
	v_mov_b32_e32 v242, v114
	v_mov_b32_e32 v243, v115
	s_nop 1
	v_permlane16_swap_b32_e32 v240, v242
	v_permlane16_swap_b32_e32 v241, v243
	flat_store_dwordx4 v[244:245], v[240:243]
	v_lshlrev_b32_e32 v32, 16, v206
	v_lshlrev_b32_e32 v121, 16, v204
	v_and_b32_e32 v116, 0xffff0000, v206
	v_fmac_f32_e32 v32, v110, v121
	v_and_b32_e32 v110, 0xffff0000, v204
	v_lshlrev_b32_e32 v117, 16, v207
	v_fmac_f32_e32 v116, v111, v110
	v_lshlrev_b32_e32 v110, 16, v205
	v_and_b32_e32 v120, 0xffff0000, v207
	v_lshl_add_u64 v[114:115], v[122:123], 0, v[152:153]
	v_fmac_f32_e32 v117, v112, v110
	v_and_b32_e32 v110, 0xffff0000, v205
	v_fmac_f32_e32 v120, v113, v110
	v_cvt_pk_bf16_f32 v110, v32, v116
	v_cvt_pk_bf16_f32 v111, v117, v120
	v_mov_b32_e32 v236, v110
	v_mov_b32_e32 v237, v111
	v_lshl_add_u64 v[234:235], v[114:115], 0, v[246:247]
	v_lshlrev_b32_e32 v32, 16, v210
	v_lshlrev_b32_e32 v115, 16, v208
	v_and_b32_e32 v112, 0xffff0000, v210
	v_fmac_f32_e32 v32, v106, v115
	v_and_b32_e32 v106, 0xffff0000, v208
	v_lshlrev_b32_e32 v113, 16, v211
	v_fmac_f32_e32 v112, v107, v106
	v_lshlrev_b32_e32 v106, 16, v209
	v_and_b32_e32 v114, 0xffff0000, v211
	v_lshl_add_u64 v[110:111], v[118:119], 0, v[152:153]
	v_fmac_f32_e32 v113, v108, v106
	v_and_b32_e32 v106, 0xffff0000, v209
	v_fmac_f32_e32 v114, v109, v106
	v_cvt_pk_bf16_f32 v106, v32, v112
	v_cvt_pk_bf16_f32 v107, v113, v114
	v_mov_b32_e32 v240, v106
	v_mov_b32_e32 v241, v107
	v_lshl_add_u64 v[244:245], v[110:111], 0, v[246:247]
	v_lshlrev_b32_e32 v32, 16, v214
	v_lshlrev_b32_e32 v111, 16, v212
	v_and_b32_e32 v108, 0xffff0000, v214
	v_fmac_f32_e32 v32, v102, v111
	v_and_b32_e32 v102, 0xffff0000, v212
	v_lshlrev_b32_e32 v109, 16, v215
	v_fmac_f32_e32 v108, v103, v102
	v_lshlrev_b32_e32 v102, 16, v213
	v_and_b32_e32 v110, 0xffff0000, v215
	v_lshl_add_u64 v[106:107], v[122:123], 0, v[150:151]
	v_fmac_f32_e32 v109, v104, v102
	v_and_b32_e32 v102, 0xffff0000, v213
	v_fmac_f32_e32 v110, v105, v102
	v_cvt_pk_bf16_f32 v102, v32, v108
	v_cvt_pk_bf16_f32 v103, v109, v110
	v_mov_b32_e32 v238, v102
	v_mov_b32_e32 v239, v103
	s_nop 1
	v_permlane16_swap_b32_e32 v236, v238
	v_permlane16_swap_b32_e32 v237, v239
	flat_store_dwordx4 v[234:235], v[236:239]
	v_lshlrev_b32_e32 v32, 16, v218
	v_lshlrev_b32_e32 v107, 16, v216
	v_and_b32_e32 v104, 0xffff0000, v218
	v_fmac_f32_e32 v32, v98, v107
	v_and_b32_e32 v98, 0xffff0000, v216
	v_lshlrev_b32_e32 v105, 16, v219
	v_fmac_f32_e32 v104, v99, v98
	v_lshlrev_b32_e32 v98, 16, v217
	v_and_b32_e32 v106, 0xffff0000, v219
	v_lshl_add_u64 v[102:103], v[118:119], 0, v[150:151]
	v_fmac_f32_e32 v105, v100, v98
	v_and_b32_e32 v98, 0xffff0000, v217
	v_fmac_f32_e32 v106, v101, v98
	v_cvt_pk_bf16_f32 v98, v32, v104
; #define EPI_HALF(AI, ...) _Pragma("unroll") for(int bj=0;bj<2;++bj) _Pragma("unroll") for(int m=0;m<4;++m) _Pragma("unroll") for(int n=0;n<2;++n) { \
;     const int ai=(AI); const int row=brow+ai*128+wr*64+m*16+fq*4; const int col=bcol+bj*128+wc*32+n*16+fr; \
;     f32x4& v=acc[ai][bj][m][n]; __VA_ARGS__ }
; DEVI void run_phase(const int ph, const Params& P, char* shmc, const int wave_u) {
;     ...
;       for (int ah = 0; ah < 2; ++ah) {
;         u32x2 gb[2][4][2], tq[2][4][2];
;         EPI_HALF(ah, { (void)v; gb[bj][m][n] = *reinterpret_cast<const u32x2*>(gates + (long)col * 4096 + 2048 + row);
;           tq[bj][m][n] = *reinterpret_cast<const u32x2*>(tmp5 + (long)col * 2048 + row); })
;         EPI_HALF(ah, { const u32x2 b = gb[bj][m][n]; const u32x2 tw = tq[bj][m][n];
;           const f32x4 t0 = {__uint_as_float(tw[0] << 16), __uint_as_float(tw[0] & 0xffff0000u), __uint_as_float(tw[1] << 16), __uint_as_float(tw[1] & 0xffff0000u)};
;           st_bf4(merged + (long)col * 2048 + row, t0[0] + v[0] * __uint_as_float(b[0] << 16), t0[1] + v[1] * __uint_as_float(b[0] & 0xffff0000u),
;                  t0[2] + v[2] * __uint_as_float(b[1] << 16), t0[3] + v[3] * __uint_as_float(b[1] & 0xffff0000u)); })
;       }
	v_cvt_pk_bf16_f32 v99, v105, v106
	v_mov_b32_e32 v242, v98
	v_mov_b32_e32 v243, v99
	s_nop 1
	v_permlane16_swap_b32_e32 v240, v242
	v_permlane16_swap_b32_e32 v241, v243
	flat_store_dwordx4 v[244:245], v[240:243]
	v_lshlrev_b32_e32 v32, 16, v222
	v_lshlrev_b32_e32 v103, 16, v220
	v_and_b32_e32 v100, 0xffff0000, v222
	v_fmac_f32_e32 v32, v94, v103
	v_and_b32_e32 v94, 0xffff0000, v220
	v_lshlrev_b32_e32 v101, 16, v223
	v_fmac_f32_e32 v100, v95, v94
	v_lshlrev_b32_e32 v94, 16, v221
	v_and_b32_e32 v102, 0xffff0000, v223
	v_lshl_add_u64 v[98:99], v[178:179], 0, v[132:133]
	v_fmac_f32_e32 v101, v96, v94
	v_and_b32_e32 v94, 0xffff0000, v221
	v_fmac_f32_e32 v102, v97, v94
	v_cvt_pk_bf16_f32 v94, v32, v100
	v_cvt_pk_bf16_f32 v95, v101, v102
	v_mov_b32_e32 v236, v94
	v_mov_b32_e32 v237, v95
	v_lshl_add_u64 v[234:235], v[98:99], 0, v[246:247]
	v_lshlrev_b32_e32 v32, 16, v226
	v_lshlrev_b32_e32 v99, 16, v224
	v_and_b32_e32 v96, 0xffff0000, v226
	v_fmac_f32_e32 v32, v90, v99
	v_and_b32_e32 v90, 0xffff0000, v224
	v_lshlrev_b32_e32 v97, 16, v227
	v_fmac_f32_e32 v96, v91, v90
	v_lshlrev_b32_e32 v90, 16, v225
	v_and_b32_e32 v98, 0xffff0000, v227
	v_fmac_f32_e32 v97, v92, v90
	v_and_b32_e32 v90, 0xffff0000, v225
	v_lshl_add_u64 v[94:95], v[178:179], 0, v[130:131]
	v_fmac_f32_e32 v98, v93, v90
	v_cvt_pk_bf16_f32 v90, v32, v96
	v_cvt_pk_bf16_f32 v91, v97, v98
	v_lshlrev_b32_e32 v32, 16, v228
	v_lshlrev_b32_e32 v97, 16, v176
	v_mov_b32_e32 v240, v90
	v_mov_b32_e32 v241, v91
	v_lshl_add_u64 v[244:245], v[94:95], 0, v[246:247]
	v_and_b32_e32 v94, 0xffff0000, v228
	v_fmac_f32_e32 v32, v86, v97
	v_and_b32_e32 v86, 0xffff0000, v176
	v_lshlrev_b32_e32 v95, 16, v229
	v_fmac_f32_e32 v94, v87, v86
	v_lshlrev_b32_e32 v86, 16, v177
	v_and_b32_e32 v96, 0xffff0000, v229
	v_lshl_add_u64 v[90:91], s[82:83], 0, v[132:133]
	v_fmac_f32_e32 v95, v88, v86
	v_and_b32_e32 v86, 0xffff0000, v177
	v_lshl_add_u64 v[92:93], v[90:91], 0, v[156:157]
	v_fmac_f32_e32 v96, v89, v86
	v_cvt_pk_bf16_f32 v86, v32, v94
	v_cvt_pk_bf16_f32 v87, v95, v96
	v_lshlrev_b32_e32 v32, 16, v174
	v_lshlrev_b32_e32 v95, 16, v172
	v_mov_b32_e32 v238, v86
	v_mov_b32_e32 v239, v87
	s_nop 1
	v_permlane16_swap_b32_e32 v236, v238
	v_permlane16_swap_b32_e32 v237, v239
	flat_store_dwordx4 v[234:235], v[236:239]
	v_and_b32_e32 v92, 0xffff0000, v174
	v_fmac_f32_e32 v32, v82, v95
	v_and_b32_e32 v82, 0xffff0000, v172
	v_lshlrev_b32_e32 v93, 16, v175
	v_lshl_add_u64 v[86:87], s[82:83], 0, v[130:131]
	v_fmac_f32_e32 v92, v83, v82
	v_lshlrev_b32_e32 v82, 16, v173
	v_and_b32_e32 v94, 0xffff0000, v175
	v_lshl_add_u64 v[88:89], v[86:87], 0, v[156:157]
	v_fmac_f32_e32 v93, v84, v82
	v_and_b32_e32 v82, 0xffff0000, v173
	v_fmac_f32_e32 v94, v85, v82
	v_cvt_pk_bf16_f32 v82, v32, v92
	v_cvt_pk_bf16_f32 v83, v93, v94
	v_mov_b32_e32 v242, v82
	v_mov_b32_e32 v243, v83
	s_nop 1
	v_permlane16_swap_b32_e32 v240, v242
	v_permlane16_swap_b32_e32 v241, v243
	flat_store_dwordx4 v[244:245], v[240:243]
	v_lshlrev_b32_e32 v32, 16, v170
	v_lshlrev_b32_e32 v89, 16, v168
	v_and_b32_e32 v84, 0xffff0000, v170
	v_fmac_f32_e32 v32, v78, v89
	v_and_b32_e32 v78, 0xffff0000, v168
	v_lshlrev_b32_e32 v85, 16, v171
	v_fmac_f32_e32 v84, v79, v78
	v_lshlrev_b32_e32 v78, 16, v169
	v_and_b32_e32 v88, 0xffff0000, v171
	v_lshl_add_u64 v[82:83], v[90:91], 0, v[152:153]
	v_fmac_f32_e32 v85, v80, v78
	v_and_b32_e32 v78, 0xffff0000, v169
	v_fmac_f32_e32 v88, v81, v78
	v_cvt_pk_bf16_f32 v78, v32, v84
	v_cvt_pk_bf16_f32 v79, v85, v88
	v_mov_b32_e32 v236, v78
	v_mov_b32_e32 v237, v79
	v_lshl_add_u64 v[234:235], v[82:83], 0, v[246:247]
	v_lshlrev_b32_e32 v32, 16, v166
	v_lshlrev_b32_e32 v83, 16, v164
	v_and_b32_e32 v80, 0xffff0000, v166
	v_fmac_f32_e32 v32, v74, v83
	v_and_b32_e32 v74, 0xffff0000, v164
	v_lshlrev_b32_e32 v81, 16, v167
	v_fmac_f32_e32 v80, v75, v74
	v_lshlrev_b32_e32 v74, 16, v165
	v_and_b32_e32 v82, 0xffff0000, v167
	v_lshl_add_u64 v[78:79], v[86:87], 0, v[152:153]
	v_fmac_f32_e32 v81, v76, v74
	v_and_b32_e32 v74, 0xffff0000, v165
	v_fmac_f32_e32 v82, v77, v74
	v_cvt_pk_bf16_f32 v74, v32, v80
	v_cvt_pk_bf16_f32 v75, v81, v82
	v_mov_b32_e32 v240, v74
	v_mov_b32_e32 v241, v75
	v_lshl_add_u64 v[244:245], v[78:79], 0, v[246:247]
	v_lshlrev_b32_e32 v32, 16, v162
	s_waitcnt vmcnt(0) lgkmcnt(0)
; #define EPI_HALF(AI, ...) _Pragma("unroll") for(int bj=0;bj<2;++bj) _Pragma("unroll") for(int m=0;m<4;++m) _Pragma("unroll") for(int n=0;n<2;++n) { \
;     const int ai=(AI); const int row=brow+ai*128+wr*64+m*16+fq*4; const int col=bcol+bj*128+wc*32+n*16+fr; \
;     f32x4& v=acc[ai][bj][m][n]; __VA_ARGS__ }
; DEVI void run_phase(const int ph, const Params& P, char* shmc, const int wave_u) {
;     ...
;       for (int ah = 0; ah < 2; ++ah) {
;         u32x2 gb[2][4][2], tq[2][4][2];
;         EPI_HALF(ah, { (void)v; gb[bj][m][n] = *reinterpret_cast<const u32x2*>(gates + (long)col * 4096 + 2048 + row);
;           tq[bj][m][n] = *reinterpret_cast<const u32x2*>(tmp5 + (long)col * 2048 + row); })
;         EPI_HALF(ah, { const u32x2 b = gb[bj][m][n]; const u32x2 tw = tq[bj][m][n];
;           const f32x4 t0 = {__uint_as_float(tw[0] << 16), __uint_as_float(tw[0] & 0xffff0000u), __uint_as_float(tw[1] << 16), __uint_as_float(tw[1] & 0xffff0000u)};
;           st_bf4(merged + (long)col * 2048 + row, t0[0] + v[0] * __uint_as_float(b[0] << 16), t0[1] + v[1] * __uint_as_float(b[0] & 0xffff0000u),
;                  t0[2] + v[2] * __uint_as_float(b[1] << 16), t0[3] + v[3] * __uint_as_float(b[1] & 0xffff0000u)); })
;       }
	v_lshlrev_b32_e32 v79, 16, v160
	v_and_b32_e32 v76, 0xffff0000, v162
	v_fmac_f32_e32 v32, v70, v79
	v_and_b32_e32 v70, 0xffff0000, v160
	v_lshlrev_b32_e32 v77, 16, v163
	v_fmac_f32_e32 v76, v71, v70
	v_lshlrev_b32_e32 v70, 16, v161
	v_and_b32_e32 v78, 0xffff0000, v163
	v_lshl_add_u64 v[74:75], v[90:91], 0, v[150:151]
	v_fmac_f32_e32 v77, v72, v70
	v_and_b32_e32 v70, 0xffff0000, v161
	v_fmac_f32_e32 v78, v73, v70
	v_cvt_pk_bf16_f32 v70, v32, v76
	v_cvt_pk_bf16_f32 v71, v77, v78
	v_mov_b32_e32 v238, v70
	v_mov_b32_e32 v239, v71
	s_nop 1
	v_permlane16_swap_b32_e32 v236, v238
	v_permlane16_swap_b32_e32 v237, v239
	flat_store_dwordx4 v[234:235], v[236:239]
	v_lshlrev_b32_e32 v32, 16, v158
	v_lshlrev_b32_e32 v75, 16, v154
	v_and_b32_e32 v72, 0xffff0000, v158
	v_fmac_f32_e32 v32, v66, v75
	v_and_b32_e32 v66, 0xffff0000, v154
	v_lshlrev_b32_e32 v73, 16, v159
	v_fmac_f32_e32 v72, v67, v66
	v_lshlrev_b32_e32 v66, 16, v155
	v_and_b32_e32 v74, 0xffff0000, v159
	v_fmac_f32_e32 v73, v68, v66
	v_and_b32_e32 v66, 0xffff0000, v155
	v_lshl_add_u64 v[70:71], v[86:87], 0, v[150:151]
	v_fmac_f32_e32 v74, v69, v66
	v_cvt_pk_bf16_f32 v66, v32, v72
	v_cvt_pk_bf16_f32 v67, v73, v74
	v_mov_b32_e32 v242, v66
	v_mov_b32_e32 v243, v67
	s_nop 1
	v_permlane16_swap_b32_e32 v240, v242
	v_permlane16_swap_b32_e32 v241, v243
	flat_store_dwordx4 v[244:245], v[240:243]
	v_add_u32_e32 v66, 0x80, v138
	v_ashrrev_i32_e32 v67, 31, v66
	v_lshlrev_b64 v[88:89], 1, v[66:67]
	v_lshl_add_u64 v[66:67], s[84:85], 0, v[88:89]
	v_lshl_add_u64 v[68:69], v[66:67], 0, v[136:137]
	flat_load_dwordx2 v[90:91], v[68:69]
	v_lshl_add_u64 v[68:69], v[140:141], 0, v[88:89]
	flat_load_dwordx2 v[92:93], v[68:69]
	v_lshl_add_u64 v[68:69], v[142:143], 0, v[88:89]
	flat_load_dwordx2 v[94:95], v[68:69]
	v_lshl_add_u64 v[68:69], v[66:67], 0, v[134:135]
	flat_load_dwordx2 v[96:97], v[68:69]
	v_add_u32_e32 v68, 0x90, v138
	v_ashrrev_i32_e32 v69, 31, v68
	v_lshlrev_b64 v[98:99], 1, v[68:69]
	v_lshl_add_u64 v[68:69], s[84:85], 0, v[98:99]
	v_lshl_add_u64 v[70:71], v[140:141], 0, v[98:99]
	flat_load_dwordx2 v[100:101], v[70:71]
	v_lshl_add_u64 v[70:71], v[68:69], 0, v[136:137]
	flat_load_dwordx2 v[102:103], v[70:71]
	v_lshl_add_u64 v[70:71], v[142:143], 0, v[98:99]
	flat_load_dwordx2 v[104:105], v[70:71]
	v_lshl_add_u64 v[70:71], v[68:69], 0, v[134:135]
	flat_load_dwordx2 v[106:107], v[70:71]
	v_add_u32_e32 v70, 0xa0, v138
	v_ashrrev_i32_e32 v71, 31, v70
	v_lshlrev_b64 v[108:109], 1, v[70:71]
	v_lshl_add_u64 v[70:71], s[84:85], 0, v[108:109]
	v_lshl_add_u64 v[72:73], v[140:141], 0, v[108:109]
	flat_load_dwordx2 v[110:111], v[72:73]
	v_lshl_add_u64 v[72:73], v[70:71], 0, v[136:137]
	flat_load_dwordx2 v[112:113], v[72:73]
	v_lshl_add_u64 v[72:73], v[142:143], 0, v[108:109]
	flat_load_dwordx2 v[114:115], v[72:73]
	v_lshl_add_u64 v[72:73], v[70:71], 0, v[134:135]
	flat_load_dwordx2 v[116:117], v[72:73]
	v_add_u32_e32 v72, 0xb0, v138
	v_ashrrev_i32_e32 v73, 31, v72
	v_lshlrev_b64 v[118:119], 1, v[72:73]
	v_lshl_add_u64 v[120:121], s[84:85], 0, v[118:119]
	v_lshl_add_u64 v[72:73], v[140:141], 0, v[118:119]
	flat_load_dwordx2 v[122:123], v[72:73]
	v_lshl_add_u64 v[72:73], v[120:121], 0, v[136:137]
	flat_load_dwordx2 v[124:125], v[72:73]
	v_lshl_add_u64 v[72:73], v[142:143], 0, v[118:119]
	flat_load_dwordx2 v[126:127], v[72:73]
	v_lshl_add_u64 v[72:73], v[120:121], 0, v[134:135]
	flat_load_dwordx2 v[128:129], v[72:73]
	v_lshl_add_u64 v[72:73], v[144:145], 0, v[88:89]
	flat_load_dwordx2 v[138:139], v[72:73]
	v_lshl_add_u64 v[72:73], v[66:67], 0, v[132:133]
	flat_load_dwordx2 v[140:141], v[72:73]
	v_lshl_add_u64 v[66:67], v[66:67], 0, v[130:131]
	flat_load_dwordx2 v[150:151], v[66:67]
	v_lshl_add_u64 v[72:73], v[148:149], 0, v[88:89]
	flat_load_dwordx2 v[142:143], v[72:73]
	v_lshl_add_u64 v[66:67], v[144:145], 0, v[98:99]
	flat_load_dwordx2 v[86:87], v[66:67]
	v_lshl_add_u64 v[66:67], v[68:69], 0, v[132:133]
	flat_load_dwordx2 v[152:153], v[66:67]
	v_lshl_add_u64 v[66:67], v[148:149], 0, v[98:99]
	flat_load_dwordx2 v[82:83], v[66:67]
	v_lshl_add_u64 v[66:67], v[68:69], 0, v[130:131]
	flat_load_dwordx2 v[84:85], v[66:67]
	v_lshl_add_u64 v[68:69], v[120:121], 0, v[130:131]
	flat_load_dwordx2 v[68:69], v[68:69]
	v_lshl_add_u64 v[66:67], v[144:145], 0, v[108:109]
	flat_load_dwordx2 v[78:79], v[66:67]
	v_lshl_add_u64 v[66:67], v[70:71], 0, v[132:133]
	flat_load_dwordx2 v[80:81], v[66:67]
	v_lshl_add_u64 v[66:67], v[148:149], 0, v[108:109]
	flat_load_dwordx2 v[74:75], v[66:67]
	v_lshl_add_u64 v[66:67], v[70:71], 0, v[130:131]
	flat_load_dwordx2 v[76:77], v[66:67]
	v_lshl_add_u64 v[66:67], v[144:145], 0, v[118:119]
	flat_load_dwordx2 v[70:71], v[66:67]
	v_lshl_add_u64 v[66:67], v[120:121], 0, v[132:133]
	flat_load_dwordx2 v[72:73], v[66:67]
	v_lshl_add_u64 v[66:67], v[148:149], 0, v[118:119]
	flat_load_dwordx2 v[66:67], v[66:67]
	v_lshl_add_u64 v[88:89], s[82:83], 0, v[88:89]
	v_readlane_b32 s0, v254, 26
	s_add_i32 s72, s72, s0
	s_cmpk_gt_i32 s72, 0x1ff
	v_readlane_b32 s1, v254, 27
	s_waitcnt vmcnt(0) lgkmcnt(0)
; #define EPI_HALF(AI, ...) _Pragma("unroll") for(int bj=0;bj<2;++bj) _Pragma("unroll") for(int m=0;m<4;++m) _Pragma("unroll") for(int n=0;n<2;++n) { \
;     const int ai=(AI); const int row=brow+ai*128+wr*64+m*16+fq*4; const int col=bcol+bj*128+wc*32+n*16+fr; \
;     f32x4& v=acc[ai][bj][m][n]; __VA_ARGS__ }
; DEVI void run_phase(const int ph, const Params& P, char* shmc, const int wave_u) {
;     ...
;       for (int ah = 0; ah < 2; ++ah) {
;         u32x2 gb[2][4][2], tq[2][4][2];
;         EPI_HALF(ah, { (void)v; gb[bj][m][n] = *reinterpret_cast<const u32x2*>(gates + (long)col * 4096 + 2048 + row);
;           tq[bj][m][n] = *reinterpret_cast<const u32x2*>(tmp5 + (long)col * 2048 + row); })
;         EPI_HALF(ah, { const u32x2 b = gb[bj][m][n]; const u32x2 tw = tq[bj][m][n];
;           const f32x4 t0 = {__uint_as_float(tw[0] << 16), __uint_as_float(tw[0] & 0xffff0000u), __uint_as_float(tw[1] << 16), __uint_as_float(tw[1] & 0xffff0000u)};
;           st_bf4(merged + (long)col * 2048 + row, t0[0] + v[0] * __uint_as_float(b[0] << 16), t0[1] + v[1] * __uint_as_float(b[0] & 0xffff0000u),
;                  t0[2] + v[2] * __uint_as_float(b[1] << 16), t0[3] + v[3] * __uint_as_float(b[1] & 0xffff0000u)); })
;       }
	v_lshlrev_b32_e32 v32, 16, v90
	v_and_b32_e32 v120, 0xffff0000, v90
	v_lshlrev_b32_e32 v145, 16, v92
	v_fmac_f32_e32 v32, v62, v145
	v_and_b32_e32 v62, 0xffff0000, v92
	v_lshlrev_b32_e32 v121, 16, v91
	v_fmac_f32_e32 v120, v63, v62
	v_lshlrev_b32_e32 v62, 16, v93
	v_and_b32_e32 v144, 0xffff0000, v91
	v_lshl_add_u64 v[90:91], v[88:89], 0, v[136:137]
	v_fmac_f32_e32 v121, v64, v62
	v_and_b32_e32 v62, 0xffff0000, v93
	v_fmac_f32_e32 v144, v65, v62
	v_cvt_pk_bf16_f32 v62, v32, v120
	v_cvt_pk_bf16_f32 v63, v121, v144
	v_mov_b32_e32 v236, v62
	v_mov_b32_e32 v237, v63
	v_lshl_add_u64 v[234:235], v[90:91], 0, v[246:247]
	v_lshlrev_b32_e32 v32, 16, v96
	v_lshlrev_b32_e32 v91, 16, v94
	v_and_b32_e32 v64, 0xffff0000, v96
	v_fmac_f32_e32 v32, v58, v91
	v_and_b32_e32 v58, 0xffff0000, v94
	v_lshlrev_b32_e32 v65, 16, v97
	v_fmac_f32_e32 v64, v59, v58
	v_lshlrev_b32_e32 v58, 16, v95
	v_and_b32_e32 v90, 0xffff0000, v97
	v_fmac_f32_e32 v65, v60, v58
	v_and_b32_e32 v58, 0xffff0000, v95
	v_lshl_add_u64 v[62:63], v[88:89], 0, v[134:135]
	v_fmac_f32_e32 v90, v61, v58
	v_cvt_pk_bf16_f32 v58, v32, v64
	v_cvt_pk_bf16_f32 v59, v65, v90
	v_lshlrev_b32_e32 v32, 16, v102
	v_lshlrev_b32_e32 v65, 16, v100
	v_mov_b32_e32 v240, v58
	v_mov_b32_e32 v241, v59
	v_lshl_add_u64 v[244:245], v[62:63], 0, v[246:247]
	v_and_b32_e32 v62, 0xffff0000, v102
	v_fmac_f32_e32 v32, v54, v65
	v_and_b32_e32 v54, 0xffff0000, v100
	v_lshl_add_u64 v[58:59], s[82:83], 0, v[98:99]
	v_lshlrev_b32_e32 v63, 16, v103
	v_fmac_f32_e32 v62, v55, v54
	v_lshlrev_b32_e32 v54, 16, v101
	v_and_b32_e32 v64, 0xffff0000, v103
	v_lshl_add_u64 v[60:61], v[58:59], 0, v[136:137]
	v_fmac_f32_e32 v63, v56, v54
	v_and_b32_e32 v54, 0xffff0000, v101
	v_fmac_f32_e32 v64, v57, v54
	v_cvt_pk_bf16_f32 v54, v32, v62
	v_cvt_pk_bf16_f32 v55, v63, v64
	v_mov_b32_e32 v238, v54
	v_mov_b32_e32 v239, v55
	s_nop 1
	v_permlane16_swap_b32_e32 v236, v238
	v_permlane16_swap_b32_e32 v237, v239
	flat_store_dwordx4 v[234:235], v[236:239]
	v_lshlrev_b32_e32 v32, 16, v106
	v_lshlrev_b32_e32 v61, 16, v104
	v_and_b32_e32 v56, 0xffff0000, v106
	v_fmac_f32_e32 v32, v50, v61
	v_and_b32_e32 v50, 0xffff0000, v104
	v_lshlrev_b32_e32 v57, 16, v107
	v_fmac_f32_e32 v56, v51, v50
	v_lshlrev_b32_e32 v50, 16, v105
	v_and_b32_e32 v60, 0xffff0000, v107
	v_fmac_f32_e32 v57, v52, v50
	v_and_b32_e32 v50, 0xffff0000, v105
	v_lshl_add_u64 v[54:55], v[58:59], 0, v[134:135]
	v_fmac_f32_e32 v60, v53, v50
	v_cvt_pk_bf16_f32 v50, v32, v56
	v_cvt_pk_bf16_f32 v51, v57, v60
	v_lshlrev_b32_e32 v32, 16, v112
	v_lshlrev_b32_e32 v57, 16, v110
	v_mov_b32_e32 v242, v50
	v_mov_b32_e32 v243, v51
	s_nop 1
	v_permlane16_swap_b32_e32 v240, v242
	v_permlane16_swap_b32_e32 v241, v243
	flat_store_dwordx4 v[244:245], v[240:243]
	v_and_b32_e32 v54, 0xffff0000, v112
	v_fmac_f32_e32 v32, v46, v57
	v_and_b32_e32 v46, 0xffff0000, v110
	v_lshl_add_u64 v[50:51], s[82:83], 0, v[108:109]
	v_lshlrev_b32_e32 v55, 16, v113
	v_fmac_f32_e32 v54, v47, v46
	v_lshlrev_b32_e32 v46, 16, v111
	v_and_b32_e32 v56, 0xffff0000, v113
	v_lshl_add_u64 v[52:53], v[50:51], 0, v[136:137]
	v_fmac_f32_e32 v55, v48, v46
	v_and_b32_e32 v46, 0xffff0000, v111
	v_fmac_f32_e32 v56, v49, v46
	v_cvt_pk_bf16_f32 v46, v32, v54
	v_cvt_pk_bf16_f32 v47, v55, v56
	v_mov_b32_e32 v236, v46
	v_mov_b32_e32 v237, v47
	v_lshl_add_u64 v[234:235], v[52:53], 0, v[246:247]
	v_lshlrev_b32_e32 v32, 16, v116
	v_lshlrev_b32_e32 v53, 16, v114
	v_and_b32_e32 v48, 0xffff0000, v116
	v_fmac_f32_e32 v32, v42, v53
	v_and_b32_e32 v42, 0xffff0000, v114
	v_lshlrev_b32_e32 v49, 16, v117
	v_fmac_f32_e32 v48, v43, v42
	v_lshlrev_b32_e32 v42, 16, v115
	v_and_b32_e32 v52, 0xffff0000, v117
	v_fmac_f32_e32 v49, v44, v42
	v_and_b32_e32 v42, 0xffff0000, v115
	v_lshl_add_u64 v[46:47], v[50:51], 0, v[134:135]
	v_fmac_f32_e32 v52, v45, v42
	v_cvt_pk_bf16_f32 v42, v32, v48
	v_cvt_pk_bf16_f32 v43, v49, v52
	v_lshlrev_b32_e32 v32, 16, v124
	v_lshlrev_b32_e32 v49, 16, v122
	v_mov_b32_e32 v240, v42
	v_mov_b32_e32 v241, v43
	v_lshl_add_u64 v[244:245], v[46:47], 0, v[246:247]
	v_and_b32_e32 v46, 0xffff0000, v124
	v_fmac_f32_e32 v32, v38, v49
	v_and_b32_e32 v38, 0xffff0000, v122
	v_lshl_add_u64 v[42:43], s[82:83], 0, v[118:119]
	v_lshlrev_b32_e32 v47, 16, v125
	v_fmac_f32_e32 v46, v39, v38
	v_lshlrev_b32_e32 v38, 16, v123
	v_and_b32_e32 v48, 0xffff0000, v125
	v_lshl_add_u64 v[44:45], v[42:43], 0, v[136:137]
	v_fmac_f32_e32 v47, v40, v38
	v_and_b32_e32 v38, 0xffff0000, v123
	v_fmac_f32_e32 v48, v41, v38
	v_cvt_pk_bf16_f32 v38, v32, v46
	v_cvt_pk_bf16_f32 v39, v47, v48
	v_mov_b32_e32 v238, v38
	v_mov_b32_e32 v239, v39
	s_nop 1
	v_permlane16_swap_b32_e32 v236, v238
	v_permlane16_swap_b32_e32 v237, v239
	flat_store_dwordx4 v[234:235], v[236:239]
	v_lshlrev_b32_e32 v32, 16, v128
	v_lshlrev_b32_e32 v45, 16, v126
	v_and_b32_e32 v40, 0xffff0000, v128
	v_fmac_f32_e32 v32, v34, v45
	v_and_b32_e32 v34, 0xffff0000, v126
	v_lshlrev_b32_e32 v41, 16, v129
	v_fmac_f32_e32 v40, v35, v34
	v_lshlrev_b32_e32 v34, 16, v127
	v_and_b32_e32 v44, 0xffff0000, v129
	v_lshl_add_u64 v[38:39], v[42:43], 0, v[134:135]
	v_fmac_f32_e32 v41, v36, v34
	v_and_b32_e32 v34, 0xffff0000, v127
	v_fmac_f32_e32 v44, v37, v34
	v_cvt_pk_bf16_f32 v34, v32, v40
	v_cvt_pk_bf16_f32 v35, v41, v44
	v_mov_b32_e32 v242, v34
	v_mov_b32_e32 v243, v35
	s_nop 1
; #define EPI_HALF(AI, ...) _Pragma("unroll") for(int bj=0;bj<2;++bj) _Pragma("unroll") for(int m=0;m<4;++m) _Pragma("unroll") for(int n=0;n<2;++n) { \
;     const int ai=(AI); const int row=brow+ai*128+wr*64+m*16+fq*4; const int col=bcol+bj*128+wc*32+n*16+fr; \
;     f32x4& v=acc[ai][bj][m][n]; __VA_ARGS__ }
; DEVI void run_phase(const int ph, const Params& P, char* shmc, const int wave_u) {
;     ...
;       for (int ah = 0; ah < 2; ++ah) {
;         u32x2 gb[2][4][2], tq[2][4][2];
;         EPI_HALF(ah, { (void)v; gb[bj][m][n] = *reinterpret_cast<const u32x2*>(gates + (long)col * 4096 + 2048 + row);
;           tq[bj][m][n] = *reinterpret_cast<const u32x2*>(tmp5 + (long)col * 2048 + row); })
;         EPI_HALF(ah, { const u32x2 b = gb[bj][m][n]; const u32x2 tw = tq[bj][m][n];
;           const f32x4 t0 = {__uint_as_float(tw[0] << 16), __uint_as_float(tw[0] & 0xffff0000u), __uint_as_float(tw[1] << 16), __uint_as_float(tw[1] & 0xffff0000u)};
;           st_bf4(merged + (long)col * 2048 + row, t0[0] + v[0] * __uint_as_float(b[0] << 16), t0[1] + v[1] * __uint_as_float(b[0] & 0xffff0000u),
;                  t0[2] + v[2] * __uint_as_float(b[1] << 16), t0[3] + v[3] * __uint_as_float(b[1] & 0xffff0000u)); })
;       }
	v_permlane16_swap_b32_e32 v240, v242
	v_permlane16_swap_b32_e32 v241, v243
	flat_store_dwordx4 v[244:245], v[240:243]
	v_lshlrev_b32_e32 v32, 16, v140
	v_lshlrev_b32_e32 v39, 16, v138
	v_and_b32_e32 v36, 0xffff0000, v140
	v_fmac_f32_e32 v32, v28, v39
	v_and_b32_e32 v28, 0xffff0000, v138
	v_lshlrev_b32_e32 v37, 16, v141
	v_fmac_f32_e32 v36, v29, v28
	v_lshlrev_b32_e32 v28, 16, v139
	v_and_b32_e32 v38, 0xffff0000, v141
	v_lshl_add_u64 v[34:35], v[88:89], 0, v[132:133]
	v_fmac_f32_e32 v37, v30, v28
	v_and_b32_e32 v28, 0xffff0000, v139
	v_fmac_f32_e32 v38, v31, v28
	v_cvt_pk_bf16_f32 v28, v32, v36
	v_cvt_pk_bf16_f32 v29, v37, v38
	v_mov_b32_e32 v236, v28
	v_mov_b32_e32 v237, v29
	v_lshl_add_u64 v[234:235], v[34:35], 0, v[246:247]
	v_lshlrev_b32_e32 v30, 16, v150
	v_lshlrev_b32_e32 v35, 16, v142
	v_and_b32_e32 v31, 0xffff0000, v150
	v_fmac_f32_e32 v30, v24, v35
	v_and_b32_e32 v24, 0xffff0000, v142
	v_lshlrev_b32_e32 v32, 16, v151
	v_fmac_f32_e32 v31, v25, v24
	v_lshlrev_b32_e32 v24, 16, v143
	v_and_b32_e32 v34, 0xffff0000, v151
	v_fmac_f32_e32 v32, v26, v24
	v_and_b32_e32 v24, 0xffff0000, v143
	v_fmac_f32_e32 v34, v27, v24
	v_cvt_pk_bf16_f32 v24, v30, v31
	v_lshlrev_b32_e32 v26, 16, v152
	v_lshlrev_b32_e32 v30, 16, v86
	v_lshl_add_u64 v[28:29], v[88:89], 0, v[130:131]
	v_and_b32_e32 v27, 0xffff0000, v152
	v_fmac_f32_e32 v26, v20, v30
	v_and_b32_e32 v20, 0xffff0000, v86
	v_cvt_pk_bf16_f32 v25, v32, v34
	v_mov_b32_e32 v240, v24
	v_mov_b32_e32 v241, v25
	v_lshl_add_u64 v[244:245], v[28:29], 0, v[246:247]
	v_lshlrev_b32_e32 v28, 16, v153
	v_fmac_f32_e32 v27, v21, v20
	v_lshlrev_b32_e32 v20, 16, v87
	v_and_b32_e32 v29, 0xffff0000, v153
	v_fmac_f32_e32 v28, v22, v20
	v_and_b32_e32 v20, 0xffff0000, v87
	v_fmac_f32_e32 v29, v23, v20
	v_cvt_pk_bf16_f32 v20, v26, v27
	v_lshlrev_b32_e32 v22, 16, v84
	v_lshlrev_b32_e32 v26, 16, v82
	v_lshl_add_u64 v[24:25], v[58:59], 0, v[132:133]
	v_and_b32_e32 v23, 0xffff0000, v84
	v_fmac_f32_e32 v22, v16, v26
	v_and_b32_e32 v16, 0xffff0000, v82
	v_cvt_pk_bf16_f32 v21, v28, v29
	v_mov_b32_e32 v238, v20
	v_mov_b32_e32 v239, v21
	s_nop 1
	v_permlane16_swap_b32_e32 v236, v238
	v_permlane16_swap_b32_e32 v237, v239
	flat_store_dwordx4 v[234:235], v[236:239]
	v_lshlrev_b32_e32 v24, 16, v85
	v_fmac_f32_e32 v23, v17, v16
	v_lshlrev_b32_e32 v16, 16, v83
	v_and_b32_e32 v25, 0xffff0000, v85
	v_fmac_f32_e32 v24, v18, v16
	v_and_b32_e32 v16, 0xffff0000, v83
	v_fmac_f32_e32 v25, v19, v16
	v_cvt_pk_bf16_f32 v16, v22, v23
	v_lshlrev_b32_e32 v18, 16, v80
	v_lshlrev_b32_e32 v22, 16, v78
	v_lshl_add_u64 v[20:21], v[58:59], 0, v[130:131]
	v_and_b32_e32 v19, 0xffff0000, v80
	v_fmac_f32_e32 v18, v12, v22
	v_and_b32_e32 v12, 0xffff0000, v78
	v_cvt_pk_bf16_f32 v17, v24, v25
	v_mov_b32_e32 v242, v16
	v_mov_b32_e32 v243, v17
	s_nop 1
	v_permlane16_swap_b32_e32 v240, v242
	v_permlane16_swap_b32_e32 v241, v243
	flat_store_dwordx4 v[244:245], v[240:243]
	v_lshlrev_b32_e32 v20, 16, v81
	v_fmac_f32_e32 v19, v13, v12
	v_lshlrev_b32_e32 v12, 16, v79
	v_and_b32_e32 v21, 0xffff0000, v81
	v_fmac_f32_e32 v20, v14, v12
	v_and_b32_e32 v12, 0xffff0000, v79
	v_fmac_f32_e32 v21, v15, v12
	v_cvt_pk_bf16_f32 v12, v18, v19
	v_lshlrev_b32_e32 v14, 16, v76
	v_lshlrev_b32_e32 v18, 16, v74
	v_lshl_add_u64 v[16:17], v[50:51], 0, v[132:133]
	v_and_b32_e32 v15, 0xffff0000, v76
	v_fmac_f32_e32 v14, v8, v18
	v_and_b32_e32 v8, 0xffff0000, v74
	v_cvt_pk_bf16_f32 v13, v20, v21
	v_mov_b32_e32 v236, v12
	v_mov_b32_e32 v237, v13
	v_lshl_add_u64 v[234:235], v[16:17], 0, v[246:247]
	v_lshlrev_b32_e32 v16, 16, v77
	v_fmac_f32_e32 v15, v9, v8
	v_lshlrev_b32_e32 v8, 16, v75
	v_and_b32_e32 v17, 0xffff0000, v77
	v_fmac_f32_e32 v16, v10, v8
	v_and_b32_e32 v8, 0xffff0000, v75
	v_fmac_f32_e32 v17, v11, v8
	v_cvt_pk_bf16_f32 v8, v14, v15
	v_lshlrev_b32_e32 v10, 16, v72
	v_lshlrev_b32_e32 v14, 16, v70
	v_lshl_add_u64 v[12:13], v[50:51], 0, v[130:131]
	v_and_b32_e32 v11, 0xffff0000, v72
	v_fmac_f32_e32 v10, v4, v14
	v_and_b32_e32 v4, 0xffff0000, v70
	v_cvt_pk_bf16_f32 v9, v16, v17
	v_mov_b32_e32 v240, v8
	v_mov_b32_e32 v241, v9
	v_lshl_add_u64 v[244:245], v[12:13], 0, v[246:247]
	v_lshlrev_b32_e32 v12, 16, v73
	v_fmac_f32_e32 v11, v5, v4
	v_lshlrev_b32_e32 v4, 16, v71
	v_and_b32_e32 v13, 0xffff0000, v73
	v_fmac_f32_e32 v12, v6, v4
	v_and_b32_e32 v4, 0xffff0000, v71
	v_fmac_f32_e32 v13, v7, v4
	v_cvt_pk_bf16_f32 v4, v10, v11
	v_lshlrev_b32_e32 v6, 16, v68
	v_lshlrev_b32_e32 v10, 16, v66
	v_lshl_add_u64 v[8:9], v[42:43], 0, v[132:133]
	v_and_b32_e32 v7, 0xffff0000, v68
	v_fmac_f32_e32 v6, v0, v10
	v_and_b32_e32 v0, 0xffff0000, v66
	v_cvt_pk_bf16_f32 v5, v12, v13
	v_mov_b32_e32 v238, v4
	v_mov_b32_e32 v239, v5
	s_nop 1
	v_permlane16_swap_b32_e32 v236, v238
	v_permlane16_swap_b32_e32 v237, v239
	flat_store_dwordx4 v[234:235], v[236:239]
	v_lshlrev_b32_e32 v8, 16, v69
	v_fmac_f32_e32 v7, v1, v0
	v_lshlrev_b32_e32 v0, 16, v67
	v_and_b32_e32 v9, 0xffff0000, v69
	v_lshl_add_u64 v[4:5], v[42:43], 0, v[130:131]
	v_fmac_f32_e32 v8, v2, v0
	v_and_b32_e32 v0, 0xffff0000, v67
	v_fmac_f32_e32 v9, v3, v0
	v_cvt_pk_bf16_f32 v0, v6, v7
	v_cvt_pk_bf16_f32 v1, v8, v9
	v_mov_b32_e32 v242, v0
	v_mov_b32_e32 v243, v1
	s_nop 1
	v_permlane16_swap_b32_e32 v240, v242
	v_permlane16_swap_b32_e32 v241, v243
	flat_store_dwordx4 v[244:245], v[240:243]
	s_cbranch_scc1 .LBB0_204

; #define EPI_HALF(AI, ...) _Pragma("unroll") for(int bj=0;bj<2;++bj) _Pragma("unroll") for(int m=0;m<4;++m) _Pragma("unroll") for(int n=0;n<2;++n) { \
;     const int ai=(AI); const int row=brow+ai*128+wr*64+m*16+fq*4; const int col=bcol+bj*128+wc*32+n*16+fr; \
;     f32x4& v=acc[ai][bj][m][n]; __VA_ARGS__ }
; DEVI void run_phase(const int ph, const Params& P, char* shmc, const int wave_u) {
;     ...
;       { GEMM_IDS
; #pragma unroll
;       for (int ah = 0; ah < 2; ++ah) {
;         u32x2 ga[2][4][2];
;         EPI_HALF(ah, { (void)v; ga[bj][m][n] = *reinterpret_cast<const u32x2*>(gates + (long)col * 4096 + row); })
;         EPI_HALF(ah, { const u32x2 a = ga[bj][m][n];
;           st_bf4(tmp5 + (long)col * 2048 + row, v[0] * __uint_as_float(a[0] << 16), v[1] * __uint_as_float(a[0] & 0xffff0000u),
;                  v[2] * __uint_as_float(a[1] << 16), v[3] * __uint_as_float(a[1] & 0xffff0000u)); })
;       }
.LBB0_224:
	s_or_b64 exec, exec, s[70:71]
	v_mbcnt_lo_u32_b32 v224, -1, 0
	v_mbcnt_hi_u32_b32 v224, -1, v224
	v_bfe_u32 v224, v224, 4, 1
	v_mul_u32_u24_e32 v224, 24, v224
	v_mov_b32_e32 v225, 0
	v_mbcnt_lo_u32_b32 v32, -1, 0
	v_mbcnt_hi_u32_b32 v32, -1, v32
	v_readlane_b32 s16, v255, 13
	v_or_b32_e32 v130, s5, v32
	v_ashrrev_i32_e32 v132, 2, v130
	v_and_b32_e32 v132, 0xffffffc0, v132
	v_and_b32_e32 v131, 15, v32
	v_add_u32_e32 v132, s6, v132
	v_lshrrev_b32_e32 v32, 2, v32
	v_and_or_b32 v136, v32, 12, v132
	v_lshrrev_b32_e32 v32, 1, v130
	v_and_b32_e32 v32, 0x60, v32
	v_or3_b32 v132, v131, v32, s0
	v_ashrrev_i32_e32 v137, 31, v136
	v_lshlrev_b64 v[178:179], 1, v[136:137]
	v_readlane_b32 s17, v255, 14
	v_ashrrev_i32_e32 v133, 31, v132
	v_lshlrev_b64 v[130:131], 13, v[132:133]
	v_lshl_add_u64 v[142:143], s[16:17], 0, v[178:179]
	v_lshl_add_u64 v[138:139], v[142:143], 0, v[130:131]
	v_or_b32_e32 v194, 16, v132
	flat_load_dwordx2 v[192:193], v[138:139]
	v_ashrrev_i32_e32 v195, 31, v194
	v_lshlrev_b64 v[134:135], 13, v[194:195]
	v_lshl_add_u64 v[140:141], v[142:143], 0, v[134:135]
	flat_load_dwordx2 v[196:197], v[140:141]
	flat_load_dwordx2 v[182:183], v[138:139] offset:32
	flat_load_dwordx2 v[176:177], v[140:141] offset:32
	flat_load_dwordx2 v[170:171], v[138:139] offset:64
	flat_load_dwordx2 v[164:165], v[140:141] offset:64
	flat_load_dwordx2 v[156:157], v[138:139] offset:96
	flat_load_dwordx2 v[152:153], v[140:141] offset:96
	v_or_b32_e32 v162, 0x80, v132
	v_ashrrev_i32_e32 v163, 31, v162
	v_lshlrev_b64 v[138:139], 13, v[162:163]
	v_lshl_add_u64 v[148:149], v[142:143], 0, v[138:139]
	flat_load_dwordx2 v[158:159], v[148:149]
	v_or_b32_e32 v166, 0x90, v132
	v_ashrrev_i32_e32 v167, 31, v166
	v_lshlrev_b64 v[140:141], 13, v[166:167]
	v_lshl_add_u64 v[142:143], v[142:143], 0, v[140:141]
	flat_load_dwordx2 v[172:173], v[142:143]
	flat_load_dwordx2 v[168:169], v[148:149] offset:32
	flat_load_dwordx2 v[160:161], v[142:143] offset:32
	flat_load_dwordx2 v[154:155], v[148:149] offset:64
	flat_load_dwordx2 v[150:151], v[142:143] offset:64
	s_nop 0
	flat_load_dwordx2 v[148:149], v[148:149] offset:96
	s_nop 0
	flat_load_dwordx2 v[142:143], v[142:143] offset:96
	v_lshl_add_u64 v[178:179], s[84:85], 0, v[178:179]
	v_lshlrev_b64 v[132:133], 12, v[132:133]
	v_lshl_add_u64 v[198:199], v[178:179], 0, v[132:133]
	v_or_b32_e32 v180, 16, v136
	v_ashrrev_i32_e32 v181, 31, v180
	v_or_b32_e32 v174, 32, v136
	v_ashrrev_i32_e32 v175, 31, v174
	v_or_b32_e32 v144, 48, v136
	v_ashrrev_i32_e32 v145, 31, v144
	s_add_u32 s70, s68, 0x80800
	s_addc_u32 s71, s69, 0
	s_waitcnt vmcnt(0) lgkmcnt(0)
	v_lshlrev_b32_e32 v32, 16, v192
	v_mul_f32_e32 v32, v126, v32
	v_and_b32_e32 v126, 0xffff0000, v192
	v_mul_f32_e32 v126, v127, v126
	v_cvt_pk_bf16_f32 v126, v32, v126
	v_lshlrev_b32_e32 v32, 16, v196
	v_lshlrev_b32_e32 v127, 16, v193
	v_mul_f32_e32 v32, v122, v32
	v_and_b32_e32 v122, 0xffff0000, v196
	v_mul_f32_e32 v127, v128, v127
	v_and_b32_e32 v128, 0xffff0000, v193
	v_mul_f32_e32 v122, v123, v122
	v_mul_f32_e32 v128, v129, v128
	v_cvt_pk_bf16_f32 v127, v127, v128
	v_mov_b32_e32 v200, v126
	v_mov_b32_e32 v201, v127
	v_lshl_add_u64 v[216:217], v[198:199], 0, v[224:225]
	v_cvt_pk_bf16_f32 v122, v32, v122
	v_lshlrev_b32_e32 v32, 16, v182
	v_lshlrev_b64 v[126:127], 12, v[194:195]
	v_lshlrev_b32_e32 v123, 16, v197
	v_mul_f32_e32 v32, v118, v32
	v_and_b32_e32 v118, 0xffff0000, v182
	v_lshl_add_u64 v[128:129], v[178:179], 0, v[126:127]
	v_mul_f32_e32 v123, v124, v123
	v_and_b32_e32 v124, 0xffff0000, v197
	v_mul_f32_e32 v118, v119, v118
	v_mul_f32_e32 v124, v125, v124
	v_cvt_pk_bf16_f32 v123, v123, v124
	v_mov_b32_e32 v204, v122
	v_mov_b32_e32 v205, v123
	v_lshl_add_u64 v[218:219], v[128:129], 0, v[224:225]
	v_cvt_pk_bf16_f32 v118, v32, v118
	v_lshlrev_b32_e32 v32, 16, v176
	v_lshl_add_u64 v[124:125], s[84:85], 0, v[132:133]
	v_lshlrev_b64 v[122:123], 1, v[180:181]
	v_lshlrev_b32_e32 v119, 16, v183
	v_mul_f32_e32 v32, v114, v32
	v_and_b32_e32 v114, 0xffff0000, v176
	v_lshl_add_u64 v[128:129], v[124:125], 0, v[122:123]
	v_mul_f32_e32 v119, v120, v119
	v_and_b32_e32 v120, 0xffff0000, v183
	v_mul_f32_e32 v114, v115, v114
	v_mul_f32_e32 v120, v121, v120
	v_cvt_pk_bf16_f32 v119, v119, v120
	v_mov_b32_e32 v202, v118
	v_mov_b32_e32 v203, v119
	s_nop 1
	v_permlane16_swap_b32_e32 v200, v202
	v_permlane16_swap_b32_e32 v201, v203
	flat_store_dwordx4 v[216:217], v[200:203]
	v_cvt_pk_bf16_f32 v114, v32, v114
	v_lshlrev_b32_e32 v32, 16, v170
	v_lshl_add_u64 v[118:119], s[84:85], 0, v[126:127]
	v_lshlrev_b32_e32 v115, 16, v177
	v_mul_f32_e32 v32, v110, v32
	v_and_b32_e32 v110, 0xffff0000, v170
	v_lshl_add_u64 v[120:121], v[118:119], 0, v[122:123]
	v_mul_f32_e32 v115, v116, v115
	v_and_b32_e32 v116, 0xffff0000, v177
	v_mul_f32_e32 v110, v111, v110
	v_mul_f32_e32 v116, v117, v116
	v_cvt_pk_bf16_f32 v115, v115, v116
	v_mov_b32_e32 v206, v114
	v_mov_b32_e32 v207, v115
	s_nop 1
	v_permlane16_swap_b32_e32 v204, v206
	v_permlane16_swap_b32_e32 v205, v207
	flat_store_dwordx4 v[218:219], v[204:207]
	v_cvt_pk_bf16_f32 v110, v32, v110
	v_lshlrev_b32_e32 v32, 16, v164
	v_lshlrev_b64 v[114:115], 1, v[174:175]
	v_lshlrev_b32_e32 v111, 16, v171
	v_mul_f32_e32 v32, v106, v32
	v_and_b32_e32 v106, 0xffff0000, v164
	v_lshl_add_u64 v[116:117], v[124:125], 0, v[114:115]
	v_mul_f32_e32 v111, v112, v111
	v_and_b32_e32 v112, 0xffff0000, v171
	v_mul_f32_e32 v106, v107, v106
	v_mul_f32_e32 v112, v113, v112
	v_cvt_pk_bf16_f32 v111, v111, v112
	v_mov_b32_e32 v208, v110
	v_mov_b32_e32 v209, v111
	v_lshl_add_u64 v[220:221], v[116:117], 0, v[224:225]
	v_cvt_pk_bf16_f32 v106, v32, v106
	v_lshlrev_b32_e32 v32, 16, v156
; #define EPI_HALF(AI, ...) _Pragma("unroll") for(int bj=0;bj<2;++bj) _Pragma("unroll") for(int m=0;m<4;++m) _Pragma("unroll") for(int n=0;n<2;++n) { \
;     const int ai=(AI); const int row=brow+ai*128+wr*64+m*16+fq*4; const int col=bcol+bj*128+wc*32+n*16+fr; \
;     f32x4& v=acc[ai][bj][m][n]; __VA_ARGS__ }
; DEVI void run_phase(const int ph, const Params& P, char* shmc, const int wave_u) {
;     ...
;       { GEMM_IDS
; #pragma unroll
;       for (int ah = 0; ah < 2; ++ah) {
;         u32x2 ga[2][4][2];
;         EPI_HALF(ah, { (void)v; ga[bj][m][n] = *reinterpret_cast<const u32x2*>(gates + (long)col * 4096 + row); })
;         EPI_HALF(ah, { const u32x2 a = ga[bj][m][n];
;           st_bf4(tmp5 + (long)col * 2048 + row, v[0] * __uint_as_float(a[0] << 16), v[1] * __uint_as_float(a[0] & 0xffff0000u),
;                  v[2] * __uint_as_float(a[1] << 16), v[3] * __uint_as_float(a[1] & 0xffff0000u)); })
;       }
	v_lshlrev_b32_e32 v107, 16, v165
	v_mul_f32_e32 v32, v102, v32
	v_and_b32_e32 v102, 0xffff0000, v156
	v_lshl_add_u64 v[110:111], v[118:119], 0, v[114:115]
	v_mul_f32_e32 v107, v108, v107
	v_and_b32_e32 v108, 0xffff0000, v165
	v_mul_f32_e32 v102, v103, v102
	v_mul_f32_e32 v108, v109, v108
	v_cvt_pk_bf16_f32 v107, v107, v108
	v_mov_b32_e32 v212, v106
	v_mov_b32_e32 v213, v107
	v_lshl_add_u64 v[222:223], v[110:111], 0, v[224:225]
	v_cvt_pk_bf16_f32 v102, v32, v102
	v_lshlrev_b32_e32 v32, 16, v152
	v_lshlrev_b64 v[106:107], 1, v[144:145]
	v_lshlrev_b32_e32 v103, 16, v157
	v_mul_f32_e32 v32, v98, v32
	v_and_b32_e32 v98, 0xffff0000, v152
	v_lshl_add_u64 v[108:109], v[124:125], 0, v[106:107]
	v_mul_f32_e32 v103, v104, v103
	v_and_b32_e32 v104, 0xffff0000, v157
	v_mul_f32_e32 v98, v99, v98
	v_mul_f32_e32 v104, v105, v104
	v_cvt_pk_bf16_f32 v103, v103, v104
	v_mov_b32_e32 v210, v102
	v_mov_b32_e32 v211, v103
	s_nop 1
	v_permlane16_swap_b32_e32 v208, v210
	v_permlane16_swap_b32_e32 v209, v211
	flat_store_dwordx4 v[220:221], v[208:211]
	v_cvt_pk_bf16_f32 v98, v32, v98
	v_lshlrev_b32_e32 v32, 16, v158
	v_lshlrev_b32_e32 v99, 16, v153
	v_mul_f32_e32 v32, v94, v32
	v_and_b32_e32 v94, 0xffff0000, v158
	v_lshl_add_u64 v[102:103], v[118:119], 0, v[106:107]
	v_mul_f32_e32 v99, v100, v99
	v_and_b32_e32 v100, 0xffff0000, v153
	v_mul_f32_e32 v94, v95, v94
	v_mul_f32_e32 v100, v101, v100
	v_cvt_pk_bf16_f32 v99, v99, v100
	v_mov_b32_e32 v214, v98
	v_mov_b32_e32 v215, v99
	s_nop 1
	v_permlane16_swap_b32_e32 v212, v214
	v_permlane16_swap_b32_e32 v213, v215
	flat_store_dwordx4 v[222:223], v[212:215]
	v_cvt_pk_bf16_f32 v94, v32, v94
	v_lshlrev_b32_e32 v32, 16, v172
	v_lshlrev_b64 v[98:99], 12, v[162:163]
	v_lshlrev_b32_e32 v95, 16, v159
	v_mul_f32_e32 v32, v90, v32
	v_and_b32_e32 v90, 0xffff0000, v172
	v_lshl_add_u64 v[100:101], v[178:179], 0, v[98:99]
	v_mul_f32_e32 v95, v96, v95
	v_and_b32_e32 v96, 0xffff0000, v159
	v_mul_f32_e32 v90, v91, v90
	v_mul_f32_e32 v96, v97, v96
	v_cvt_pk_bf16_f32 v95, v95, v96
	v_mov_b32_e32 v200, v94
	v_mov_b32_e32 v201, v95
	v_lshl_add_u64 v[216:217], v[100:101], 0, v[224:225]
	v_cvt_pk_bf16_f32 v90, v32, v90
	v_lshlrev_b32_e32 v32, 16, v168
	v_lshlrev_b64 v[94:95], 12, v[166:167]
	v_lshlrev_b32_e32 v91, 16, v173
	v_mul_f32_e32 v32, v86, v32
	v_and_b32_e32 v86, 0xffff0000, v168
	v_lshl_add_u64 v[96:97], v[178:179], 0, v[94:95]
	v_mul_f32_e32 v91, v92, v91
	v_and_b32_e32 v92, 0xffff0000, v173
	v_mul_f32_e32 v86, v87, v86
	v_mul_f32_e32 v92, v93, v92
	v_cvt_pk_bf16_f32 v91, v91, v92
	v_mov_b32_e32 v204, v90
	v_mov_b32_e32 v205, v91
	v_lshl_add_u64 v[218:219], v[96:97], 0, v[224:225]
	v_cvt_pk_bf16_f32 v86, v32, v86
	v_lshlrev_b32_e32 v32, 16, v160
	v_lshl_add_u64 v[90:91], s[84:85], 0, v[98:99]
	v_lshlrev_b32_e32 v87, 16, v169
	v_mul_f32_e32 v32, v82, v32
	v_and_b32_e32 v82, 0xffff0000, v160
	v_lshl_add_u64 v[92:93], v[90:91], 0, v[122:123]
	v_mul_f32_e32 v87, v88, v87
	v_and_b32_e32 v88, 0xffff0000, v169
	v_mul_f32_e32 v82, v83, v82
	v_mul_f32_e32 v88, v89, v88
	v_cvt_pk_bf16_f32 v87, v87, v88
	v_mov_b32_e32 v202, v86
	v_mov_b32_e32 v203, v87
	s_nop 1
	v_permlane16_swap_b32_e32 v200, v202
	v_permlane16_swap_b32_e32 v201, v203
	flat_store_dwordx4 v[216:217], v[200:203]
	v_cvt_pk_bf16_f32 v82, v32, v82
	v_lshlrev_b32_e32 v32, 16, v154
	v_lshl_add_u64 v[86:87], s[84:85], 0, v[94:95]
	v_lshlrev_b32_e32 v83, 16, v161
	v_mul_f32_e32 v32, v78, v32
	v_and_b32_e32 v78, 0xffff0000, v154
	v_lshl_add_u64 v[88:89], v[86:87], 0, v[122:123]
	v_mul_f32_e32 v83, v84, v83
	v_and_b32_e32 v84, 0xffff0000, v161
	v_mul_f32_e32 v78, v79, v78
	v_mul_f32_e32 v84, v85, v84
	v_cvt_pk_bf16_f32 v83, v83, v84
	v_mov_b32_e32 v206, v82
	v_mov_b32_e32 v207, v83
	s_nop 1
	v_permlane16_swap_b32_e32 v204, v206
	v_permlane16_swap_b32_e32 v205, v207
	flat_store_dwordx4 v[218:219], v[204:207]
	v_cvt_pk_bf16_f32 v78, v32, v78
	v_lshlrev_b32_e32 v32, 16, v150
	v_lshlrev_b32_e32 v79, 16, v155
	v_mul_f32_e32 v32, v74, v32
	v_and_b32_e32 v74, 0xffff0000, v150
	v_lshl_add_u64 v[82:83], v[90:91], 0, v[114:115]
	v_mul_f32_e32 v79, v80, v79
	v_and_b32_e32 v80, 0xffff0000, v155
	v_mul_f32_e32 v74, v75, v74
	v_mul_f32_e32 v80, v81, v80
	v_cvt_pk_bf16_f32 v79, v79, v80
	v_mov_b32_e32 v208, v78
	v_mov_b32_e32 v209, v79
	v_lshl_add_u64 v[220:221], v[82:83], 0, v[224:225]
	v_cvt_pk_bf16_f32 v74, v32, v74
	v_lshlrev_b32_e32 v32, 16, v148
	v_lshlrev_b32_e32 v75, 16, v151
	v_mul_f32_e32 v32, v70, v32
	v_and_b32_e32 v70, 0xffff0000, v148
	v_lshl_add_u64 v[78:79], v[86:87], 0, v[114:115]
	v_mul_f32_e32 v75, v76, v75
	v_and_b32_e32 v76, 0xffff0000, v151
	v_mul_f32_e32 v70, v71, v70
	v_mul_f32_e32 v76, v77, v76
	v_cvt_pk_bf16_f32 v75, v75, v76
	v_mov_b32_e32 v212, v74
	v_mov_b32_e32 v213, v75
	v_lshl_add_u64 v[222:223], v[78:79], 0, v[224:225]
	v_lshlrev_b32_e32 v71, 16, v149
	v_cvt_pk_bf16_f32 v70, v32, v70
	v_lshlrev_b32_e32 v32, 16, v142
	v_mul_f32_e32 v71, v72, v71
	v_and_b32_e32 v72, 0xffff0000, v149
	v_mul_f32_e32 v32, v66, v32
	v_and_b32_e32 v66, 0xffff0000, v142
	v_lshl_add_u64 v[74:75], v[90:91], 0, v[106:107]
	v_mul_f32_e32 v72, v73, v72
	v_cvt_pk_bf16_f32 v71, v71, v72
	v_mul_f32_e32 v66, v67, v66
	v_lshlrev_b32_e32 v67, 16, v143
	v_mov_b32_e32 v210, v70
	v_mov_b32_e32 v211, v71
	s_nop 1
	v_permlane16_swap_b32_e32 v208, v210
	v_permlane16_swap_b32_e32 v209, v211
	flat_store_dwordx4 v[220:221], v[208:211]
	v_lshl_add_u64 v[70:71], v[86:87], 0, v[106:107]
	v_mul_f32_e32 v67, v68, v67
	v_and_b32_e32 v68, 0xffff0000, v143
	v_cvt_pk_bf16_f32 v66, v32, v66
	v_mul_f32_e32 v68, v69, v68
	v_cvt_pk_bf16_f32 v67, v67, v68
	v_mov_b32_e32 v214, v66
	v_mov_b32_e32 v215, v67
	s_nop 1
; #define EPI_HALF(AI, ...) _Pragma("unroll") for(int bj=0;bj<2;++bj) _Pragma("unroll") for(int m=0;m<4;++m) _Pragma("unroll") for(int n=0;n<2;++n) { \
;     const int ai=(AI); const int row=brow+ai*128+wr*64+m*16+fq*4; const int col=bcol+bj*128+wc*32+n*16+fr; \
;     f32x4& v=acc[ai][bj][m][n]; __VA_ARGS__ }
; DEVI void run_phase(const int ph, const Params& P, char* shmc, const int wave_u) {
;     ...
;       { GEMM_IDS
; #pragma unroll
;       for (int ah = 0; ah < 2; ++ah) {
;         u32x2 ga[2][4][2];
;         EPI_HALF(ah, { (void)v; ga[bj][m][n] = *reinterpret_cast<const u32x2*>(gates + (long)col * 4096 + row); })
;         EPI_HALF(ah, { const u32x2 a = ga[bj][m][n];
;           st_bf4(tmp5 + (long)col * 2048 + row, v[0] * __uint_as_float(a[0] << 16), v[1] * __uint_as_float(a[0] & 0xffff0000u),
;                  v[2] * __uint_as_float(a[1] << 16), v[3] * __uint_as_float(a[1] & 0xffff0000u)); })
;       }
	v_permlane16_swap_b32_e32 v212, v214
	v_permlane16_swap_b32_e32 v213, v215
	flat_store_dwordx4 v[222:223], v[212:215]
	v_add_u32_e32 v66, 0x80, v136
	v_ashrrev_i32_e32 v67, 31, v66
	v_lshlrev_b64 v[66:67], 1, v[66:67]
	v_lshl_add_u64 v[72:73], s[16:17], 0, v[66:67]
	v_lshl_add_u64 v[74:75], v[72:73], 0, v[130:131]
	flat_load_dwordx2 v[74:75], v[74:75]
	v_add_u32_e32 v78, 0x90, v136
	v_lshl_add_u64 v[76:77], v[72:73], 0, v[134:135]
	v_ashrrev_i32_e32 v79, 31, v78
	flat_load_dwordx2 v[76:77], v[76:77]
	v_lshlrev_b64 v[78:79], 1, v[78:79]
	v_lshl_add_u64 v[80:81], s[16:17], 0, v[78:79]
	v_lshl_add_u64 v[82:83], v[80:81], 0, v[130:131]
	flat_load_dwordx2 v[82:83], v[82:83]
	v_add_u32_e32 v86, 0xa0, v136
	v_lshl_add_u64 v[84:85], v[80:81], 0, v[134:135]
	v_ashrrev_i32_e32 v87, 31, v86
	flat_load_dwordx2 v[84:85], v[84:85]
	v_lshlrev_b64 v[86:87], 1, v[86:87]
	v_lshl_add_u64 v[88:89], s[16:17], 0, v[86:87]
	v_lshl_add_u64 v[90:91], v[88:89], 0, v[130:131]
	flat_load_dwordx2 v[90:91], v[90:91]
	v_add_u32_e32 v68, 0xb0, v136
	v_ashrrev_i32_e32 v69, 31, v68
	v_lshl_add_u64 v[92:93], v[88:89], 0, v[134:135]
	v_lshlrev_b64 v[68:69], 1, v[68:69]
	flat_load_dwordx2 v[92:93], v[92:93]
	v_lshl_add_u64 v[70:71], s[16:17], 0, v[68:69]
	v_lshl_add_u64 v[96:97], v[70:71], 0, v[130:131]
	flat_load_dwordx2 v[96:97], v[96:97]
	v_lshl_add_u64 v[100:101], v[70:71], 0, v[134:135]
	flat_load_dwordx2 v[100:101], v[100:101]
	v_lshl_add_u64 v[102:103], v[72:73], 0, v[138:139]
	flat_load_dwordx2 v[102:103], v[102:103]
	v_lshl_add_u64 v[72:73], v[72:73], 0, v[140:141]
	flat_load_dwordx2 v[72:73], v[72:73]
	v_lshl_add_u64 v[104:105], v[80:81], 0, v[138:139]
	flat_load_dwordx2 v[104:105], v[104:105]
	v_lshl_add_u64 v[80:81], v[80:81], 0, v[140:141]
	v_lshl_add_u64 v[106:107], v[88:89], 0, v[138:139]
	v_lshl_add_u64 v[88:89], v[88:89], 0, v[140:141]
	flat_load_dwordx2 v[88:89], v[88:89]
	v_lshl_add_u64 v[108:109], v[70:71], 0, v[138:139]
	flat_load_dwordx2 v[80:81], v[80:81]
	v_lshl_add_u64 v[70:71], v[70:71], 0, v[140:141]
	flat_load_dwordx2 v[106:107], v[106:107]
	v_lshl_add_u64 v[66:67], s[84:85], 0, v[66:67]
	flat_load_dwordx2 v[108:109], v[108:109]
	v_lshl_add_u64 v[110:111], v[66:67], 0, v[132:133]
	flat_load_dwordx2 v[70:71], v[70:71]
	s_mov_b64 s[16:17], 0x800
	v_mov_b32_e32 v131, v33
	s_waitcnt vmcnt(0) lgkmcnt(0)
	v_lshlrev_b32_e32 v32, 16, v74
	v_mul_f32_e32 v32, v62, v32
	v_and_b32_e32 v62, 0xffff0000, v74
	v_mul_f32_e32 v62, v63, v62
	v_cvt_pk_bf16_f32 v62, v32, v62
	v_lshlrev_b32_e32 v32, 16, v76
	v_lshlrev_b32_e32 v63, 16, v75
	v_mul_f32_e32 v32, v58, v32
	v_and_b32_e32 v58, 0xffff0000, v76
	v_mul_f32_e32 v63, v64, v63
	v_and_b32_e32 v64, 0xffff0000, v75
	v_mul_f32_e32 v58, v59, v58
	v_mul_f32_e32 v64, v65, v64
	v_cvt_pk_bf16_f32 v63, v63, v64
	v_mov_b32_e32 v200, v62
	v_mov_b32_e32 v201, v63
	v_lshl_add_u64 v[216:217], v[110:111], 0, v[224:225]
	v_cvt_pk_bf16_f32 v58, v32, v58
	v_lshlrev_b32_e32 v32, 16, v82
	v_lshlrev_b32_e32 v59, 16, v77
	v_mul_f32_e32 v32, v54, v32
	v_and_b32_e32 v54, 0xffff0000, v82
	v_lshl_add_u64 v[62:63], v[66:67], 0, v[126:127]
	v_mul_f32_e32 v59, v60, v59
	v_and_b32_e32 v60, 0xffff0000, v77
	v_mul_f32_e32 v54, v55, v54
	v_mul_f32_e32 v60, v61, v60
	v_cvt_pk_bf16_f32 v59, v59, v60
	v_mov_b32_e32 v204, v58
	v_mov_b32_e32 v205, v59
	v_lshl_add_u64 v[218:219], v[62:63], 0, v[224:225]
	v_cvt_pk_bf16_f32 v54, v32, v54
	v_lshlrev_b32_e32 v32, 16, v84
	v_lshl_add_u64 v[58:59], s[84:85], 0, v[78:79]
	v_lshlrev_b32_e32 v55, 16, v83
	v_mul_f32_e32 v32, v50, v32
	v_and_b32_e32 v50, 0xffff0000, v84
	v_lshl_add_u64 v[60:61], v[58:59], 0, v[132:133]
	v_mul_f32_e32 v55, v56, v55
	v_and_b32_e32 v56, 0xffff0000, v83
	v_mul_f32_e32 v50, v51, v50
	v_mul_f32_e32 v56, v57, v56
	v_cvt_pk_bf16_f32 v55, v55, v56
	v_mov_b32_e32 v202, v54
	v_mov_b32_e32 v203, v55
	s_nop 1
	v_permlane16_swap_b32_e32 v200, v202
	v_permlane16_swap_b32_e32 v201, v203
	flat_store_dwordx4 v[216:217], v[200:203]
	v_cvt_pk_bf16_f32 v50, v32, v50
	v_lshlrev_b32_e32 v32, 16, v90
	v_lshlrev_b32_e32 v51, 16, v85
	v_mul_f32_e32 v32, v46, v32
	v_and_b32_e32 v46, 0xffff0000, v90
	v_lshl_add_u64 v[54:55], v[58:59], 0, v[126:127]
	v_mul_f32_e32 v51, v52, v51
	v_and_b32_e32 v52, 0xffff0000, v85
	v_mul_f32_e32 v46, v47, v46
	v_mul_f32_e32 v52, v53, v52
	v_cvt_pk_bf16_f32 v51, v51, v52
	v_mov_b32_e32 v206, v50
	v_mov_b32_e32 v207, v51
	s_nop 1
	v_permlane16_swap_b32_e32 v204, v206
	v_permlane16_swap_b32_e32 v205, v207
	flat_store_dwordx4 v[218:219], v[204:207]
	v_cvt_pk_bf16_f32 v46, v32, v46
	v_lshlrev_b32_e32 v32, 16, v92
	v_lshl_add_u64 v[50:51], s[84:85], 0, v[86:87]
	v_lshlrev_b32_e32 v47, 16, v91
	v_mul_f32_e32 v32, v42, v32
	v_and_b32_e32 v42, 0xffff0000, v92
	v_lshl_add_u64 v[52:53], v[50:51], 0, v[132:133]
	v_mul_f32_e32 v47, v48, v47
	v_and_b32_e32 v48, 0xffff0000, v91
	v_mul_f32_e32 v42, v43, v42
	v_mul_f32_e32 v48, v49, v48
	v_cvt_pk_bf16_f32 v47, v47, v48
	v_mov_b32_e32 v208, v46
	v_mov_b32_e32 v209, v47
	v_lshl_add_u64 v[220:221], v[52:53], 0, v[224:225]
	v_cvt_pk_bf16_f32 v42, v32, v42
	v_lshlrev_b32_e32 v32, 16, v96
	v_lshlrev_b32_e32 v43, 16, v93
	v_mul_f32_e32 v32, v38, v32
	v_and_b32_e32 v38, 0xffff0000, v96
	v_lshl_add_u64 v[46:47], v[50:51], 0, v[126:127]
	v_mul_f32_e32 v43, v44, v43
	v_and_b32_e32 v44, 0xffff0000, v93
	v_mul_f32_e32 v38, v39, v38
	v_mul_f32_e32 v44, v45, v44
	v_cvt_pk_bf16_f32 v43, v43, v44
	v_mov_b32_e32 v212, v42
	v_mov_b32_e32 v213, v43
	v_lshl_add_u64 v[222:223], v[46:47], 0, v[224:225]
	v_cvt_pk_bf16_f32 v38, v32, v38
	v_lshlrev_b32_e32 v32, 16, v100
	v_lshl_add_u64 v[42:43], s[84:85], 0, v[68:69]
	v_lshlrev_b32_e32 v39, 16, v97
	v_mul_f32_e32 v32, v34, v32
; #define EPI_HALF(AI, ...) _Pragma("unroll") for(int bj=0;bj<2;++bj) _Pragma("unroll") for(int m=0;m<4;++m) _Pragma("unroll") for(int n=0;n<2;++n) { \
;     const int ai=(AI); const int row=brow+ai*128+wr*64+m*16+fq*4; const int col=bcol+bj*128+wc*32+n*16+fr; \
;     f32x4& v=acc[ai][bj][m][n]; __VA_ARGS__ }
; DEVI void run_phase(const int ph, const Params& P, char* shmc, const int wave_u) {
;     ...
;       { GEMM_IDS
; #pragma unroll
;       for (int ah = 0; ah < 2; ++ah) {
;         u32x2 ga[2][4][2];
;         EPI_HALF(ah, { (void)v; ga[bj][m][n] = *reinterpret_cast<const u32x2*>(gates + (long)col * 4096 + row); })
;         EPI_HALF(ah, { const u32x2 a = ga[bj][m][n];
;           st_bf4(tmp5 + (long)col * 2048 + row, v[0] * __uint_as_float(a[0] << 16), v[1] * __uint_as_float(a[0] & 0xffff0000u),
;                  v[2] * __uint_as_float(a[1] << 16), v[3] * __uint_as_float(a[1] & 0xffff0000u)); })
;       }
	v_and_b32_e32 v34, 0xffff0000, v100
	v_lshl_add_u64 v[44:45], v[42:43], 0, v[132:133]
	v_mul_f32_e32 v39, v40, v39
	v_and_b32_e32 v40, 0xffff0000, v97
	v_mul_f32_e32 v34, v35, v34
	v_mul_f32_e32 v40, v41, v40
	v_cvt_pk_bf16_f32 v39, v39, v40
	v_mov_b32_e32 v210, v38
	v_mov_b32_e32 v211, v39
	s_nop 1
	v_permlane16_swap_b32_e32 v208, v210
	v_permlane16_swap_b32_e32 v209, v211
	flat_store_dwordx4 v[220:221], v[208:211]
	v_cvt_pk_bf16_f32 v34, v32, v34
	v_lshlrev_b32_e32 v32, 16, v102
	v_mul_f32_e32 v28, v28, v32
	v_and_b32_e32 v32, 0xffff0000, v102
	v_lshlrev_b32_e32 v35, 16, v101
	v_mul_f32_e32 v29, v29, v32
	v_lshlrev_b32_e32 v32, 16, v103
	v_lshl_add_u64 v[38:39], v[42:43], 0, v[126:127]
	v_mul_f32_e32 v35, v36, v35
	v_and_b32_e32 v36, 0xffff0000, v101
	v_mul_f32_e32 v30, v30, v32
	v_and_b32_e32 v32, 0xffff0000, v103
	v_mul_f32_e32 v36, v37, v36
	v_cvt_pk_bf16_f32 v35, v35, v36
	v_mov_b32_e32 v214, v34
	v_mov_b32_e32 v215, v35
	s_nop 1
	v_permlane16_swap_b32_e32 v212, v214
	v_permlane16_swap_b32_e32 v213, v215
	flat_store_dwordx4 v[222:223], v[212:215]
	v_mul_f32_e32 v31, v31, v32
	v_cvt_pk_bf16_f32 v28, v28, v29
	v_cvt_pk_bf16_f32 v29, v30, v31
	v_lshlrev_b32_e32 v30, 16, v72
	v_mul_f32_e32 v24, v24, v30
	v_and_b32_e32 v30, 0xffff0000, v72
	v_mul_f32_e32 v25, v25, v30
	v_lshlrev_b32_e32 v30, 16, v73
	v_lshl_add_u64 v[34:35], v[66:67], 0, v[98:99]
	v_mul_f32_e32 v26, v26, v30
	v_and_b32_e32 v30, 0xffff0000, v73
	v_mov_b32_e32 v200, v28
	v_mov_b32_e32 v201, v29
	v_lshl_add_u64 v[216:217], v[34:35], 0, v[224:225]
	v_mul_f32_e32 v27, v27, v30
	v_cvt_pk_bf16_f32 v24, v24, v25
	v_cvt_pk_bf16_f32 v25, v26, v27
	v_lshlrev_b32_e32 v26, 16, v104
	v_mul_f32_e32 v20, v20, v26
	v_and_b32_e32 v26, 0xffff0000, v104
	v_mul_f32_e32 v21, v21, v26
	v_lshlrev_b32_e32 v26, 16, v105
	v_lshl_add_u64 v[28:29], v[66:67], 0, v[94:95]
	v_mul_f32_e32 v22, v22, v26
	v_and_b32_e32 v26, 0xffff0000, v105
	v_mov_b32_e32 v204, v24
	v_mov_b32_e32 v205, v25
	v_lshl_add_u64 v[218:219], v[28:29], 0, v[224:225]
	v_mul_f32_e32 v23, v23, v26
	v_cvt_pk_bf16_f32 v20, v20, v21
	v_cvt_pk_bf16_f32 v21, v22, v23
	v_lshlrev_b32_e32 v22, 16, v80
	v_mul_f32_e32 v16, v16, v22
	v_and_b32_e32 v22, 0xffff0000, v80
	v_mul_f32_e32 v17, v17, v22
	v_lshlrev_b32_e32 v22, 16, v81
	v_lshl_add_u64 v[24:25], v[58:59], 0, v[98:99]
	v_mul_f32_e32 v18, v18, v22
	v_and_b32_e32 v22, 0xffff0000, v81
	v_mov_b32_e32 v202, v20
	v_mov_b32_e32 v203, v21
	s_nop 1
	v_permlane16_swap_b32_e32 v200, v202
	v_permlane16_swap_b32_e32 v201, v203
	flat_store_dwordx4 v[216:217], v[200:203]
	v_mul_f32_e32 v19, v19, v22
	v_cvt_pk_bf16_f32 v16, v16, v17
	v_cvt_pk_bf16_f32 v17, v18, v19
	v_lshlrev_b32_e32 v18, 16, v106
	v_mul_f32_e32 v12, v12, v18
	v_and_b32_e32 v18, 0xffff0000, v106
	v_mul_f32_e32 v13, v13, v18
	v_lshlrev_b32_e32 v18, 16, v107
	v_lshl_add_u64 v[20:21], v[58:59], 0, v[94:95]
	v_mul_f32_e32 v14, v14, v18
	v_and_b32_e32 v18, 0xffff0000, v107
	v_mov_b32_e32 v206, v16
	v_mov_b32_e32 v207, v17
	s_nop 1
	v_permlane16_swap_b32_e32 v204, v206
	v_permlane16_swap_b32_e32 v205, v207
	flat_store_dwordx4 v[218:219], v[204:207]
	v_mul_f32_e32 v15, v15, v18
	v_cvt_pk_bf16_f32 v12, v12, v13
	v_cvt_pk_bf16_f32 v13, v14, v15
	v_lshlrev_b32_e32 v14, 16, v88
	v_mul_f32_e32 v8, v8, v14
	v_and_b32_e32 v14, 0xffff0000, v88
	v_mul_f32_e32 v9, v9, v14
	v_lshlrev_b32_e32 v14, 16, v89
	v_lshl_add_u64 v[16:17], v[50:51], 0, v[98:99]
	v_mul_f32_e32 v10, v10, v14
	v_and_b32_e32 v14, 0xffff0000, v89
	v_mov_b32_e32 v208, v12
	v_mov_b32_e32 v209, v13
	v_lshl_add_u64 v[220:221], v[16:17], 0, v[224:225]
	v_mul_f32_e32 v11, v11, v14
	v_cvt_pk_bf16_f32 v8, v8, v9
	v_cvt_pk_bf16_f32 v9, v10, v11
	v_lshlrev_b32_e32 v10, 16, v108
	v_mul_f32_e32 v4, v4, v10
	v_and_b32_e32 v10, 0xffff0000, v108
	v_mul_f32_e32 v5, v5, v10
	v_lshlrev_b32_e32 v10, 16, v109
	v_lshl_add_u64 v[12:13], v[50:51], 0, v[94:95]
	v_mul_f32_e32 v6, v6, v10
	v_and_b32_e32 v10, 0xffff0000, v109
	v_mov_b32_e32 v212, v8
	v_mov_b32_e32 v213, v9
	v_lshl_add_u64 v[222:223], v[12:13], 0, v[224:225]
	v_mul_f32_e32 v7, v7, v10
	v_cvt_pk_bf16_f32 v4, v4, v5
	v_cvt_pk_bf16_f32 v5, v6, v7
	v_lshlrev_b32_e32 v6, 16, v70
	v_mul_f32_e32 v0, v0, v6
	v_and_b32_e32 v6, 0xffff0000, v70
	v_lshl_add_u64 v[8:9], v[42:43], 0, v[98:99]
	v_mul_f32_e32 v1, v1, v6
	v_lshlrev_b32_e32 v6, 16, v71
	v_mov_b32_e32 v210, v4
	v_mov_b32_e32 v211, v5
	s_nop 1
	v_permlane16_swap_b32_e32 v208, v210
	v_permlane16_swap_b32_e32 v209, v211
	flat_store_dwordx4 v[220:221], v[208:211]
	v_lshl_add_u64 v[4:5], v[42:43], 0, v[94:95]
	v_mul_f32_e32 v2, v2, v6
	v_and_b32_e32 v6, 0xffff0000, v71
	v_cvt_pk_bf16_f32 v0, v0, v1
	v_mul_f32_e32 v3, v3, v6
	v_cvt_pk_bf16_f32 v1, v2, v3
	v_mov_b32_e32 v214, v0
	v_mov_b32_e32 v215, v1
	s_nop 1
	v_permlane16_swap_b32_e32 v212, v214
	v_permlane16_swap_b32_e32 v213, v215
	flat_store_dwordx4 v[222:223], v[212:215]
	v_mov_b32_e32 v0, v33
	v_mbcnt_lo_u32_b32 v10, -1, 0
	v_mbcnt_hi_u32_b32 v10, -1, v10
	s_waitcnt vmcnt(0)
;   #define STAGE(P,BASE,LD,br,kt) do{const char* _ub=(const char*)((BASE)+(long)(br)*(LD)+(long)(kt)*BK); \
;     for(int _i=0;_i<2;++_i){int _b=tidg*16+_i*8192;int _r,_c;stage_rc(_b,_r,_c); \
;       const unsigned _vo=(unsigned)(_r*(int)(LD)+_c)*2u; \
;       __builtin_amdgcn_global_load_lds((const unsigned*)(_ub+_vo), \
;         (unsigned*)((char*)(P)+_b),16,0,0);}}while(0)
;   #define WAIT_V(n) asm volatile("s_waitcnt vmcnt(" #n ")":::"memory")
;   #define BAR __builtin_amdgcn_s_barrier()
; DEVI void gemm_core(const bf16* __restrict__ A, const long lda, const bf16* __restrict__ Bt, const long ldb, const int K,
;                     acc_t& acc, bf16* shm, const int wave_u) {
;     ...
;   int tidg = get_tid(wave_u);
;   const int wid=tidg>>6,lane=tidg&63,wr=wid>>2,wc=wid&3,fr=lane&15,fq=lane>>4;
;   bf16x8 At[4][2],B0[2][2],B1[2][2];
;   const int nt=K/BK;
;   WAIT_V(0);
;   STAGE(SB(0,0),Bt,ldb,0,0); STAGE(SA(0,0),A,lda,0,0);
;   STAGE(SB(0,1),Bt,ldb,HALF,0); STAGE(SA(0,1),A,lda,HALF,0);
;   if(wr==1)BAR;
	s_nop 0
	v_or_b32_e32 v140, s5, v10
	v_bfe_i32 v2, v140, 27, 1
	v_lshlrev_b32_e32 v14, 4, v140
	v_lshrrev_b32_e32 v2, 22, v2
	v_add_u32_e32 v2, v14, v2
	v_and_b32_e32 v2, 0xfffffc00, v2
	v_sub_u32_e32 v2, v14, v2
	v_lshrrev_b32_e32 v3, 4, v2
	v_ashrrev_i32_e32 v1, 31, v140
	v_bitop3_b32 v2, v3, v2, 32 bitop3:0x6c
	v_lshrrev_b32_e32 v1, 26, v1
	v_ashrrev_i32_e32 v4, 31, v2
	v_add_u32_e32 v1, v140, v1
	v_lshrrev_b32_e32 v4, 26, v4
	v_ashrrev_i32_e32 v1, 6, v1
	v_add_u32_e32 v4, v2, v4
	v_lshlrev_b32_e32 v3, 3, v1
	v_ashrrev_i32_e32 v11, 6, v4
	v_and_b32_e32 v4, 0xc0, v4
	v_and_b32_e32 v3, 0xffff0, v3
	v_lshlrev_b32_e32 v5, 5, v1
	v_sub_u32_e32 v2, v2, v4
	v_add_u32_e32 v3, v11, v3
	v_and_b32_e32 v12, 32, v5
	v_ashrrev_i16_sdwa v2, v187, sext(v2) dst_sel:DWORD dst_unused:UNUSED_PAD src0_sel:DWORD src1_sel:BYTE_0
	v_bfe_i32 v13, v2, 0, 16
	v_lshl_or_b32 v2, v3, 11, v12
	v_add_lshl_u32 v32, v2, v13, 1
	v_add_u32_e32 v145, s33, v14
	v_lshl_add_u64 v[2:3], s[68:69], 0, v[32:33]
	v_readfirstlane_b32 s1, v145
	v_lshl_add_u64 v[4:5], v[2:3], 0, s[16:17]
	s_mov_b32 m0, s1
	v_add_u32_e32 v22, 0x2000, v14
	global_load_lds_dwordx4 v[4:5], off
	v_ashrrev_i32_e32 v4, 31, v22
	v_lshrrev_b32_e32 v4, 22, v4
	v_add_u32_e32 v4, v22, v4
	v_ashrrev_i32_e32 v15, 10, v4
	v_mul_i32_i24_e32 v4, 0x400, v15
	v_sub_u32_e32 v4, v22, v4
	v_lshrrev_b32_e32 v5, 4, v4
	v_bitop3_b32 v4, v5, v4, 32 bitop3:0x6c
	v_ashrrev_i32_e32 v6, 31, v4
	v_lshrrev_b32_e32 v6, 26, v6
	v_add_u32_e32 v6, v4, v6
	v_lshlrev_b32_e32 v5, 3, v15
	v_ashrrev_i32_e32 v16, 6, v6
	v_and_b32_e32 v6, 0xc0, v6
	v_and_b32_e32 v5, 0xffff0, v5
	v_lshlrev_b32_e32 v7, 5, v15
	v_sub_u32_e32 v4, v4, v6
	v_add_u32_e32 v5, v16, v5
	v_and_b32_e32 v17, 32, v7
	v_ashrrev_i16_sdwa v4, v187, sext(v4) dst_sel:DWORD dst_unused:UNUSED_PAD src0_sel:DWORD src1_sel:BYTE_0
	v_bfe_i32 v18, v4, 0, 16
	v_lshl_or_b32 v4, v5, 11, v17
	v_add_lshl_u32 v130, v4, v18, 1
	v_add_u32_e32 v8, s33, v22
	v_lshl_add_u64 v[4:5], s[68:69], 0, v[130:131]
	v_readfirstlane_b32 s1, v8
	v_lshl_add_u64 v[6:7], v[4:5], 0, s[16:17]
	s_mov_b32 m0, s1
	v_add_u32_e32 v149, 16, v14
	global_load_lds_dwordx4 v[6:7], off
	v_lshl_add_u64 v[6:7], s[8:9], 0, v[32:33]
	v_readfirstlane_b32 s1, v149
	v_lshl_add_u64 v[8:9], v[6:7], 0, s[16:17]
	s_mov_b32 m0, s1
	v_add_u32_e32 v150, 0x2000, v149
	global_load_lds_dwordx4 v[8:9], off
	v_lshl_add_u64 v[8:9], s[8:9], 0, v[130:131]
	v_readfirstlane_b32 s1, v150
	v_lshl_add_u64 v[20:21], v[8:9], 0, s[16:17]
	s_mov_b32 m0, s1
	v_add_u32_e32 v151, s74, v14
	global_load_lds_dwordx4 v[20:21], off
	v_readfirstlane_b32 s1, v151
	v_add_u32_e32 v20, s74, v22
	s_mov_b32 m0, s1
	v_readfirstlane_b32 s1, v20
	global_load_lds_dwordx4 v32, s[70:71]
	s_mov_b32 m0, s1
	v_add_u32_e32 v153, 0x4000, v149
	global_load_lds_dwordx4 v130, s[70:71]
	s_add_u32 s70, s8, 0x80800
	v_readfirstlane_b32 s1, v153
	v_add_u32_e32 v154, 0x6000, v149
	s_addc_u32 s71, s9, 0
	s_mov_b32 m0, s1
	v_readfirstlane_b32 s1, v154
	global_load_lds_dwordx4 v32, s[70:71]
	s_mov_b32 m0, s1
	v_ashrrev_i32_e32 v19, 8, v140
	global_load_lds_dwordx4 v130, s[70:71]
	v_cmp_eq_u32_e32 vcc, 1, v19
	s_and_saveexec_b64 s[70:71], vcc
	s_cbranch_execz .LBB0_226
	s_barrier

; template <bool MLA> ...
;     ...
;       const char* Ks = K_lds + buf * SHM_K + r32 * KP;
;       f32x16 p0, p1;
; #pragma unroll
;       for (int r = 0; r < 16; ++r) { p0[r] = 0.f; p1[r] = 0.f; }
; #pragma unroll
;       for (int d0 = 0; d0 < ND0; ++d0) { const int off = kq4[d0 & 3] + (d0 >> 2) * 128;
;         bf16x8 b0 = *reinterpret_cast<const bf16x8*>(Ks + off);
;         bf16x8 b1 = *reinterpret_cast<const bf16x8*>(Ks + off + 32 * KP);
;         p0 = __builtin_amdgcn_mfma_f32_32x32x16_bf16(b0, qr[d0], p0, 0, 0, 0);
;         p1 = __builtin_amdgcn_mfma_f32_32x32x16_bf16(b1, qr[d0], p1, 0, 0, 0); }
.LBB0_252:
	s_add_i32 s12, s0, 0x400
	v_cmp_lt_i32_e32 vcc, s12, v174
	s_and_saveexec_b64 s[12:13], vcc
	s_cbranch_execz .LBB0_249
	s_mul_i32 s38, s68, 0x6000
	v_add_u32_e32 v225, s38, v181
	v_add_u32_e32 v230, v225, v175
	ds_read_b128 v[66:69], v230 offset:32768
	ds_read_b128 v[82:85], v230 offset:45056
	v_add_u32_e32 v231, v225, v176
	ds_read_b128 v[226:229], v231 offset:32768
	v_add_u32_e32 v232, v225, v177
	v_add_u32_e32 v225, v225, v178
	s_add_i32 s38, s0, 0x440
	v_cmp_le_i32_e32 vcc, s38, v173
	s_waitcnt lgkmcnt(0)
	v_mfma_f32_32x32x16_bf16 v[66:81], v[66:69], v[98:101], 0
	v_mfma_f32_32x32x16_bf16 v[66:81], v[226:229], v[102:105], v[66:81]
	ds_read_b128 v[226:229], v231 offset:45056
	v_mfma_f32_32x32x16_bf16 v[82:97], v[82:85], v[98:101], 0
	s_waitcnt lgkmcnt(0)
	v_mfma_f32_32x32x16_bf16 v[82:97], v[226:229], v[102:105], v[82:97]
	ds_read_b128 v[226:229], v232 offset:32768
	s_waitcnt lgkmcnt(0)
	v_mfma_f32_32x32x16_bf16 v[66:81], v[226:229], v[106:109], v[66:81]
	ds_read_b128 v[226:229], v232 offset:45056
	s_waitcnt lgkmcnt(0)
	v_mfma_f32_32x32x16_bf16 v[82:97], v[226:229], v[106:109], v[82:97]
	ds_read_b128 v[226:229], v225 offset:32768
	s_waitcnt lgkmcnt(0)
	v_mfma_f32_32x32x16_bf16 v[66:81], v[226:229], v[110:113], v[66:81]
	ds_read_b128 v[226:229], v225 offset:45056
	s_waitcnt lgkmcnt(0)
	v_mfma_f32_32x32x16_bf16 v[82:97], v[226:229], v[110:113], v[82:97]
	ds_read_b128 v[226:229], v230 offset:32896
	s_waitcnt lgkmcnt(0)
	v_mfma_f32_32x32x16_bf16 v[66:81], v[226:229], v[114:117], v[66:81]
	ds_read_b128 v[226:229], v230 offset:45184
	s_waitcnt lgkmcnt(0)
	v_mfma_f32_32x32x16_bf16 v[82:97], v[226:229], v[114:117], v[82:97]
	ds_read_b128 v[226:229], v231 offset:32896
	s_waitcnt lgkmcnt(0)
	v_mfma_f32_32x32x16_bf16 v[66:81], v[226:229], v[118:121], v[66:81]
	ds_read_b128 v[226:229], v231 offset:45184
	s_waitcnt lgkmcnt(0)
	v_mfma_f32_32x32x16_bf16 v[82:97], v[226:229], v[118:121], v[82:97]
	ds_read_b128 v[226:229], v232 offset:32896
	s_waitcnt lgkmcnt(0)
	v_mfma_f32_32x32x16_bf16 v[66:81], v[226:229], v[122:125], v[66:81]
	ds_read_b128 v[226:229], v232 offset:45184
	s_waitcnt lgkmcnt(0)
	v_mfma_f32_32x32x16_bf16 v[82:97], v[226:229], v[122:125], v[82:97]
	ds_read_b128 v[226:229], v225 offset:32896
	s_waitcnt lgkmcnt(0)
	v_mfma_f32_32x32x16_bf16 v[66:81], v[226:229], v[126:129], v[66:81]
	ds_read_b128 v[226:229], v225 offset:45184
	s_waitcnt lgkmcnt(0)
	v_mfma_f32_32x32x16_bf16 v[82:97], v[226:229], v[126:129], v[82:97]
	ds_read_b128 v[226:229], v230 offset:33024
	s_waitcnt lgkmcnt(0)
	v_mfma_f32_32x32x16_bf16 v[66:81], v[226:229], v[130:133], v[66:81]
	ds_read_b128 v[226:229], v230 offset:45312
	s_waitcnt lgkmcnt(0)
	v_mfma_f32_32x32x16_bf16 v[82:97], v[226:229], v[130:133], v[82:97]
	ds_read_b128 v[226:229], v231 offset:33024
	s_waitcnt lgkmcnt(0)
	v_mfma_f32_32x32x16_bf16 v[66:81], v[226:229], v[134:137], v[66:81]
	ds_read_b128 v[226:229], v231 offset:45312
	s_waitcnt lgkmcnt(0)
	v_mfma_f32_32x32x16_bf16 v[82:97], v[226:229], v[134:137], v[82:97]
	ds_read_b128 v[226:229], v232 offset:33024
	s_waitcnt lgkmcnt(0)
	v_mfma_f32_32x32x16_bf16 v[66:81], v[226:229], v[138:141], v[66:81]
	ds_read_b128 v[226:229], v232 offset:45312
	s_waitcnt lgkmcnt(0)
	v_mfma_f32_32x32x16_bf16 v[82:97], v[226:229], v[138:141], v[82:97]
	ds_read_b128 v[226:229], v225 offset:33024
	s_waitcnt lgkmcnt(0)
	v_mfma_f32_32x32x16_bf16 v[66:81], v[226:229], v[142:145], v[66:81]
	ds_read_b128 v[226:229], v225 offset:45312
	s_waitcnt lgkmcnt(0)
	v_mfma_f32_32x32x16_bf16 v[82:97], v[226:229], v[142:145], v[82:97]
	s_and_saveexec_b64 s[38:39], vcc
	s_xor_b64 s[38:39], exec, s[38:39]
	s_cbranch_execz .LBB0_255
	s_nop 8
	v_max_f32_e32 v225, v82, v82
	v_max_f32_e32 v226, v66, v66
	v_max_f32_e32 v225, v226, v225
	v_max_f32_e32 v226, v83, v83
	v_max_f32_e32 v227, v67, v67
	v_max_f32_e32 v226, v227, v226
	s_mov_b32 s4, 0xff800000
	v_max3_f32 v225, v225, s4, v226
	v_max_f32_e32 v226, v84, v84
	v_max_f32_e32 v227, v68, v68
	v_max_f32_e32 v226, v227, v226
	v_max_f32_e32 v227, v85, v85
	v_max_f32_e32 v228, v69, v69
	v_max_f32_e32 v227, v228, v227
	v_max3_f32 v225, v225, v226, v227
	v_max_f32_e32 v226, v86, v86
	v_max_f32_e32 v227, v70, v70
	v_max_f32_e32 v226, v227, v226
	v_max_f32_e32 v227, v87, v87
	v_max_f32_e32 v228, v71, v71
	v_max_f32_e32 v227, v228, v227
	v_max3_f32 v225, v225, v226, v227
	v_max_f32_e32 v226, v88, v88
	v_max_f32_e32 v227, v72, v72
	v_max_f32_e32 v226, v227, v226
	v_max_f32_e32 v227, v89, v89
	v_max_f32_e32 v228, v73, v73
	v_max_f32_e32 v227, v228, v227
	v_max3_f32 v225, v225, v226, v227
	v_max_f32_e32 v226, v90, v90
	v_max_f32_e32 v227, v74, v74
	v_max_f32_e32 v226, v227, v226
	v_max_f32_e32 v227, v91, v91
	v_max_f32_e32 v228, v75, v75
	v_max_f32_e32 v227, v228, v227
	v_max3_f32 v225, v225, v226, v227
	v_max_f32_e32 v226, v92, v92
	v_max_f32_e32 v227, v76, v76
	v_max_f32_e32 v226, v227, v226
	v_max_f32_e32 v227, v93, v93
	v_max_f32_e32 v228, v77, v77
	v_max_f32_e32 v227, v228, v227
	v_max3_f32 v225, v225, v226, v227
	v_max_f32_e32 v226, v94, v94
	v_max_f32_e32 v227, v78, v78
	v_max_f32_e32 v226, v227, v226
	v_max_f32_e32 v227, v95, v95
	v_max_f32_e32 v228, v79, v79
	v_max_f32_e32 v227, v228, v227
	v_max3_f32 v225, v225, v226, v227
	v_max_f32_e32 v226, v96, v96
	v_max_f32_e32 v227, v80, v80
	v_max_f32_e32 v226, v227, v226
	v_max_f32_e32 v227, v97, v97
	v_max_f32_e32 v228, v81, v81
	v_max_f32_e32 v227, v228, v227
	v_max3_f32 v225, v225, v226, v227

; template <bool MLA> ...
;     ...
;       const char* Ks = K_lds + buf * SHM_K + r32 * KP;
;       f32x16 p0, p1;
; #pragma unroll
;       for (int r = 0; r < 16; ++r) { p0[r] = 0.f; p1[r] = 0.f; }
; #pragma unroll
;       for (int d0 = 0; d0 < ND0; ++d0) { const int off = kq4[d0 & 3] + (d0 >> 2) * 128;
;         bf16x8 b0 = *reinterpret_cast<const bf16x8*>(Ks + off);
;         bf16x8 b1 = *reinterpret_cast<const bf16x8*>(Ks + off + 32 * KP);
;         p0 = __builtin_amdgcn_mfma_f32_32x32x16_bf16(b0, qr[d0], p0, 0, 0, 0);
;         p1 = __builtin_amdgcn_mfma_f32_32x32x16_bf16(b1, qr[d0], p1, 0, 0, 0); }
.LBB0_302:
	v_cmp_lt_i32_e64 s[0:1], s39, v180
	s_and_saveexec_b64 s[8:9], s[0:1]
	s_cbranch_execz .LBB0_299
	s_lshl_b32 s69, s12, 14
	v_add_u32_e32 v32, s69, v195
	v_add_u32_e32 v42, v32, v181
	ds_read_b128 v[34:37], v42 offset:32768
	ds_read_b128 v[38:41], v42 offset:40960
	v_add_u32_e32 v43, v32, v182
	v_add_u32_e32 v44, v32, v193
	v_add_u32_e32 v32, v32, v194
	s_waitcnt lgkmcnt(0)
	v_mfma_f32_32x32x16_bf16 v[80:95], v[34:37], v[112:115], 0
	v_cmp_le_i32_e64 s[0:1], s39, v196
	v_mfma_f32_32x32x16_bf16 v[96:111], v[38:41], v[112:115], 0
	ds_read_b128 v[34:37], v43 offset:32768
	ds_read_b128 v[38:41], v43 offset:40960
	s_waitcnt lgkmcnt(0)
	v_mfma_f32_32x32x16_bf16 v[80:95], v[34:37], v[116:119], v[80:95]
	v_mfma_f32_32x32x16_bf16 v[96:111], v[38:41], v[116:119], v[96:111]
	ds_read_b128 v[34:37], v44 offset:32768
	ds_read_b128 v[38:41], v44 offset:40960
	s_waitcnt lgkmcnt(0)
	v_mfma_f32_32x32x16_bf16 v[80:95], v[34:37], v[120:123], v[80:95]
	v_mfma_f32_32x32x16_bf16 v[96:111], v[38:41], v[120:123], v[96:111]
	ds_read_b128 v[34:37], v32 offset:32768
	ds_read_b128 v[38:41], v32 offset:40960
	s_waitcnt lgkmcnt(0)
	v_mfma_f32_32x32x16_bf16 v[80:95], v[34:37], v[124:127], v[80:95]
	v_mfma_f32_32x32x16_bf16 v[96:111], v[38:41], v[124:127], v[96:111]
	ds_read_b128 v[34:37], v42 offset:32896
	ds_read_b128 v[38:41], v42 offset:41088
	s_waitcnt lgkmcnt(0)
	v_mfma_f32_32x32x16_bf16 v[80:95], v[34:37], v[128:131], v[80:95]
	v_mfma_f32_32x32x16_bf16 v[96:111], v[38:41], v[128:131], v[96:111]
	ds_read_b128 v[34:37], v43 offset:32896
	ds_read_b128 v[38:41], v43 offset:41088
	s_waitcnt lgkmcnt(0)
	v_mfma_f32_32x32x16_bf16 v[80:95], v[34:37], v[132:135], v[80:95]
	v_mfma_f32_32x32x16_bf16 v[96:111], v[38:41], v[132:135], v[96:111]
	ds_read_b128 v[34:37], v44 offset:32896
	ds_read_b128 v[38:41], v44 offset:41088
	s_waitcnt lgkmcnt(0)
	v_mfma_f32_32x32x16_bf16 v[80:95], v[34:37], v[136:139], v[80:95]
	v_mfma_f32_32x32x16_bf16 v[96:111], v[38:41], v[136:139], v[96:111]
	ds_read_b128 v[34:37], v32 offset:32896
	ds_read_b128 v[38:41], v32 offset:41088
	s_waitcnt lgkmcnt(0)
	v_mfma_f32_32x32x16_bf16 v[80:95], v[34:37], v[140:143], v[80:95]
	v_mfma_f32_32x32x16_bf16 v[96:111], v[38:41], v[140:143], v[96:111]
	s_nop 10
	v_exp_f32_e32 v217, v80
	v_exp_f32_e32 v216, v81
	v_exp_f32_e32 v214, v82
	v_exp_f32_e32 v213, v83
	v_exp_f32_e32 v212, v84
	v_exp_f32_e32 v211, v85
	v_exp_f32_e32 v210, v86
	v_exp_f32_e32 v232, v96
	v_exp_f32_e32 v230, v97
	v_exp_f32_e32 v233, v98
	v_exp_f32_e32 v231, v99
	v_exp_f32_e32 v229, v100
	v_exp_f32_e32 v228, v101
	v_exp_f32_e32 v227, v102
	v_exp_f32_e32 v226, v103
	v_exp_f32_e32 v224, v104
	v_exp_f32_e32 v225, v105
	v_exp_f32_e32 v223, v106
	v_exp_f32_e32 v222, v107
	v_exp_f32_e32 v221, v108
	v_exp_f32_e32 v220, v109
	v_exp_f32_e32 v219, v110
	v_exp_f32_e32 v218, v111
	v_exp_f32_e32 v209, v87
	v_exp_f32_e32 v208, v88
	v_exp_f32_e32 v111, v89
	v_exp_f32_e32 v110, v90
	v_exp_f32_e32 v109, v91
	v_exp_f32_e32 v108, v92
	v_exp_f32_e32 v85, v93
	v_exp_f32_e32 v45, v94
	v_exp_f32_e32 v32, v95
	s_and_saveexec_b64 s[12:13], s[0:1]
	s_xor_b64 s[0:1], exec, s[12:13]
	s_cbranch_execz .LBB0_305
; template <bool MASK>
; DEVI void sb_half(f32x16& p, const int keybase, const int bound, const int hi, float& run) {
;   float om[16];
; #pragma unroll
;   for (int r = 0; r < 16; ++r) {
;     const float e = __builtin_amdgcn_exp2f(p[r]);
;     float q = __builtin_amdgcn_rcpf(1.f + e);
;     if (MASK) { const int key = keybase + (r & 3) + 8 * (r >> 2); q = key < bound ? q : 1.f; }
;     om[r] = q; }
;   float tot[4], par[4];
; #pragma unroll
;   for (int ri = 0; ri < 4; ++ri) { const float s0 = (om[4 * ri] * om[4 * ri + 1]) * (om[4 * ri + 2] * om[4 * ri + 3]);
;     par[ri] = partner_of(s0, hi); tot[ri] = s0 * par[ri]; }
; #pragma unroll
;     ...
;     float a = run * (hi == 0 ? par[ri] : 1.f);
; #pragma unroll
;     for (int e = 3; e >= 0; --e) { const int r = 4 * ri + e; const float an = a * om[r]; p[r] = a - an; a = an; }
;     run *= tot[ri];
;   }
; }
	v_add_f32_e32 v34, 1.0, v232
	v_rcp_f32_e32 v86, v34
	v_add_f32_e32 v34, 1.0, v230
	v_rcp_f32_e32 v88, v34
	v_add_f32_e32 v34, 1.0, v233
	v_rcp_f32_e32 v87, v34
	v_add_f32_e32 v34, 1.0, v231
	v_rcp_f32_e32 v89, v34
	v_add_f32_e32 v34, 1.0, v229
	v_rcp_f32_e32 v38, v34
	v_add_f32_e32 v34, 1.0, v228
	v_rcp_f32_e32 v40, v34
	v_add_f32_e32 v34, 1.0, v227
	v_rcp_f32_e32 v39, v34
	v_add_f32_e32 v34, 1.0, v226
	v_rcp_f32_e32 v41, v34
	v_add_f32_e32 v34, 1.0, v224
	v_rcp_f32_e32 v42, v34
	v_add_f32_e32 v34, 1.0, v225
	v_rcp_f32_e32 v46, v34
	v_add_f32_e32 v34, 1.0, v223
	v_rcp_f32_e32 v44, v34
	v_add_f32_e32 v34, 1.0, v222
	v_rcp_f32_e32 v84, v34
	v_add_f32_e32 v34, 1.0, v221
	v_rcp_f32_e32 v80, v34
	v_add_f32_e32 v34, 1.0, v220
	v_rcp_f32_e32 v82, v34
	v_add_f32_e32 v34, 1.0, v219
	v_rcp_f32_e32 v81, v34
	v_add_f32_e32 v34, 1.0, v218
	v_rcp_f32_e32 v83, v34
	v_pk_mul_f32 v[34:35], v[86:87], v[88:89]
	v_pk_mul_f32 v[36:37], v[38:39], v[40:41]
	v_pk_mul_f32 v[106:107], v[34:35], v[34:35] op_sel:[0,1] op_sel_hi:[1,0]
	v_pk_mul_f32 v[92:93], v[80:81], v[82:83]
	v_mov_b32_e32 v34, v106
	v_mov_b32_e32 v35, v106
	s_nop 1
	v_permlane32_swap_b32_e32 v34, v35
	v_cndmask_b32_e64 v35, v34, v35, s[6:7]
	v_mul_f32_e32 v34, v36, v37
	v_mov_b32_e32 v36, v34
	v_mov_b32_e32 v37, v34
	s_nop 1
	v_permlane32_swap_b32_e32 v36, v37
	v_mov_b32_e32 v43, v92
	v_mov_b32_e32 v47, v93
	v_cndmask_b32_e64 v36, v36, v37, s[6:7]
	v_pk_mul_f32 v[92:93], v[42:43], v[46:47]
	v_mul_f32_e32 v37, v34, v36
	v_mov_b32_e32 v34, v93
	v_mov_b32_e32 v43, v93
	s_nop 1
	v_permlane32_swap_b32_e32 v34, v43
	v_mul_f32_e32 v90, v44, v84
	v_cndmask_b32_e64 v91, v34, v43, s[6:7]
	v_pk_mul_f32 v[92:93], v[92:93], v[90:91]
	v_add_f32_e32 v32, 1.0, v32
	v_mov_b32_e32 v34, v92
	v_mov_b32_e32 v43, v92
	s_nop 1
	v_permlane32_swap_b32_e32 v34, v43
	v_cndmask_b32_e64 v176, v34, v43, s[6:7]
	v_cndmask_b32_e64 v34, 1.0, v91, s[6:7]
	v_mul_f32_e32 v219, v177, v34
	v_mul_f32_e32 v218, v83, v219
	v_mul_f32_e32 v220, v81, v218
	v_mul_f32_e32 v222, v82, v220
	v_mul_f32_e32 v224, v80, v222
	v_pk_mul_f32 v[80:81], v[92:93], v[176:177]
	v_cndmask_b32_e64 v34, 1.0, v176, s[6:7]
	v_mul_f32_e32 v91, v34, v81
	v_pk_mul_f32 v[94:95], v[80:81], v[80:81] op_sel:[0,1] op_sel_hi:[1,0]
	v_cndmask_b32_e64 v34, 1.0, v36, s[6:7]
	v_mul_f32_e32 v231, v34, v94
	v_mul_f32_e32 v230, v41, v231
	v_mul_f32_e32 v232, v39, v230
	v_mul_f32_e32 v96, v40, v232
	v_add_f32_e32 v34, 1.0, v217
	v_mul_f32_e32 v234, v38, v96
	v_rcp_f32_e32 v38, v34
	v_add_f32_e32 v34, 1.0, v216
	v_rcp_f32_e32 v40, v34
	v_add_f32_e32 v34, 1.0, v214
	v_rcp_f32_e32 v39, v34
	v_add_f32_e32 v34, 1.0, v213
	v_rcp_f32_e32 v41, v34
	v_add_f32_e32 v34, 1.0, v212
	v_rcp_f32_e32 v43, v34
	v_add_f32_e32 v34, 1.0, v211
	v_mul_f32_e32 v90, v84, v91
	v_rcp_f32_e32 v47, v34
	v_add_f32_e32 v34, 1.0, v210
	v_mul_f32_e32 v226, v44, v90
	v_rcp_f32_e32 v81, v34
	v_add_f32_e32 v34, 1.0, v209
	v_mul_f32_e32 v92, v46, v226
	v_rcp_f32_e32 v83, v34
	v_add_f32_e32 v34, 1.0, v208
	v_mul_f32_e32 v228, v42, v92
	v_rcp_f32_e32 v42, v34
	v_add_f32_e32 v34, 1.0, v111
	v_rcp_f32_e32 v46, v34
	v_add_f32_e32 v34, 1.0, v110
	v_rcp_f32_e32 v80, v34
	v_add_f32_e32 v34, 1.0, v109
	v_rcp_f32_e32 v82, v34
	v_pk_mul_f32 v[98:99], v[38:39], v[40:41]
	v_add_f32_e32 v34, 1.0, v108
	v_rcp_f32_e32 v84, v32
	v_mul_f32_e32 v32, v98, v99
	v_rcp_f32_e32 v44, v34
	v_add_f32_e32 v34, 1.0, v85
	v_add_f32_e32 v36, 1.0, v45
	v_mov_b32_e32 v45, v32
	v_mov_b32_e32 v85, v32
	v_pk_mul_f32 v[98:99], v[42:43], v[46:47]
	v_pk_mul_f32 v[100:101], v[80:81], v[82:83]
	v_rcp_f32_e32 v36, v36
	v_permlane32_swap_b32_e32 v45, v85
	v_pk_mul_f32 v[98:99], v[98:99], v[100:101]
	v_cndmask_b32_e64 v215, v45, v85, s[6:7]
	v_mov_b32_e32 v85, v98
	v_mov_b32_e32 v100, v98
	s_nop 1
	v_permlane32_swap_b32_e32 v85, v100
	v_rcp_f32_e32 v34, v34
	v_cndmask_b32_e64 v104, v85, v100, s[6:7]
	v_mov_b32_e32 v85, v94
	v_cndmask_b32_e64 v95, 1.0, v35, s[6:7]
	v_mul_f32_e32 v176, v32, v215
	v_mov_b32_e32 v32, v99
	v_mov_b32_e32 v45, v99
	v_pk_mul_f32 v[108:109], v[36:37], v[84:85]
	s_nop 0
	v_permlane32_swap_b32_e32 v32, v45
	v_mul_f32_e32 v95, v95, v109
	v_cndmask_b32_e64 v105, v32, v45, s[6:7]
	v_mul_f32_e32 v94, v89, v95
	v_mov_b32_e32 v45, v106
	v_pk_mul_f32 v[102:103], v[98:99], v[104:105]
	v_mul_f32_e32 v98, v87, v94
	v_pk_mul_f32 v[106:107], v[44:45], v[34:35]
	v_mul_f32_e32 v88, v88, v98
	v_pk_mul_f32 v[106:107], v[106:107], v[108:109]
	v_mov_b32_e32 v221, v218
	v_mov_b32_e32 v223, v220
	v_mov_b32_e32 v225, v222
	v_mov_b32_e32 v227, v90
	v_mov_b32_e32 v93, v226
	v_mov_b32_e32 v229, v92
	v_mov_b32_e32 v233, v230
	v_mov_b32_e32 v97, v232
	v_mov_b32_e32 v235, v96
	v_mov_b32_e32 v99, v94
	v_mul_f32_e32 v86, v86, v88
	v_mov_b32_e32 v89, v98
	v_mov_b32_e32 v87, v88
	v_mov_b32_e32 v35, v106
	v_mov_b32_e32 v37, v106
	v_pk_add_f32 v[100:101], v[88:89], v[86:87] neg_lo:[0,1] neg_hi:[0,1]
	v_pk_add_f32 v[98:99], v[94:95], v[98:99] neg_lo:[0,1] neg_hi:[0,1]
	v_pk_add_f32 v[96:97], v[96:97], v[234:235] neg_lo:[0,1] neg_hi:[0,1]
	v_pk_add_f32 v[94:95], v[230:231], v[232:233] neg_lo:[0,1] neg_hi:[0,1]
	v_pk_add_f32 v[92:93], v[92:93], v[228:229] neg_lo:[0,1] neg_hi:[0,1]
	v_pk_add_f32 v[90:91], v[90:91], v[226:227] neg_lo:[0,1] neg_hi:[0,1]
	v_pk_add_f32 v[88:89], v[222:223], v[224:225] neg_lo:[0,1] neg_hi:[0,1]
	v_pk_add_f32 v[86:87], v[218:219], v[220:221] neg_lo:[0,1] neg_hi:[0,1]
	v_permlane32_swap_b32_e32 v35, v37

; template <bool MLA> ...
;     ...
;       const char* Ks = K_lds + buf * SHM_K + r32 * KP;
;       f32x16 p0, p1;
; #pragma unroll
;       for (int r = 0; r < 16; ++r) { p0[r] = 0.f; p1[r] = 0.f; }
; #pragma unroll
;       for (int d0 = 0; d0 < ND0; ++d0) { const int off = kq4[d0 & 3] + (d0 >> 2) * 128;
;         bf16x8 b0 = *reinterpret_cast<const bf16x8*>(Ks + off);
;         bf16x8 b1 = *reinterpret_cast<const bf16x8*>(Ks + off + 32 * KP);
;         p0 = __builtin_amdgcn_mfma_f32_32x32x16_bf16(b0, qr[d0], p0, 0, 0, 0);
;         p1 = __builtin_amdgcn_mfma_f32_32x32x16_bf16(b1, qr[d0], p1, 0, 0, 0); }
.LBB0_370:
	s_add_i32 s12, s72, s94
	s_addk_i32 s12, 0xc0
	v_cmp_lt_i32_e32 vcc, s12, v215
	s_and_saveexec_b64 s[0:1], vcc
	s_cbranch_execz .LBB0_367
	s_mul_i32 s13, s39, 0x6000
	v_add_u32_e32 v223, s13, v216
	v_add_u32_e32 v228, v223, v213
	ds_read_b128 v[66:69], v228 offset:32768
	ds_read_b128 v[82:85], v228 offset:45056
	v_add_u32_e32 v229, v223, v212
	ds_read_b128 v[224:227], v229 offset:32768
	v_add_u32_e32 v230, v223, v211
	v_add_u32_e32 v223, v223, v210
	v_cmp_ge_i32_e32 vcc, s12, v214
	s_waitcnt lgkmcnt(0)
	v_mfma_f32_32x32x16_bf16 v[66:81], v[66:69], v[142:145], 0
	v_mfma_f32_32x32x16_bf16 v[66:81], v[224:227], v[138:141], v[66:81]
	ds_read_b128 v[224:227], v229 offset:45056
	v_mfma_f32_32x32x16_bf16 v[82:97], v[82:85], v[142:145], 0
	s_waitcnt lgkmcnt(0)
	v_mfma_f32_32x32x16_bf16 v[82:97], v[224:227], v[138:141], v[82:97]
	ds_read_b128 v[224:227], v230 offset:32768
	s_waitcnt lgkmcnt(0)
	v_mfma_f32_32x32x16_bf16 v[66:81], v[224:227], v[134:137], v[66:81]
	ds_read_b128 v[224:227], v230 offset:45056
	s_waitcnt lgkmcnt(0)
	v_mfma_f32_32x32x16_bf16 v[82:97], v[224:227], v[134:137], v[82:97]
	ds_read_b128 v[224:227], v223 offset:32768
	s_waitcnt lgkmcnt(0)
	v_mfma_f32_32x32x16_bf16 v[66:81], v[224:227], v[130:133], v[66:81]
	ds_read_b128 v[224:227], v223 offset:45056
	s_waitcnt lgkmcnt(0)
	v_mfma_f32_32x32x16_bf16 v[82:97], v[224:227], v[130:133], v[82:97]
	ds_read_b128 v[224:227], v228 offset:32896
	s_waitcnt lgkmcnt(0)
	v_mfma_f32_32x32x16_bf16 v[66:81], v[224:227], v[126:129], v[66:81]
	ds_read_b128 v[224:227], v228 offset:45184
	s_waitcnt lgkmcnt(0)
	v_mfma_f32_32x32x16_bf16 v[82:97], v[224:227], v[126:129], v[82:97]
	ds_read_b128 v[224:227], v229 offset:32896
	s_waitcnt lgkmcnt(0)
	v_mfma_f32_32x32x16_bf16 v[66:81], v[224:227], v[122:125], v[66:81]
	ds_read_b128 v[224:227], v229 offset:45184
	s_waitcnt lgkmcnt(0)
	v_mfma_f32_32x32x16_bf16 v[82:97], v[224:227], v[122:125], v[82:97]
	ds_read_b128 v[224:227], v230 offset:32896
	s_waitcnt lgkmcnt(0)
	v_mfma_f32_32x32x16_bf16 v[66:81], v[224:227], v[118:121], v[66:81]
	ds_read_b128 v[224:227], v230 offset:45184
	s_waitcnt lgkmcnt(0)
	v_mfma_f32_32x32x16_bf16 v[82:97], v[224:227], v[118:121], v[82:97]
	ds_read_b128 v[224:227], v223 offset:32896
	s_waitcnt lgkmcnt(0)
	v_mfma_f32_32x32x16_bf16 v[66:81], v[224:227], v[114:117], v[66:81]
	ds_read_b128 v[224:227], v223 offset:45184
	s_waitcnt lgkmcnt(0)
	v_mfma_f32_32x32x16_bf16 v[82:97], v[224:227], v[114:117], v[82:97]
	ds_read_b128 v[224:227], v228 offset:33024
	s_waitcnt lgkmcnt(0)
	v_mfma_f32_32x32x16_bf16 v[66:81], v[224:227], v[110:113], v[66:81]
	ds_read_b128 v[224:227], v228 offset:45312
	s_waitcnt lgkmcnt(0)
	v_mfma_f32_32x32x16_bf16 v[82:97], v[224:227], v[110:113], v[82:97]
	ds_read_b128 v[224:227], v229 offset:33024
	s_waitcnt lgkmcnt(0)
	v_mfma_f32_32x32x16_bf16 v[66:81], v[224:227], v[106:109], v[66:81]
	ds_read_b128 v[224:227], v229 offset:45312
	s_waitcnt lgkmcnt(0)
	v_mfma_f32_32x32x16_bf16 v[82:97], v[224:227], v[106:109], v[82:97]
	ds_read_b128 v[224:227], v230 offset:33024
	s_waitcnt lgkmcnt(0)
	v_mfma_f32_32x32x16_bf16 v[66:81], v[224:227], v[102:105], v[66:81]
	ds_read_b128 v[224:227], v230 offset:45312
	s_waitcnt lgkmcnt(0)
	v_mfma_f32_32x32x16_bf16 v[82:97], v[224:227], v[102:105], v[82:97]
	ds_read_b128 v[224:227], v223 offset:33024
	s_waitcnt lgkmcnt(0)
	v_mfma_f32_32x32x16_bf16 v[66:81], v[224:227], v[98:101], v[66:81]
	ds_read_b128 v[224:227], v223 offset:45312
	s_waitcnt lgkmcnt(0)
	v_mfma_f32_32x32x16_bf16 v[82:97], v[224:227], v[98:101], v[82:97]
	s_and_saveexec_b64 s[12:13], vcc
	s_xor_b64 s[12:13], exec, s[12:13]
	s_cbranch_execz .LBB0_373
; template <bool MLA> ...
;     ...
;         float pmax = -INFINITY;
;         if (needmask) {
; #pragma unroll
;           for (int r = 0; r < 16; ++r) { const int key = kb + (r & 3) + 8 * (r >> 2);
;             p0[r] = key < bound ? p0[r] : -INFINITY; p1[r] = key + 32 < bound ? p1[r] : -INFINITY;
;             pmax = fmaxf(pmax, fmaxf(p0[r], p1[r])); }
	v_add_u32_e32 v223, s94, v217
	v_cmp_lt_i32_e32 vcc, v223, v192
	s_mov_b32 s4, 0xff800000
	s_nop 2
	v_cndmask_b32_e32 v66, v188, v66, vcc
	v_cmp_lt_i32_e32 vcc, v223, v207
	v_max_f32_e32 v225, v66, v66
	s_nop 0
	v_cndmask_b32_e32 v82, v188, v82, vcc
	v_cmp_lt_i32_e32 vcc, v223, v206
	v_max_f32_e32 v224, v82, v82
	v_max_f32_e32 v224, v225, v224
	v_cndmask_b32_e32 v67, v188, v67, vcc
	v_cmp_lt_i32_e32 vcc, v223, v205
	v_max_f32_e32 v226, v67, v67
	s_nop 0
	v_cndmask_b32_e32 v83, v188, v83, vcc
	v_cmp_lt_i32_e32 vcc, v223, v204
	v_max_f32_e32 v225, v83, v83
	v_max_f32_e32 v225, v226, v225
	v_cndmask_b32_e32 v68, v188, v68, vcc
	v_cmp_lt_i32_e32 vcc, v223, v203
	v_max3_f32 v224, v224, s4, v225
	v_max_f32_e32 v226, v68, v68
	v_cndmask_b32_e32 v84, v188, v84, vcc
	v_cmp_lt_i32_e32 vcc, v223, v202
	v_max_f32_e32 v225, v84, v84
	v_max_f32_e32 v225, v226, v225
	v_cndmask_b32_e32 v69, v188, v69, vcc
	v_cmp_lt_i32_e32 vcc, v223, v201
	v_max_f32_e32 v227, v69, v69
	s_nop 0
	v_cndmask_b32_e32 v85, v188, v85, vcc
	v_cmp_lt_i32_e32 vcc, v223, v200
	v_max_f32_e32 v226, v85, v85
	v_max_f32_e32 v226, v227, v226
	v_cndmask_b32_e32 v70, v188, v70, vcc
	v_cmp_lt_i32_e32 vcc, v223, v199
	v_max3_f32 v224, v224, v225, v226
	v_max_f32_e32 v226, v70, v70
	v_cndmask_b32_e32 v86, v188, v86, vcc
	v_cmp_lt_i32_e32 vcc, v223, v198
	v_max_f32_e32 v225, v86, v86
	v_max_f32_e32 v225, v226, v225
	v_cndmask_b32_e32 v71, v188, v71, vcc
	v_cmp_lt_i32_e32 vcc, v223, v197
	v_max_f32_e32 v227, v71, v71
	s_nop 0
	v_cndmask_b32_e32 v87, v188, v87, vcc
	v_cmp_lt_i32_e32 vcc, v223, v196
	v_max_f32_e32 v226, v87, v87
	v_max_f32_e32 v226, v227, v226
	v_cndmask_b32_e32 v72, v188, v72, vcc
	v_cmp_lt_i32_e32 vcc, v223, v195
	v_max3_f32 v224, v224, v225, v226
	v_max_f32_e32 v226, v72, v72
	v_cndmask_b32_e32 v88, v188, v88, vcc
	v_cmp_lt_i32_e32 vcc, v223, v194
	v_max_f32_e32 v225, v88, v88
	v_max_f32_e32 v225, v226, v225
	v_cndmask_b32_e32 v73, v188, v73, vcc
	v_cmp_lt_i32_e32 vcc, v223, v193
	v_max_f32_e32 v227, v73, v73
	s_nop 0
	v_cndmask_b32_e32 v89, v188, v89, vcc
	v_cmp_lt_i32_e32 vcc, v223, v183
	v_max_f32_e32 v226, v89, v89
	v_max_f32_e32 v226, v227, v226
	v_cndmask_b32_e32 v74, v188, v74, vcc
	v_cmp_lt_i32_e32 vcc, v223, v182
	v_max3_f32 v224, v224, v225, v226
	v_max_f32_e32 v226, v74, v74
	v_cndmask_b32_e32 v90, v188, v90, vcc
	v_cmp_lt_i32_e32 vcc, v223, v181
	v_max_f32_e32 v225, v90, v90
	v_max_f32_e32 v225, v226, v225
	v_cndmask_b32_e32 v75, v188, v75, vcc
	v_cmp_lt_i32_e32 vcc, v223, v180
	v_max_f32_e32 v227, v75, v75
	s_nop 0
	v_cndmask_b32_e32 v91, v188, v91, vcc
	v_cmp_lt_i32_e32 vcc, v223, v179
	v_max_f32_e32 v226, v91, v91
	v_max_f32_e32 v226, v227, v226
	v_cndmask_b32_e32 v76, v188, v76, vcc
	v_cmp_lt_i32_e32 vcc, v223, v178
	v_max3_f32 v224, v224, v225, v226
	v_max_f32_e32 v226, v76, v76
	v_cndmask_b32_e32 v92, v188, v92, vcc
	v_cmp_lt_i32_e32 vcc, v223, v177
	v_max_f32_e32 v225, v92, v92
	v_max_f32_e32 v225, v226, v225
	v_cndmask_b32_e32 v77, v188, v77, vcc
	v_cmp_lt_i32_e32 vcc, v223, v176
	v_max_f32_e32 v227, v77, v77
	s_nop 0
	v_cndmask_b32_e32 v93, v188, v93, vcc
	v_cmp_lt_i32_e32 vcc, v223, v175
	v_max_f32_e32 v226, v93, v93
	v_max_f32_e32 v226, v227, v226
	v_cndmask_b32_e32 v78, v188, v78, vcc
	v_cmp_lt_i32_e32 vcc, v223, v174
	v_max3_f32 v224, v224, v225, v226
	v_max_f32_e32 v226, v78, v78
	v_cndmask_b32_e32 v94, v188, v94, vcc
	v_cmp_lt_i32_e32 vcc, v223, v173
	v_max_f32_e32 v225, v94, v94
	v_max_f32_e32 v225, v226, v225
	v_cndmask_b32_e32 v79, v188, v79, vcc
	v_cmp_lt_i32_e32 vcc, v223, v172
	v_max_f32_e32 v227, v79, v79
	s_nop 0
	v_cndmask_b32_e32 v95, v188, v95, vcc
	v_cmp_lt_i32_e32 vcc, v223, v171
	v_max_f32_e32 v226, v95, v95
	v_max_f32_e32 v226, v227, v226
	v_cndmask_b32_e32 v80, v188, v80, vcc
	v_cmp_lt_i32_e32 vcc, v223, v170
	v_max3_f32 v224, v224, v225, v226
	v_max_f32_e32 v226, v80, v80
	v_cndmask_b32_e32 v96, v188, v96, vcc
	v_cmp_lt_i32_e32 vcc, v223, v169
	v_max_f32_e32 v225, v96, v96
	v_max_f32_e32 v225, v226, v225
	v_cndmask_b32_e32 v81, v188, v81, vcc
	v_cmp_lt_i32_e32 vcc, v223, v168
	v_max_f32_e32 v226, v81, v81
	s_nop 0
	v_cndmask_b32_e32 v97, v188, v97, vcc
	v_max_f32_e32 v223, v97, v97
	v_max_f32_e32 v223, v226, v223
	v_max3_f32 v223, v224, v225, v223

; template <bool MLA> ...
;     ...
;       const char* Ks = K_lds + buf * SHM_K + r32 * KP;
;       f32x16 p0, p1;
; #pragma unroll
;       for (int r = 0; r < 16; ++r) { p0[r] = 0.f; p1[r] = 0.f; }
; #pragma unroll
;       for (int d0 = 0; d0 < ND0; ++d0) { const int off = kq4[d0 & 3] + (d0 >> 2) * 128;
;         bf16x8 b0 = *reinterpret_cast<const bf16x8*>(Ks + off);
;         bf16x8 b1 = *reinterpret_cast<const bf16x8*>(Ks + off + 32 * KP);
;         p0 = __builtin_amdgcn_mfma_f32_32x32x16_bf16(b0, qr[d0], p0, 0, 0, 0);
;         p1 = __builtin_amdgcn_mfma_f32_32x32x16_bf16(b1, qr[d0], p1, 0, 0, 0); }
.LBB0_430:
	s_add_i32 s12, s72, s68
	s_add_i32 s0, s12, 0xc0
	v_cmp_lt_i32_e64 s[0:1], s0, v161
	s_and_saveexec_b64 s[8:9], s[0:1]
	s_cbranch_execz .LBB0_427
	s_lshl_b32 s73, s13, 14
	v_add_u32_e32 v32, s73, v166
	v_add_u32_e32 v42, v32, v162
	ds_read_b128 v[34:37], v42 offset:32768
	ds_read_b128 v[38:41], v42 offset:40960
	v_add_u32_e32 v43, v32, v163
	v_add_u32_e32 v44, v32, v164
	v_add_u32_e32 v32, v32, v165
	s_waitcnt lgkmcnt(0)
	v_mfma_f32_32x32x16_bf16 v[80:95], v[34:37], v[112:115], 0
	s_addk_i32 s12, 0x100
	v_cmp_le_i32_e64 s[0:1], s12, v160
	v_mfma_f32_32x32x16_bf16 v[96:111], v[38:41], v[112:115], 0
	ds_read_b128 v[34:37], v43 offset:32768
	ds_read_b128 v[38:41], v43 offset:40960
	s_waitcnt lgkmcnt(0)
	v_mfma_f32_32x32x16_bf16 v[80:95], v[34:37], v[116:119], v[80:95]
	v_mfma_f32_32x32x16_bf16 v[96:111], v[38:41], v[116:119], v[96:111]
	ds_read_b128 v[34:37], v44 offset:32768
	ds_read_b128 v[38:41], v44 offset:40960
	s_waitcnt lgkmcnt(0)
	v_mfma_f32_32x32x16_bf16 v[80:95], v[34:37], v[120:123], v[80:95]
	v_mfma_f32_32x32x16_bf16 v[96:111], v[38:41], v[120:123], v[96:111]
	ds_read_b128 v[34:37], v32 offset:32768
	ds_read_b128 v[38:41], v32 offset:40960
	s_waitcnt lgkmcnt(0)
	v_mfma_f32_32x32x16_bf16 v[80:95], v[34:37], v[124:127], v[80:95]
	v_mfma_f32_32x32x16_bf16 v[96:111], v[38:41], v[124:127], v[96:111]
	ds_read_b128 v[34:37], v42 offset:32896
	ds_read_b128 v[38:41], v42 offset:41088
	s_waitcnt lgkmcnt(0)
	v_mfma_f32_32x32x16_bf16 v[80:95], v[34:37], v[128:131], v[80:95]
	v_mfma_f32_32x32x16_bf16 v[96:111], v[38:41], v[128:131], v[96:111]
	ds_read_b128 v[34:37], v43 offset:32896
	ds_read_b128 v[38:41], v43 offset:41088
	s_waitcnt lgkmcnt(0)
	v_mfma_f32_32x32x16_bf16 v[80:95], v[34:37], v[132:135], v[80:95]
	v_mfma_f32_32x32x16_bf16 v[96:111], v[38:41], v[132:135], v[96:111]
	ds_read_b128 v[34:37], v44 offset:32896
	ds_read_b128 v[38:41], v44 offset:41088
	s_waitcnt lgkmcnt(0)
	v_mfma_f32_32x32x16_bf16 v[80:95], v[34:37], v[136:139], v[80:95]
	v_mfma_f32_32x32x16_bf16 v[96:111], v[38:41], v[136:139], v[96:111]
	ds_read_b128 v[34:37], v32 offset:32896
	ds_read_b128 v[38:41], v32 offset:41088
	s_waitcnt lgkmcnt(0)
	v_mfma_f32_32x32x16_bf16 v[80:95], v[34:37], v[140:143], v[80:95]
	v_mfma_f32_32x32x16_bf16 v[96:111], v[38:41], v[140:143], v[96:111]
	s_nop 10
	v_exp_f32_e32 v183, v80
	v_exp_f32_e32 v182, v81
	v_exp_f32_e32 v181, v82
	v_exp_f32_e32 v180, v83
	v_exp_f32_e32 v179, v84
	v_exp_f32_e32 v178, v85
	v_exp_f32_e32 v177, v86
	v_exp_f32_e32 v205, v96
	v_exp_f32_e32 v203, v97
	v_exp_f32_e32 v206, v98
	v_exp_f32_e32 v204, v99
	v_exp_f32_e32 v202, v100
	v_exp_f32_e32 v201, v101
	v_exp_f32_e32 v200, v102
	v_exp_f32_e32 v198, v103
	v_exp_f32_e32 v196, v104
	v_exp_f32_e32 v199, v105
	v_exp_f32_e32 v197, v106
	v_exp_f32_e32 v195, v107
	v_exp_f32_e32 v194, v108
	v_exp_f32_e32 v193, v109
	v_exp_f32_e32 v192, v110
	v_exp_f32_e32 v154, v111
	v_exp_f32_e32 v176, v87
	v_exp_f32_e32 v175, v88
	v_exp_f32_e32 v174, v89
	v_exp_f32_e32 v173, v90
	v_exp_f32_e32 v111, v91
	v_exp_f32_e32 v110, v92
	v_exp_f32_e32 v109, v93
	v_exp_f32_e32 v85, v94
	v_exp_f32_e32 v47, v95
	s_and_saveexec_b64 s[12:13], s[0:1]
	s_xor_b64 s[0:1], exec, s[12:13]
	s_cbranch_execz .LBB0_433
; template <bool MASK>
; DEVI void sb_half(f32x16& p, const int keybase, const int bound, const int hi, float& run) {
;   float om[16];
; #pragma unroll
;   for (int r = 0; r < 16; ++r) {
;     const float e = __builtin_amdgcn_exp2f(p[r]);
;     float q = __builtin_amdgcn_rcpf(1.f + e);
;     if (MASK) { const int key = keybase + (r & 3) + 8 * (r >> 2); q = key < bound ? q : 1.f; }
;     om[r] = q; }
;   float tot[4], par[4];
; #pragma unroll
;   for (int ri = 0; ri < 4; ++ri) { const float s0 = (om[4 * ri] * om[4 * ri + 1]) * (om[4 * ri + 2] * om[4 * ri + 3]);
;     par[ri] = partner_of(s0, hi); tot[ri] = s0 * par[ri]; }
; #pragma unroll
;     ...
;     float a = run * (hi == 0 ? par[ri] : 1.f);
; #pragma unroll
;     for (int e = 3; e >= 0; --e) { const int r = 4 * ri + e; const float an = a * om[r]; p[r] = a - an; a = an; }
;     run *= tot[ri];
;   }
; }
	v_add_f32_e32 v32, 1.0, v205
	v_rcp_f32_e32 v86, v32
	v_add_f32_e32 v32, 1.0, v203
	v_rcp_f32_e32 v88, v32
	v_add_f32_e32 v32, 1.0, v206
	v_rcp_f32_e32 v87, v32
	v_add_f32_e32 v32, 1.0, v204
	v_rcp_f32_e32 v89, v32
	v_add_f32_e32 v32, 1.0, v202
	v_add_f32_e32 v34, 1.0, v195
	v_rcp_f32_e32 v38, v32
	v_add_f32_e32 v32, 1.0, v201
	v_rcp_f32_e32 v46, v34
	v_add_f32_e32 v34, 1.0, v194
	v_rcp_f32_e32 v40, v32
	v_add_f32_e32 v32, 1.0, v200
	v_rcp_f32_e32 v80, v34
	v_add_f32_e32 v34, 1.0, v193
	v_rcp_f32_e32 v39, v32
	v_add_f32_e32 v32, 1.0, v198
	v_rcp_f32_e32 v82, v34
	v_add_f32_e32 v34, 1.0, v192
	v_rcp_f32_e32 v41, v32
	v_rcp_f32_e32 v81, v34
	v_add_f32_e32 v34, 1.0, v154
	v_rcp_f32_e32 v83, v34
	v_pk_mul_f32 v[34:35], v[86:87], v[88:89]
	v_add_f32_e32 v32, 1.0, v196
	v_pk_mul_f32 v[106:107], v[34:35], v[34:35] op_sel:[0,1] op_sel_hi:[1,0]
	v_rcp_f32_e32 v42, v32
	v_add_f32_e32 v32, 1.0, v199
	v_mov_b32_e32 v34, v106
	v_mov_b32_e32 v35, v106
	v_rcp_f32_e32 v44, v32
	s_nop 0
	v_permlane32_swap_b32_e32 v34, v35
	v_pk_mul_f32 v[36:37], v[38:39], v[40:41]
	v_cndmask_b32_e64 v35, v34, v35, s[6:7]
	v_mul_f32_e32 v34, v36, v37
	v_add_f32_e32 v32, 1.0, v197
	v_mov_b32_e32 v36, v34
	v_mov_b32_e32 v37, v34
	v_pk_mul_f32 v[92:93], v[80:81], v[82:83]
	v_rcp_f32_e32 v32, v32
	v_permlane32_swap_b32_e32 v36, v37
	v_mov_b32_e32 v43, v92
	v_mov_b32_e32 v45, v93
	v_cndmask_b32_e64 v36, v36, v37, s[6:7]
	v_pk_mul_f32 v[92:93], v[42:43], v[44:45]
	v_mul_f32_e32 v37, v34, v36
	v_mov_b32_e32 v34, v93
	v_mov_b32_e32 v43, v93
	s_nop 1
	v_permlane32_swap_b32_e32 v34, v43
	v_mul_f32_e32 v90, v32, v46
	v_cndmask_b32_e64 v91, v34, v43, s[6:7]
	v_pk_mul_f32 v[92:93], v[92:93], v[90:91]
	s_nop 0
	v_mov_b32_e32 v34, v92
	v_mov_b32_e32 v43, v92
	s_nop 1
	v_permlane32_swap_b32_e32 v34, v43
	v_cndmask_b32_e64 v154, v34, v43, s[6:7]
	v_cndmask_b32_e64 v34, 1.0, v91, s[6:7]
	v_mul_f32_e32 v193, v155, v34
	v_mul_f32_e32 v192, v83, v193
	v_mul_f32_e32 v194, v81, v192
	v_mul_f32_e32 v196, v82, v194
	v_mul_f32_e32 v198, v80, v196
	v_pk_mul_f32 v[80:81], v[92:93], v[154:155]
	v_cndmask_b32_e64 v34, 1.0, v154, s[6:7]
	v_mul_f32_e32 v91, v34, v81
	v_mul_f32_e32 v90, v46, v91
	v_mul_f32_e32 v154, v32, v90
	v_pk_mul_f32 v[94:95], v[80:81], v[80:81] op_sel:[0,1] op_sel_hi:[1,0]
	v_cndmask_b32_e64 v32, 1.0, v36, s[6:7]
	v_mul_f32_e32 v203, v32, v94
	v_mul_f32_e32 v202, v41, v203
	v_mul_f32_e32 v204, v39, v202
	v_mul_f32_e32 v96, v40, v204
	v_add_f32_e32 v32, 1.0, v183
	v_mul_f32_e32 v206, v38, v96
	v_rcp_f32_e32 v38, v32
	v_add_f32_e32 v32, 1.0, v182
	v_rcp_f32_e32 v40, v32
	v_add_f32_e32 v32, 1.0, v181
	v_rcp_f32_e32 v39, v32
	v_add_f32_e32 v32, 1.0, v180
	v_rcp_f32_e32 v41, v32
	v_add_f32_e32 v32, 1.0, v179
	v_rcp_f32_e32 v43, v32
	v_add_f32_e32 v32, 1.0, v178
	v_rcp_f32_e32 v45, v32
	v_add_f32_e32 v32, 1.0, v177
	v_rcp_f32_e32 v81, v32
	v_add_f32_e32 v32, 1.0, v176
	v_mul_f32_e32 v92, v44, v154
	v_rcp_f32_e32 v83, v32
	v_add_f32_e32 v32, 1.0, v175
	v_mul_f32_e32 v200, v42, v92
	v_rcp_f32_e32 v42, v32
	v_add_f32_e32 v32, 1.0, v174
	v_rcp_f32_e32 v44, v32
	v_add_f32_e32 v32, 1.0, v173
	v_rcp_f32_e32 v80, v32
	v_add_f32_e32 v32, 1.0, v111
	v_rcp_f32_e32 v82, v32
	v_add_f32_e32 v32, 1.0, v110
	v_rcp_f32_e32 v46, v32
	v_add_f32_e32 v32, 1.0, v109
	v_rcp_f32_e32 v34, v32
	v_add_f32_e32 v32, 1.0, v85
	v_rcp_f32_e32 v36, v32
	v_add_f32_e32 v32, 1.0, v47
	v_pk_mul_f32 v[98:99], v[38:39], v[40:41]
	v_rcp_f32_e32 v84, v32
	v_mul_f32_e32 v32, v98, v99
	v_mov_b32_e32 v47, v32
	v_mov_b32_e32 v85, v32
	v_pk_mul_f32 v[98:99], v[42:43], v[44:45]
	v_pk_mul_f32 v[100:101], v[80:81], v[82:83]
	v_permlane32_swap_b32_e32 v47, v85
	v_pk_mul_f32 v[98:99], v[98:99], v[100:101]
	v_cndmask_b32_e64 v108, v47, v85, s[6:7]
	v_mov_b32_e32 v47, v99
	v_mov_b32_e32 v85, v99
	s_nop 1
	v_permlane32_swap_b32_e32 v47, v85
	v_cndmask_b32_e64 v105, v47, v85, s[6:7]
	v_mov_b32_e32 v85, v94
	v_cndmask_b32_e64 v95, 1.0, v35, s[6:7]
	v_mov_b32_e32 v100, v98
	v_mov_b32_e32 v101, v98
	v_pk_mul_f32 v[110:111], v[36:37], v[84:85]
	s_nop 0
	v_permlane32_swap_b32_e32 v100, v101
	v_mul_f32_e32 v95, v95, v111
	v_cndmask_b32_e64 v104, v100, v101, s[6:7]
	v_mul_f32_e32 v94, v89, v95
	v_mov_b32_e32 v47, v106
	v_pk_mul_f32 v[102:103], v[98:99], v[104:105]
	v_mul_f32_e32 v98, v87, v94
	v_pk_mul_f32 v[106:107], v[46:47], v[34:35]
	v_mul_f32_e32 v88, v88, v98
	v_pk_mul_f32 v[106:107], v[106:107], v[110:111]
	v_mov_b32_e32 v195, v192
	v_mov_b32_e32 v197, v194
	v_mov_b32_e32 v199, v196
	v_mov_b32_e32 v155, v90
	v_mov_b32_e32 v93, v154
	v_mov_b32_e32 v201, v92
	v_mov_b32_e32 v205, v202
	v_mov_b32_e32 v97, v204
	v_mov_b32_e32 v207, v96
	v_mov_b32_e32 v99, v94
	v_mul_f32_e32 v86, v86, v88
	v_mov_b32_e32 v89, v98
	v_mov_b32_e32 v87, v88
	v_mov_b32_e32 v35, v106
	v_mov_b32_e32 v37, v106
	v_mul_f32_e32 v32, v32, v108
	v_pk_add_f32 v[100:101], v[88:89], v[86:87] neg_lo:[0,1] neg_hi:[0,1]
	v_pk_add_f32 v[98:99], v[94:95], v[98:99] neg_lo:[0,1] neg_hi:[0,1]
	v_pk_add_f32 v[96:97], v[96:97], v[206:207] neg_lo:[0,1] neg_hi:[0,1]
	v_pk_add_f32 v[94:95], v[202:203], v[204:205] neg_lo:[0,1] neg_hi:[0,1]
	v_pk_add_f32 v[92:93], v[92:93], v[200:201] neg_lo:[0,1] neg_hi:[0,1]
	v_pk_add_f32 v[90:91], v[90:91], v[154:155] neg_lo:[0,1] neg_hi:[0,1]
	v_pk_add_f32 v[88:89], v[196:197], v[198:199] neg_lo:[0,1] neg_hi:[0,1]
	v_pk_add_f32 v[86:87], v[192:193], v[194:195] neg_lo:[0,1] neg_hi:[0,1]
	v_permlane32_swap_b32_e32 v35, v37
